# attention P packing: v_cvt_pk_bf16_f32 (RNE) instead of two +0x8000 adds and a v_perm per pair
# baseline (speedup 1.0000x reference)
.LBB0_985:
	v_cmp_lt_i32_e32 vcc, v197, v203
	v_lshlrev_b64 v[2:3], 11, v[198:199]
	v_lshl_add_u64 v[2:3], s[22:23], 0, v[2:3]
	v_cndmask_b32_e32 v0, v195, v197, vcc
	v_cmp_lt_i32_e32 vcc, v204, v203
	s_waitcnt vmcnt(4)
	v_lshlrev_b32_e32 v26, 2, v0
	s_mov_b64 s[0:1], 0xd800500
	v_cndmask_b32_e32 v0, v195, v204, vcc
	v_lshlrev_b32_e32 v27, 2, v0
	v_mov_b32_e32 v0, v212
	s_nop 1
	v_permlane16_swap_b32_e32 v0, v212
	v_lshl_add_u64 v[2:3], v[2:3], 0, s[0:1]
	v_lshl_add_u64 v[20:21], s[36:37], 1, v[2:3]
	v_mov_b32_e32 v197, v1
	v_lshl_add_u64 v[20:21], v[20:21], 0, v[196:197]
	s_waitcnt lgkmcnt(0)
	v_add_f32_e32 v0, v212, v0
	v_mov_b32_e32 v22, v0
	s_nop 1
	v_permlane32_swap_b32_e32 v22, v0
	v_lshl_add_u64 v[2:3], s[38:39], 1, v[2:3]
	v_lshl_add_u64 v[2:3], v[2:3], 0, v[196:197]
	s_waitcnt lgkmcnt(0)
	v_add_f32_e32 v0, v0, v22
	v_div_scale_f32 v22, s[0:1], v0, v0, 1.0
	v_rcp_f32_e32 v23, v22
	s_nop 0
	v_fma_f32 v24, -v22, v23, 1.0
	v_fmac_f32_e32 v23, v24, v23
	v_div_scale_f32 v24, vcc, 1.0, v0, 1.0
	v_mul_f32_e32 v25, v24, v23
	s_waitcnt vmcnt(3)
	v_fma_f32 v28, -v22, v25, v24
	v_fmac_f32_e32 v25, v28, v23
	v_fma_f32 v22, -v22, v25, v24
	v_div_fmas_f32 v22, v22, v23, v25
	v_div_fixup_f32 v0, v22, v0, 1.0
	v_mov_b32_e32 v22, v120
	v_mov_b32_e32 v23, v122
	v_pk_mul_f32 v[22:23], v[22:23], v[0:1] op_sel_hi:[1,0]
	v_mov_b32_e32 v122, v121
	v_pk_mul_f32 v[24:25], v[122:123], v[0:1] op_sel_hi:[1,0]
	v_and_b32_sdwa v28, v23, v236 dst_sel:DWORD dst_unused:UNUSED_PAD src0_sel:WORD_1 src1_sel:DWORD
	v_and_b32_sdwa v29, v22, v236 dst_sel:DWORD dst_unused:UNUSED_PAD src0_sel:WORD_1 src1_sel:DWORD
	v_add3_u32 v22, v22, v29, s60
	v_add3_u32 v23, v23, v28, s60
	v_and_b32_sdwa v28, v25, v236 dst_sel:DWORD dst_unused:UNUSED_PAD src0_sel:WORD_1 src1_sel:DWORD
	v_and_b32_sdwa v29, v24, v236 dst_sel:DWORD dst_unused:UNUSED_PAD src0_sel:WORD_1 src1_sel:DWORD
	v_add3_u32 v25, v25, v28, s60
	v_add3_u32 v24, v24, v29, s60
	v_and_b32_e32 v25, 0xffff0000, v25
	v_and_b32_e32 v24, 0xffff0000, v24
	v_or_b32_sdwa v23, v25, v23 dst_sel:DWORD dst_unused:UNUSED_PAD src0_sel:DWORD src1_sel:WORD_1
	v_or_b32_sdwa v22, v24, v22 dst_sel:DWORD dst_unused:UNUSED_PAD src0_sel:DWORD src1_sel:WORD_1
	global_store_dwordx2 v[20:21], v[22:23], off
	v_mov_b32_e32 v22, v100
	v_mov_b32_e32 v23, v102
	v_pk_mul_f32 v[22:23], v[22:23], v[0:1] op_sel_hi:[1,0]
	v_mov_b32_e32 v102, v101
	v_pk_mul_f32 v[24:25], v[102:103], v[0:1] op_sel_hi:[1,0]
	v_and_b32_sdwa v28, v23, v236 dst_sel:DWORD dst_unused:UNUSED_PAD src0_sel:WORD_1 src1_sel:DWORD
	v_and_b32_sdwa v29, v22, v236 dst_sel:DWORD dst_unused:UNUSED_PAD src0_sel:WORD_1 src1_sel:DWORD
	v_add3_u32 v22, v22, v29, s60
	v_add3_u32 v23, v23, v28, s60
	v_and_b32_sdwa v28, v25, v236 dst_sel:DWORD dst_unused:UNUSED_PAD src0_sel:WORD_1 src1_sel:DWORD
	v_and_b32_sdwa v29, v24, v236 dst_sel:DWORD dst_unused:UNUSED_PAD src0_sel:WORD_1 src1_sel:DWORD
	v_add3_u32 v25, v25, v28, s60
	v_add3_u32 v24, v24, v29, s60
	v_and_b32_e32 v25, 0xffff0000, v25
	v_and_b32_e32 v24, 0xffff0000, v24
	v_or_b32_sdwa v23, v25, v23 dst_sel:DWORD dst_unused:UNUSED_PAD src0_sel:DWORD src1_sel:WORD_1
	v_or_b32_sdwa v22, v24, v22 dst_sel:DWORD dst_unused:UNUSED_PAD src0_sel:DWORD src1_sel:WORD_1
	global_store_dwordx2 v[20:21], v[22:23], off offset:32
	v_mov_b32_e32 v22, v96
	v_mov_b32_e32 v23, v98
	v_pk_mul_f32 v[22:23], v[22:23], v[0:1] op_sel_hi:[1,0]
	v_mov_b32_e32 v98, v97
	v_pk_mul_f32 v[24:25], v[98:99], v[0:1] op_sel_hi:[1,0]
	v_and_b32_sdwa v28, v23, v236 dst_sel:DWORD dst_unused:UNUSED_PAD src0_sel:WORD_1 src1_sel:DWORD
	v_and_b32_sdwa v29, v22, v236 dst_sel:DWORD dst_unused:UNUSED_PAD src0_sel:WORD_1 src1_sel:DWORD
	v_add3_u32 v22, v22, v29, s60
	v_add3_u32 v23, v23, v28, s60
	v_and_b32_sdwa v28, v25, v236 dst_sel:DWORD dst_unused:UNUSED_PAD src0_sel:WORD_1 src1_sel:DWORD
	v_and_b32_sdwa v29, v24, v236 dst_sel:DWORD dst_unused:UNUSED_PAD src0_sel:WORD_1 src1_sel:DWORD
	v_add3_u32 v25, v25, v28, s60
	v_add3_u32 v24, v24, v29, s60
	v_and_b32_e32 v25, 0xffff0000, v25
	v_and_b32_e32 v24, 0xffff0000, v24
	v_or_b32_sdwa v23, v25, v23 dst_sel:DWORD dst_unused:UNUSED_PAD src0_sel:DWORD src1_sel:WORD_1
	v_or_b32_sdwa v22, v24, v22 dst_sel:DWORD dst_unused:UNUSED_PAD src0_sel:DWORD src1_sel:WORD_1
	global_store_dwordx2 v[20:21], v[22:23], off offset:64
	v_mov_b32_e32 v22, v92
	v_mov_b32_e32 v23, v94
	v_pk_mul_f32 v[22:23], v[22:23], v[0:1] op_sel_hi:[1,0]
	v_mov_b32_e32 v94, v93
	v_pk_mul_f32 v[24:25], v[94:95], v[0:1] op_sel_hi:[1,0]
	v_and_b32_sdwa v0, v23, v236 dst_sel:DWORD dst_unused:UNUSED_PAD src0_sel:WORD_1 src1_sel:DWORD
	v_add3_u32 v0, v23, v0, s60
	v_and_b32_sdwa v23, v25, v236 dst_sel:DWORD dst_unused:UNUSED_PAD src0_sel:WORD_1 src1_sel:DWORD
	v_add3_u32 v23, v25, v23, s60
	v_and_b32_e32 v23, 0xffff0000, v23
	v_or_b32_sdwa v23, v23, v0 dst_sel:DWORD dst_unused:UNUSED_PAD src0_sel:DWORD src1_sel:WORD_1
	v_mov_b32_e32 v0, v211
	s_nop 1
	v_permlane16_swap_b32_e32 v0, v211
	v_and_b32_sdwa v28, v22, v236 dst_sel:DWORD dst_unused:UNUSED_PAD src0_sel:WORD_1 src1_sel:DWORD
	v_add3_u32 v22, v22, v28, s60
	v_and_b32_sdwa v28, v24, v236 dst_sel:DWORD dst_unused:UNUSED_PAD src0_sel:WORD_1 src1_sel:DWORD
	v_add3_u32 v24, v24, v28, s60
	v_and_b32_e32 v24, 0xffff0000, v24
	v_or_b32_sdwa v22, v24, v22 dst_sel:DWORD dst_unused:UNUSED_PAD src0_sel:DWORD src1_sel:WORD_1
	s_waitcnt lgkmcnt(0)
	v_add_f32_e32 v0, v211, v0
	global_store_dwordx2 v[20:21], v[22:23], off offset:96
	v_mov_b32_e32 v22, v0
	s_nop 1
	v_permlane32_swap_b32_e32 v22, v0
	s_waitcnt lgkmcnt(0)
	v_add_f32_e32 v0, v0, v22
	v_div_scale_f32 v22, s[0:1], v0, v0, 1.0
	v_rcp_f32_e32 v23, v22
	s_nop 0
	v_fma_f32 v24, -v22, v23, 1.0
	v_fmac_f32_e32 v23, v24, v23
	v_div_scale_f32 v24, vcc, 1.0, v0, 1.0
	v_mul_f32_e32 v25, v24, v23
	v_fma_f32 v28, -v22, v25, v24
	v_fmac_f32_e32 v25, v28, v23
	v_fma_f32 v22, -v22, v25, v24
	v_div_fmas_f32 v22, v22, v23, v25
	v_div_fixup_f32 v0, v22, v0, 1.0
	v_mov_b32_e32 v22, v56
	v_mov_b32_e32 v23, v58
	v_pk_mul_f32 v[22:23], v[22:23], v[0:1] op_sel_hi:[1,0]
	v_mov_b32_e32 v58, v57
	v_pk_mul_f32 v[24:25], v[58:59], v[0:1] op_sel_hi:[1,0]
	v_and_b32_sdwa v28, v23, v236 dst_sel:DWORD dst_unused:UNUSED_PAD src0_sel:WORD_1 src1_sel:DWORD
	v_and_b32_sdwa v29, v22, v236 dst_sel:DWORD dst_unused:UNUSED_PAD src0_sel:WORD_1 src1_sel:DWORD
	v_add3_u32 v22, v22, v29, s60
	v_add3_u32 v23, v23, v28, s60
	v_and_b32_sdwa v28, v25, v236 dst_sel:DWORD dst_unused:UNUSED_PAD src0_sel:WORD_1 src1_sel:DWORD
	v_and_b32_sdwa v29, v24, v236 dst_sel:DWORD dst_unused:UNUSED_PAD src0_sel:WORD_1 src1_sel:DWORD
	v_add3_u32 v25, v25, v28, s60
	v_add3_u32 v24, v24, v29, s60
	v_and_b32_e32 v25, 0xffff0000, v25
	v_and_b32_e32 v24, 0xffff0000, v24
	v_or_b32_sdwa v23, v25, v23 dst_sel:DWORD dst_unused:UNUSED_PAD src0_sel:DWORD src1_sel:WORD_1
	v_or_b32_sdwa v22, v24, v22 dst_sel:DWORD dst_unused:UNUSED_PAD src0_sel:DWORD src1_sel:WORD_1
	global_store_dwordx2 v[20:21], v[22:23], off offset:128
	v_mov_b32_e32 v22, v52
	v_mov_b32_e32 v23, v54
	v_pk_mul_f32 v[22:23], v[22:23], v[0:1] op_sel_hi:[1,0]
	v_mov_b32_e32 v54, v53
	v_pk_mul_f32 v[24:25], v[54:55], v[0:1] op_sel_hi:[1,0]
	v_and_b32_sdwa v28, v23, v236 dst_sel:DWORD dst_unused:UNUSED_PAD src0_sel:WORD_1 src1_sel:DWORD
	v_and_b32_sdwa v29, v22, v236 dst_sel:DWORD dst_unused:UNUSED_PAD src0_sel:WORD_1 src1_sel:DWORD
	v_add3_u32 v22, v22, v29, s60
	v_add3_u32 v23, v23, v28, s60
	v_and_b32_sdwa v28, v25, v236 dst_sel:DWORD dst_unused:UNUSED_PAD src0_sel:WORD_1 src1_sel:DWORD
	v_and_b32_sdwa v29, v24, v236 dst_sel:DWORD dst_unused:UNUSED_PAD src0_sel:WORD_1 src1_sel:DWORD
	v_add3_u32 v25, v25, v28, s60
	v_add3_u32 v24, v24, v29, s60
	v_and_b32_e32 v25, 0xffff0000, v25
	v_and_b32_e32 v24, 0xffff0000, v24
	v_or_b32_sdwa v23, v25, v23 dst_sel:DWORD dst_unused:UNUSED_PAD src0_sel:DWORD src1_sel:WORD_1
	v_or_b32_sdwa v22, v24, v22 dst_sel:DWORD dst_unused:UNUSED_PAD src0_sel:DWORD src1_sel:WORD_1
	global_store_dwordx2 v[20:21], v[22:23], off offset:160
	v_mov_b32_e32 v22, v48
	v_mov_b32_e32 v23, v50
	v_pk_mul_f32 v[22:23], v[22:23], v[0:1] op_sel_hi:[1,0]
	v_mov_b32_e32 v50, v49
	v_pk_mul_f32 v[24:25], v[50:51], v[0:1] op_sel_hi:[1,0]
	v_and_b32_sdwa v28, v23, v236 dst_sel:DWORD dst_unused:UNUSED_PAD src0_sel:WORD_1 src1_sel:DWORD
	v_and_b32_sdwa v29, v22, v236 dst_sel:DWORD dst_unused:UNUSED_PAD src0_sel:WORD_1 src1_sel:DWORD
	v_add3_u32 v22, v22, v29, s60
	v_add3_u32 v23, v23, v28, s60
	v_and_b32_sdwa v28, v25, v236 dst_sel:DWORD dst_unused:UNUSED_PAD src0_sel:WORD_1 src1_sel:DWORD
	v_and_b32_sdwa v29, v24, v236 dst_sel:DWORD dst_unused:UNUSED_PAD src0_sel:WORD_1 src1_sel:DWORD
	v_add3_u32 v25, v25, v28, s60
	v_add3_u32 v24, v24, v29, s60
	v_and_b32_e32 v25, 0xffff0000, v25
	v_and_b32_e32 v24, 0xffff0000, v24
	v_or_b32_sdwa v23, v25, v23 dst_sel:DWORD dst_unused:UNUSED_PAD src0_sel:DWORD src1_sel:WORD_1
	v_or_b32_sdwa v22, v24, v22 dst_sel:DWORD dst_unused:UNUSED_PAD src0_sel:DWORD src1_sel:WORD_1
	global_store_dwordx2 v[20:21], v[22:23], off offset:192
	v_mov_b32_e32 v22, v44
	v_mov_b32_e32 v23, v46
	v_pk_mul_f32 v[22:23], v[22:23], v[0:1] op_sel_hi:[1,0]
	v_mov_b32_e32 v46, v45
	v_pk_mul_f32 v[24:25], v[46:47], v[0:1] op_sel_hi:[1,0]
	v_and_b32_sdwa v0, v23, v236 dst_sel:DWORD dst_unused:UNUSED_PAD src0_sel:WORD_1 src1_sel:DWORD
	v_add3_u32 v0, v23, v0, s60
	v_and_b32_sdwa v23, v25, v236 dst_sel:DWORD dst_unused:UNUSED_PAD src0_sel:WORD_1 src1_sel:DWORD
	v_add3_u32 v23, v25, v23, s60
	v_and_b32_e32 v23, 0xffff0000, v23
	v_or_b32_sdwa v23, v23, v0 dst_sel:DWORD dst_unused:UNUSED_PAD src0_sel:DWORD src1_sel:WORD_1
	v_mov_b32_e32 v0, v202
	s_nop 1
	v_permlane16_swap_b32_e32 v0, v202
	v_and_b32_sdwa v28, v22, v236 dst_sel:DWORD dst_unused:UNUSED_PAD src0_sel:WORD_1 src1_sel:DWORD
	v_add3_u32 v22, v22, v28, s60
	v_and_b32_sdwa v28, v24, v236 dst_sel:DWORD dst_unused:UNUSED_PAD src0_sel:WORD_1 src1_sel:DWORD
	v_add3_u32 v24, v24, v28, s60
	v_and_b32_e32 v24, 0xffff0000, v24
	v_or_b32_sdwa v22, v24, v22 dst_sel:DWORD dst_unused:UNUSED_PAD src0_sel:DWORD src1_sel:WORD_1
	s_waitcnt lgkmcnt(0)
	v_add_f32_e32 v0, v202, v0
	global_store_dwordx2 v[20:21], v[22:23], off offset:224
	v_mov_b32_e32 v20, v0
	s_nop 1
	v_permlane32_swap_b32_e32 v20, v0
	s_waitcnt lgkmcnt(0)
	v_add_f32_e32 v0, v0, v20
	v_div_scale_f32 v20, s[0:1], v0, v0, 1.0
	v_rcp_f32_e32 v21, v20
	s_nop 0
	v_fma_f32 v22, -v20, v21, 1.0
	v_fmac_f32_e32 v21, v22, v21
	v_div_scale_f32 v22, vcc, 1.0, v0, 1.0
	v_mul_f32_e32 v23, v22, v21
	v_fma_f32 v24, -v20, v23, v22
	v_fmac_f32_e32 v23, v24, v21
	v_fma_f32 v20, -v20, v23, v22
	v_div_fmas_f32 v20, v20, v21, v23
	v_div_fixup_f32 v0, v20, v0, 1.0
	v_mov_b32_e32 v20, v16
	v_mov_b32_e32 v21, v18
	v_pk_mul_f32 v[20:21], v[20:21], v[0:1] op_sel_hi:[1,0]
	v_mov_b32_e32 v18, v17
	v_pk_mul_f32 v[16:17], v[18:19], v[0:1] op_sel_hi:[1,0]
	v_and_b32_sdwa v18, v21, v236 dst_sel:DWORD dst_unused:UNUSED_PAD src0_sel:WORD_1 src1_sel:DWORD
	v_and_b32_sdwa v19, v20, v236 dst_sel:DWORD dst_unused:UNUSED_PAD src0_sel:WORD_1 src1_sel:DWORD
	v_add3_u32 v19, v20, v19, s60
	v_add3_u32 v18, v21, v18, s60
	v_and_b32_sdwa v20, v17, v236 dst_sel:DWORD dst_unused:UNUSED_PAD src0_sel:WORD_1 src1_sel:DWORD
	v_and_b32_sdwa v21, v16, v236 dst_sel:DWORD dst_unused:UNUSED_PAD src0_sel:WORD_1 src1_sel:DWORD
	v_add3_u32 v17, v17, v20, s60
	v_add3_u32 v16, v16, v21, s60
	v_and_b32_e32 v17, 0xffff0000, v17
	v_and_b32_e32 v16, 0xffff0000, v16
	v_or_b32_sdwa v17, v17, v18 dst_sel:DWORD dst_unused:UNUSED_PAD src0_sel:DWORD src1_sel:WORD_1
	v_or_b32_sdwa v16, v16, v19 dst_sel:DWORD dst_unused:UNUSED_PAD src0_sel:DWORD src1_sel:WORD_1
	global_store_dwordx2 v[2:3], v[16:17], off
	v_mov_b32_e32 v16, v12
	v_mov_b32_e32 v17, v14
	v_pk_mul_f32 v[16:17], v[16:17], v[0:1] op_sel_hi:[1,0]
	v_mov_b32_e32 v14, v13
	v_pk_mul_f32 v[12:13], v[14:15], v[0:1] op_sel_hi:[1,0]
	v_and_b32_sdwa v14, v17, v236 dst_sel:DWORD dst_unused:UNUSED_PAD src0_sel:WORD_1 src1_sel:DWORD
	v_and_b32_sdwa v15, v16, v236 dst_sel:DWORD dst_unused:UNUSED_PAD src0_sel:WORD_1 src1_sel:DWORD
	v_add3_u32 v15, v16, v15, s60
	v_add3_u32 v14, v17, v14, s60
	v_and_b32_sdwa v16, v13, v236 dst_sel:DWORD dst_unused:UNUSED_PAD src0_sel:WORD_1 src1_sel:DWORD
	v_and_b32_sdwa v17, v12, v236 dst_sel:DWORD dst_unused:UNUSED_PAD src0_sel:WORD_1 src1_sel:DWORD
	v_add3_u32 v13, v13, v16, s60
	v_add3_u32 v12, v12, v17, s60
	v_and_b32_e32 v13, 0xffff0000, v13
	v_and_b32_e32 v12, 0xffff0000, v12
	v_or_b32_sdwa v13, v13, v14 dst_sel:DWORD dst_unused:UNUSED_PAD src0_sel:DWORD src1_sel:WORD_1
	v_or_b32_sdwa v12, v12, v15 dst_sel:DWORD dst_unused:UNUSED_PAD src0_sel:DWORD src1_sel:WORD_1
	global_store_dwordx2 v[2:3], v[12:13], off offset:32
	v_mov_b32_e32 v12, v8
	v_mov_b32_e32 v13, v10
	v_pk_mul_f32 v[12:13], v[12:13], v[0:1] op_sel_hi:[1,0]
	v_mov_b32_e32 v10, v9
	v_pk_mul_f32 v[8:9], v[10:11], v[0:1] op_sel_hi:[1,0]
	v_and_b32_sdwa v10, v13, v236 dst_sel:DWORD dst_unused:UNUSED_PAD src0_sel:WORD_1 src1_sel:DWORD
	v_and_b32_sdwa v11, v12, v236 dst_sel:DWORD dst_unused:UNUSED_PAD src0_sel:WORD_1 src1_sel:DWORD
	v_add3_u32 v11, v12, v11, s60
	v_add3_u32 v10, v13, v10, s60
	v_and_b32_sdwa v12, v9, v236 dst_sel:DWORD dst_unused:UNUSED_PAD src0_sel:WORD_1 src1_sel:DWORD
	v_and_b32_sdwa v13, v8, v236 dst_sel:DWORD dst_unused:UNUSED_PAD src0_sel:WORD_1 src1_sel:DWORD
	v_add3_u32 v9, v9, v12, s60
	v_add3_u32 v8, v8, v13, s60
	v_and_b32_e32 v9, 0xffff0000, v9
	v_and_b32_e32 v8, 0xffff0000, v8
	v_or_b32_sdwa v9, v9, v10 dst_sel:DWORD dst_unused:UNUSED_PAD src0_sel:DWORD src1_sel:WORD_1
	v_or_b32_sdwa v8, v8, v11 dst_sel:DWORD dst_unused:UNUSED_PAD src0_sel:DWORD src1_sel:WORD_1
	global_store_dwordx2 v[2:3], v[8:9], off offset:64
	v_mov_b32_e32 v8, v4
	v_mov_b32_e32 v9, v6
	v_pk_mul_f32 v[8:9], v[8:9], v[0:1] op_sel_hi:[1,0]
	v_mov_b32_e32 v6, v5
	v_pk_mul_f32 v[4:5], v[6:7], v[0:1] op_sel_hi:[1,0]
	v_and_b32_sdwa v6, v8, v236 dst_sel:DWORD dst_unused:UNUSED_PAD src0_sel:WORD_1 src1_sel:DWORD
	v_add3_u32 v6, v8, v6, s60
	v_and_b32_sdwa v7, v5, v236 dst_sel:DWORD dst_unused:UNUSED_PAD src0_sel:WORD_1 src1_sel:DWORD
	v_and_b32_sdwa v8, v4, v236 dst_sel:DWORD dst_unused:UNUSED_PAD src0_sel:WORD_1 src1_sel:DWORD
	v_and_b32_sdwa v0, v9, v236 dst_sel:DWORD dst_unused:UNUSED_PAD src0_sel:WORD_1 src1_sel:DWORD
	v_add3_u32 v5, v5, v7, s60
	v_add3_u32 v4, v4, v8, s60
	v_add3_u32 v0, v9, v0, s60
	v_and_b32_e32 v5, 0xffff0000, v5
	v_and_b32_e32 v4, 0xffff0000, v4
	v_or_b32_sdwa v5, v5, v0 dst_sel:DWORD dst_unused:UNUSED_PAD src0_sel:DWORD src1_sel:WORD_1
	v_or_b32_sdwa v4, v4, v6 dst_sel:DWORD dst_unused:UNUSED_PAD src0_sel:DWORD src1_sel:WORD_1
	global_store_dwordx2 v[2:3], v[4:5], off offset:96

.LBB0_1017:
	v_max_f32_e32 v2, v173, v173
	v_max_f32_e32 v184, v172, v172
	v_max_f32_e32 v2, v184, v2
	v_max_f32_e32 v184, v175, v175
	v_max_f32_e32 v185, v174, v174
	v_max_f32_e32 v184, v185, v184
	v_max_f32_e32 v185, v179, v179
	v_max_f32_e32 v186, v178, v178
	v_max_f32_e32 v185, v186, v185
	v_max3_f32 v185, v176, v177, v185
	v_max3_f32 v2, v2, v184, v185
	v_mov_b32_e32 v184, v2
	s_nop 1
	v_permlane16_swap_b32_e32 v184, v2
	s_xor_b64 s[8:9], s[46:47], -1
	s_andn2_b64 vcc, exec, s[8:9]
	s_waitcnt lgkmcnt(0)
	v_max_f32_e32 v184, v184, v184
	v_max_f32_e32 v2, v2, v184
	v_mov_b32_e32 v184, v2
	s_nop 1
	v_permlane32_swap_b32_e32 v184, v2
	s_waitcnt lgkmcnt(0)
	v_max3_f32 v213, v180, v2, v184
	v_sub_f32_e32 v172, v172, v213
	v_mul_f32_e32 v172, 0x3fb8aa3b, v172
	v_exp_f32_e32 v209, v172
	v_sub_f32_e32 v172, v173, v213
	v_mul_f32_e32 v172, 0x3fb8aa3b, v172
	v_exp_f32_e32 v215, v172
	v_sub_f32_e32 v172, v174, v213
	v_mul_f32_e32 v172, 0x3fb8aa3b, v172
	v_exp_f32_e32 v216, v172
	v_sub_f32_e32 v172, v175, v213
	v_mul_f32_e32 v172, 0x3fb8aa3b, v172
	v_exp_f32_e32 v217, v172
	v_sub_f32_e32 v172, v176, v213
	v_mul_f32_e32 v172, 0x3fb8aa3b, v172
	v_exp_f32_e32 v218, v172
	v_sub_f32_e32 v172, v177, v213
	v_mul_f32_e32 v172, 0x3fb8aa3b, v172
	v_exp_f32_e32 v219, v172
	v_sub_f32_e32 v172, v178, v213
	v_mul_f32_e32 v172, 0x3fb8aa3b, v172
	v_exp_f32_e32 v220, v172
	v_sub_f32_e32 v172, v179, v213
	v_sub_f32_e32 v2, v180, v213
	v_mul_f32_e32 v172, 0x3fb8aa3b, v172
	v_mul_f32_e32 v2, 0x3fb8aa3b, v2
	v_exp_f32_e32 v221, v172
	v_exp_f32_e32 v2, v2
	v_cvt_pk_bf16_f32 v172, v209, v215
	v_cvt_pk_bf16_f32 v173, v216, v217
	v_cvt_pk_bf16_f32 v174, v218, v219
	v_cvt_pk_bf16_f32 v175, v220, v221
	v_pk_mul_f32 v[122:123], v[122:123], v[2:3] op_sel_hi:[1,0]
	v_pk_mul_f32 v[120:121], v[120:121], v[2:3] op_sel_hi:[1,0]
	v_pk_mul_f32 v[102:103], v[102:103], v[2:3] op_sel_hi:[1,0]
	v_pk_mul_f32 v[100:101], v[100:101], v[2:3] op_sel_hi:[1,0]
	v_pk_mul_f32 v[98:99], v[98:99], v[2:3] op_sel_hi:[1,0]
	v_pk_mul_f32 v[96:97], v[96:97], v[2:3] op_sel_hi:[1,0]
	v_pk_mul_f32 v[94:95], v[94:95], v[2:3] op_sel_hi:[1,0]
	v_pk_mul_f32 v[92:93], v[92:93], v[2:3] op_sel_hi:[1,0]
	s_waitcnt vmcnt(3)
	v_mfma_f32_16x16x32_bf16 v[120:123], v[76:79], v[172:175], v[120:123]
	v_cndmask_b32_e64 v180, 0, 1, s[8:9]
	v_cmp_ne_u32_e64 s[6:7], 1, v180
	s_waitcnt vmcnt(2)
	v_mfma_f32_16x16x32_bf16 v[100:103], v[80:83], v[172:175], v[100:103]
	s_waitcnt vmcnt(1)
	v_mfma_f32_16x16x32_bf16 v[96:99], v[84:87], v[172:175], v[96:99]
	s_waitcnt vmcnt(0)
	v_mfma_f32_16x16x32_bf16 v[92:95], v[88:91], v[172:175], v[92:95]
	v_mfma_f32_16x16x32_bf16 v[172:175], v[60:63], v[28:31], 0
	v_mfma_f32_16x16x32_bf16 v[176:179], v[68:71], v[28:31], 0
	v_mfma_f32_16x16x32_bf16 v[172:175], v[64:67], v[32:35], v[172:175]
	v_mfma_f32_16x16x32_bf16 v[176:179], v[72:75], v[32:35], v[176:179]
	s_cbranch_vccnz .LBB0_1019
	v_cmp_lt_u32_e32 vcc, s72, v0
	s_nop 4
	v_cndmask_b32_e32 v172, v245, v172, vcc
	v_cmp_lt_u32_e32 vcc, s72, v235
	s_nop 1
	v_cndmask_b32_e32 v173, v245, v173, vcc
	v_cmp_lt_u32_e32 vcc, s72, v244
	s_nop 1
	v_cndmask_b32_e32 v174, v245, v174, vcc
	v_cmp_lt_u32_e32 vcc, s72, v253
	s_nop 1
	v_cndmask_b32_e32 v175, v245, v175, vcc
	v_cmp_lt_u32_e32 vcc, s72, v252
	s_nop 1
	v_cndmask_b32_e32 v176, v245, v176, vcc
	v_cmp_lt_u32_e32 vcc, s72, v251
	s_nop 1
	v_cndmask_b32_e32 v177, v245, v177, vcc
	v_cmp_lt_u32_e32 vcc, s72, v208
	s_nop 1
	v_cndmask_b32_e32 v178, v245, v178, vcc
	v_cmp_lt_u32_e32 vcc, s72, v201
	s_nop 1
	v_cndmask_b32_e32 v179, v245, v179, vcc
.LBB0_1019:
	s_nop 5
	v_max_f32_e32 v180, v173, v173
	v_max_f32_e32 v184, v172, v172
	v_max_f32_e32 v180, v184, v180
	v_max_f32_e32 v184, v175, v175
	v_max_f32_e32 v185, v174, v174
	v_max_f32_e32 v184, v185, v184
	v_max_f32_e32 v185, v179, v179
	v_max_f32_e32 v186, v178, v178
	v_max_f32_e32 v185, v186, v185
	v_max3_f32 v185, v176, v177, v185
	v_max3_f32 v180, v180, v184, v185
	v_mov_b32_e32 v184, v180
	s_nop 1
	v_permlane16_swap_b32_e32 v184, v180
	v_mfma_f32_16x16x32_bf16 v[238:241], v[68:71], v[36:39], 0
	s_and_b64 vcc, exec, s[6:7]
	s_waitcnt lgkmcnt(0)
	v_max_f32_e32 v184, v184, v184
	v_max_f32_e32 v180, v180, v184
	v_mov_b32_e32 v184, v180
	s_nop 1
	v_permlane32_swap_b32_e32 v184, v180
	s_waitcnt lgkmcnt(0)
	v_max3_f32 v214, v181, v180, v184
	v_sub_f32_e32 v172, v172, v214
	v_mul_f32_e32 v172, 0x3fb8aa3b, v172
	v_exp_f32_e32 v210, v172
	v_sub_f32_e32 v172, v173, v214
	v_mul_f32_e32 v172, 0x3fb8aa3b, v172
	v_exp_f32_e32 v222, v172
	v_sub_f32_e32 v172, v174, v214
	v_mul_f32_e32 v172, 0x3fb8aa3b, v172
	v_exp_f32_e32 v223, v172
	v_sub_f32_e32 v172, v175, v214
	v_mul_f32_e32 v172, 0x3fb8aa3b, v172
	v_exp_f32_e32 v246, v172
	v_sub_f32_e32 v172, v176, v214
	v_mul_f32_e32 v172, 0x3fb8aa3b, v172
	v_exp_f32_e32 v247, v172
	v_sub_f32_e32 v172, v177, v214
	v_mul_f32_e32 v172, 0x3fb8aa3b, v172
	v_exp_f32_e32 v248, v172
	v_sub_f32_e32 v172, v178, v214
	v_mul_f32_e32 v172, 0x3fb8aa3b, v172
	v_exp_f32_e32 v249, v172
	v_sub_f32_e32 v172, v179, v214
	v_sub_f32_e32 v180, v181, v214
	v_mul_f32_e32 v172, 0x3fb8aa3b, v172
	v_mul_f32_e32 v180, 0x3fb8aa3b, v180
	v_exp_f32_e32 v250, v172
	v_exp_f32_e32 v180, v180
	v_cvt_pk_bf16_f32 v172, v210, v222
	v_cvt_pk_bf16_f32 v173, v223, v246
	v_cvt_pk_bf16_f32 v174, v247, v248
	v_cvt_pk_bf16_f32 v175, v249, v250
	v_pk_mul_f32 v[58:59], v[58:59], v[180:181] op_sel_hi:[1,0]
	v_pk_mul_f32 v[56:57], v[56:57], v[180:181] op_sel_hi:[1,0]
	v_pk_mul_f32 v[54:55], v[54:55], v[180:181] op_sel_hi:[1,0]
	v_pk_mul_f32 v[52:53], v[52:53], v[180:181] op_sel_hi:[1,0]
	v_pk_mul_f32 v[50:51], v[50:51], v[180:181] op_sel_hi:[1,0]
	v_pk_mul_f32 v[48:49], v[48:49], v[180:181] op_sel_hi:[1,0]
	v_pk_mul_f32 v[46:47], v[46:47], v[180:181] op_sel_hi:[1,0]
	v_pk_mul_f32 v[44:45], v[44:45], v[180:181] op_sel_hi:[1,0]
	v_mfma_f32_16x16x32_bf16 v[56:59], v[76:79], v[172:175], v[56:59]
	v_mfma_f32_16x16x32_bf16 v[52:55], v[80:83], v[172:175], v[52:55]
	v_mfma_f32_16x16x32_bf16 v[48:51], v[84:87], v[172:175], v[48:51]
	v_mfma_f32_16x16x32_bf16 v[44:47], v[88:91], v[172:175], v[44:47]
	v_mfma_f32_16x16x32_bf16 v[172:175], v[60:63], v[36:39], 0
	v_mfma_f32_16x16x32_bf16 v[176:179], v[64:67], v[40:43], v[172:175]
	v_mfma_f32_16x16x32_bf16 v[172:175], v[72:75], v[40:43], v[238:241]
	s_cbranch_vccnz .LBB0_1021
	v_cmp_lt_u32_e32 vcc, s72, v0
	s_nop 4
	v_cndmask_b32_e32 v176, v245, v176, vcc
	v_cmp_lt_u32_e32 vcc, s72, v235
	s_nop 1
	v_cndmask_b32_e32 v177, v245, v177, vcc
	v_cmp_lt_u32_e32 vcc, s72, v244
	s_nop 1
	v_cndmask_b32_e32 v178, v245, v178, vcc
	v_cmp_lt_u32_e32 vcc, s72, v253
	s_nop 1
	v_cndmask_b32_e32 v179, v245, v179, vcc
	v_cmp_lt_u32_e32 vcc, s72, v252
	s_nop 1
	v_cndmask_b32_e32 v172, v245, v172, vcc
	v_cmp_lt_u32_e32 vcc, s72, v251
	s_nop 1
	v_cndmask_b32_e32 v173, v245, v173, vcc
	v_cmp_lt_u32_e32 vcc, s72, v208
	s_nop 1
	v_cndmask_b32_e32 v174, v245, v174, vcc
	v_cmp_lt_u32_e32 vcc, s72, v201
	s_nop 1
	v_cndmask_b32_e32 v175, v245, v175, vcc
.LBB0_1021:
	s_nop 5
	v_max_f32_e32 v0, v177, v177
	v_max_f32_e32 v181, v176, v176
	v_max_f32_e32 v0, v181, v0
	v_max_f32_e32 v181, v179, v179
	v_max_f32_e32 v184, v178, v178
	v_max_f32_e32 v181, v184, v181
	v_max_f32_e32 v184, v175, v175
	v_max_f32_e32 v185, v174, v174
	v_max_f32_e32 v184, v185, v184
	v_max3_f32 v184, v172, v173, v184
	v_max3_f32 v0, v0, v181, v184
	v_mov_b32_e32 v181, v0
	s_nop 1
	v_permlane16_swap_b32_e32 v181, v0
	s_add_i32 s61, s57, 3
	s_add_i32 s6, s56, 1
	s_cmp_ge_i32 s6, s1
	s_waitcnt lgkmcnt(0)
	v_max_f32_e32 v181, v181, v181
	v_max_f32_e32 v0, v0, v181
	v_mov_b32_e32 v181, v0
	s_nop 1
	v_permlane32_swap_b32_e32 v181, v0
	s_waitcnt lgkmcnt(0)
	v_max3_f32 v181, v182, v0, v181
	v_sub_f32_e32 v172, v172, v181
	v_mul_f32_e32 v172, 0x3fb8aa3b, v172
	v_sub_f32_e32 v0, v182, v181
	v_exp_f32_e32 v182, v172
	v_sub_f32_e32 v172, v173, v181
	v_sub_f32_e32 v176, v176, v181
	v_sub_f32_e32 v177, v177, v181
	v_mul_f32_e32 v172, 0x3fb8aa3b, v172
	v_mul_f32_e32 v176, 0x3fb8aa3b, v176
	v_mul_f32_e32 v177, 0x3fb8aa3b, v177
	v_sub_f32_e32 v178, v178, v181
	v_sub_f32_e32 v179, v179, v181
	v_exp_f32_e32 v173, v172
	v_sub_f32_e32 v172, v174, v181
	v_exp_f32_e32 v176, v176
	v_exp_f32_e32 v177, v177
	v_mul_f32_e32 v178, 0x3fb8aa3b, v178
	v_mul_f32_e32 v179, 0x3fb8aa3b, v179
	v_mul_f32_e32 v172, 0x3fb8aa3b, v172
	v_exp_f32_e32 v178, v178
	v_exp_f32_e32 v179, v179
	v_exp_f32_e32 v174, v172
	v_sub_f32_e32 v172, v175, v181
	v_mul_f32_e32 v172, 0x3fb8aa3b, v172
	v_mul_f32_e32 v0, 0x3fb8aa3b, v0
	v_exp_f32_e32 v175, v172
	v_exp_f32_e32 v172, v0
	v_cvt_pk_bf16_f32 v238, v176, v177
	v_cvt_pk_bf16_f32 v239, v178, v179
	v_cvt_pk_bf16_f32 v240, v182, v173
	v_cvt_pk_bf16_f32 v241, v174, v175
	v_pk_mul_f32 v[18:19], v[18:19], v[172:173] op_sel_hi:[1,0]
	v_pk_mul_f32 v[16:17], v[16:17], v[172:173] op_sel_hi:[1,0]
	v_pk_mul_f32 v[14:15], v[14:15], v[172:173] op_sel_hi:[1,0]
	v_pk_mul_f32 v[12:13], v[12:13], v[172:173] op_sel_hi:[1,0]
	v_pk_mul_f32 v[10:11], v[10:11], v[172:173] op_sel_hi:[1,0]
	v_pk_mul_f32 v[8:9], v[8:9], v[172:173] op_sel_hi:[1,0]
	v_pk_mul_f32 v[6:7], v[6:7], v[172:173] op_sel_hi:[1,0]
	v_pk_mul_f32 v[4:5], v[4:5], v[172:173] op_sel_hi:[1,0]
	v_mfma_f32_16x16x32_bf16 v[16:19], v[76:79], v[238:241], v[16:19]
	v_mfma_f32_16x16x32_bf16 v[12:15], v[80:83], v[238:241], v[12:15]
	v_mfma_f32_16x16x32_bf16 v[8:11], v[84:87], v[238:241], v[8:11]
	v_mfma_f32_16x16x32_bf16 v[4:7], v[88:91], v[238:241], v[4:7]
	s_cbranch_scc1 .LBB0_1027
	s_cmp_ge_i32 s6, s0
	s_mov_b64 s[10:11], -1
	s_cbranch_scc0 .LBB0_1024
	s_add_i32 s6, s3, s56
	s_add_i32 s8, s6, 1
	s_add_i32 s6, s33, s2
	s_add_i32 s44, s6, 0x60
	s_lshl_b64 s[6:7], s[44:45], 8
	s_add_u32 s6, s30, s6
	s_addc_u32 s7, s31, s7
	s_mov_b64 s[10:11], 0
	s_mov_b32 s44, s8

.LBB0_1030:
	v_max_f32_e32 v2, v177, v177
	v_max_f32_e32 v180, v176, v176
	v_max_f32_e32 v2, v180, v2
	v_max_f32_e32 v180, v179, v179
	v_max_f32_e32 v182, v178, v178
	v_max_f32_e32 v180, v182, v180
	v_max_f32_e32 v182, v175, v175
	v_max_f32_e32 v184, v174, v174
	v_max_f32_e32 v182, v184, v182
	v_max3_f32 v182, v172, v173, v182
	v_max3_f32 v2, v2, v180, v182
	v_mov_b32_e32 v180, v2
	s_nop 1
	v_permlane16_swap_b32_e32 v180, v2
	s_xor_b64 s[8:9], s[46:47], -1
	s_andn2_b64 vcc, exec, s[8:9]
	s_waitcnt lgkmcnt(0)
	v_max_f32_e32 v180, v180, v180
	v_max_f32_e32 v2, v2, v180
	v_mov_b32_e32 v180, v2
	s_nop 1
	v_permlane32_swap_b32_e32 v180, v2
	s_waitcnt lgkmcnt(0)
	v_max3_f32 v202, v213, v2, v180
	v_sub_f32_e32 v176, v176, v202
	v_mul_f32_e32 v176, 0x3fb8aa3b, v176
	v_exp_f32_e32 v211, v176
	v_sub_f32_e32 v176, v177, v202
	v_sub_f32_e32 v172, v172, v202
	v_mul_f32_e32 v176, 0x3fb8aa3b, v176
	v_mul_f32_e32 v172, 0x3fb8aa3b, v172
	v_exp_f32_e32 v212, v176
	v_sub_f32_e32 v176, v178, v202
	v_exp_f32_e32 v217, v172
	v_sub_f32_e32 v172, v173, v202
	v_mul_f32_e32 v176, 0x3fb8aa3b, v176
	v_mul_f32_e32 v172, 0x3fb8aa3b, v172
	v_exp_f32_e32 v215, v176
	v_sub_f32_e32 v176, v179, v202
	v_exp_f32_e32 v218, v172
	v_sub_f32_e32 v172, v174, v202
	v_mul_f32_e32 v176, 0x3fb8aa3b, v176
	v_mul_f32_e32 v172, 0x3fb8aa3b, v172
	v_exp_f32_e32 v216, v176
	v_exp_f32_e32 v219, v172
	v_sub_f32_e32 v172, v175, v202
	v_sub_f32_e32 v2, v213, v202
	v_mul_f32_e32 v172, 0x3fb8aa3b, v172
	v_mul_f32_e32 v2, 0x3fb8aa3b, v2
	v_exp_f32_e32 v220, v172
	v_exp_f32_e32 v2, v2
	v_cvt_pk_bf16_f32 v172, v211, v212
	v_cvt_pk_bf16_f32 v173, v215, v216
	v_cvt_pk_bf16_f32 v174, v217, v218
	v_cvt_pk_bf16_f32 v175, v219, v220
	v_pk_mul_f32 v[122:123], v[122:123], v[2:3] op_sel_hi:[1,0]
	v_pk_mul_f32 v[120:121], v[120:121], v[2:3] op_sel_hi:[1,0]
	v_pk_mul_f32 v[102:103], v[102:103], v[2:3] op_sel_hi:[1,0]
	v_pk_mul_f32 v[100:101], v[100:101], v[2:3] op_sel_hi:[1,0]
	v_pk_mul_f32 v[98:99], v[98:99], v[2:3] op_sel_hi:[1,0]
	v_pk_mul_f32 v[96:97], v[96:97], v[2:3] op_sel_hi:[1,0]
	v_pk_mul_f32 v[94:95], v[94:95], v[2:3] op_sel_hi:[1,0]
	v_pk_mul_f32 v[92:93], v[92:93], v[2:3] op_sel_hi:[1,0]
	v_mfma_f32_16x16x32_bf16 v[120:123], v[124:127], v[172:175], v[120:123]
	v_cndmask_b32_e64 v180, 0, 1, s[8:9]
	v_cmp_ne_u32_e64 s[6:7], 1, v180
	v_mfma_f32_16x16x32_bf16 v[100:103], v[128:131], v[172:175], v[100:103]
	v_mfma_f32_16x16x32_bf16 v[96:99], v[132:135], v[172:175], v[96:99]
	v_mfma_f32_16x16x32_bf16 v[92:95], v[136:139], v[172:175], v[92:95]
	v_mfma_f32_16x16x32_bf16 v[172:175], v[104:107], v[28:31], 0
	v_mfma_f32_16x16x32_bf16 v[176:179], v[112:115], v[28:31], 0
	v_mfma_f32_16x16x32_bf16 v[172:175], v[108:111], v[32:35], v[172:175]
	v_mfma_f32_16x16x32_bf16 v[176:179], v[116:119], v[32:35], v[176:179]
	s_cbranch_vccnz .LBB0_1032
	v_cmp_lt_u32_e32 vcc, s72, v0
	s_nop 4
	v_cndmask_b32_e32 v172, v245, v172, vcc
	v_cmp_lt_u32_e32 vcc, s72, v244
	s_nop 1
	v_cndmask_b32_e32 v173, v245, v173, vcc
	v_cmp_lt_u32_e32 vcc, s72, v252
	s_nop 1
	v_cndmask_b32_e32 v174, v245, v174, vcc
	v_cmp_lt_u32_e32 vcc, s72, v251
	s_nop 1
	v_cndmask_b32_e32 v175, v245, v175, vcc
	v_cmp_lt_u32_e32 vcc, s72, v249
	s_nop 1
	v_cndmask_b32_e32 v176, v245, v176, vcc
	v_cmp_lt_u32_e32 vcc, s72, v248
	s_nop 1
	v_cndmask_b32_e32 v177, v245, v177, vcc
	v_cmp_lt_u32_e32 vcc, s72, v246
	s_nop 1
	v_cndmask_b32_e32 v178, v245, v178, vcc
	v_cmp_lt_u32_e32 vcc, s72, v201
	s_nop 1
	v_cndmask_b32_e32 v179, v245, v179, vcc
.LBB0_1032:
	s_nop 5
	v_max_f32_e32 v180, v173, v173
	v_max_f32_e32 v182, v172, v172
	v_max_f32_e32 v180, v182, v180
	v_max_f32_e32 v182, v175, v175
	v_max_f32_e32 v184, v174, v174
	v_max_f32_e32 v182, v184, v182
	v_max_f32_e32 v184, v179, v179
	v_max_f32_e32 v185, v178, v178
	v_max_f32_e32 v184, v185, v184
	v_max3_f32 v184, v176, v177, v184
	v_max3_f32 v180, v180, v182, v184
	v_mov_b32_e32 v182, v180
	s_nop 1
	v_permlane16_swap_b32_e32 v182, v180
	v_mfma_f32_16x16x32_bf16 v[238:241], v[112:115], v[36:39], 0
	s_and_b64 vcc, exec, s[6:7]
	s_waitcnt lgkmcnt(0)
	v_max_f32_e32 v182, v182, v182
	v_max_f32_e32 v180, v180, v182
	v_mov_b32_e32 v182, v180
	s_nop 1
	v_permlane32_swap_b32_e32 v182, v180
	s_waitcnt lgkmcnt(0)
	v_max3_f32 v182, v214, v180, v182
	v_sub_f32_e32 v172, v172, v182
	v_mul_f32_e32 v172, 0x3fb8aa3b, v172
	v_sub_f32_e32 v180, v214, v182
	v_exp_f32_e32 v214, v172
	v_sub_f32_e32 v172, v173, v182
	v_mul_f32_e32 v172, 0x3fb8aa3b, v172
	v_exp_f32_e32 v221, v172
	v_sub_f32_e32 v172, v174, v182
	v_mul_f32_e32 v172, 0x3fb8aa3b, v172
	v_exp_f32_e32 v222, v172
	v_sub_f32_e32 v172, v175, v182
	v_mul_f32_e32 v172, 0x3fb8aa3b, v172
	v_exp_f32_e32 v223, v172
	v_sub_f32_e32 v172, v176, v182
	v_mul_f32_e32 v172, 0x3fb8aa3b, v172
	v_exp_f32_e32 v247, v172
	v_sub_f32_e32 v172, v177, v182
	v_mul_f32_e32 v172, 0x3fb8aa3b, v172
	v_exp_f32_e32 v250, v172
	v_sub_f32_e32 v172, v178, v182
	v_mul_f32_e32 v172, 0x3fb8aa3b, v172
	v_exp_f32_e32 v253, v172
	v_sub_f32_e32 v172, v179, v182
	v_mul_f32_e32 v172, 0x3fb8aa3b, v172
	v_mul_f32_e32 v180, 0x3fb8aa3b, v180
	v_exp_f32_e32 v235, v172
	v_exp_f32_e32 v180, v180
	v_cvt_pk_bf16_f32 v172, v214, v221
	v_cvt_pk_bf16_f32 v173, v222, v223
	v_cvt_pk_bf16_f32 v174, v247, v250
	v_cvt_pk_bf16_f32 v175, v253, v235
	v_pk_mul_f32 v[58:59], v[58:59], v[180:181] op_sel_hi:[1,0]
	v_pk_mul_f32 v[56:57], v[56:57], v[180:181] op_sel_hi:[1,0]
	v_pk_mul_f32 v[54:55], v[54:55], v[180:181] op_sel_hi:[1,0]
	v_pk_mul_f32 v[52:53], v[52:53], v[180:181] op_sel_hi:[1,0]
	v_pk_mul_f32 v[50:51], v[50:51], v[180:181] op_sel_hi:[1,0]
	v_pk_mul_f32 v[48:49], v[48:49], v[180:181] op_sel_hi:[1,0]
	v_pk_mul_f32 v[46:47], v[46:47], v[180:181] op_sel_hi:[1,0]
	v_pk_mul_f32 v[44:45], v[44:45], v[180:181] op_sel_hi:[1,0]
	v_mfma_f32_16x16x32_bf16 v[56:59], v[124:127], v[172:175], v[56:59]
	v_mfma_f32_16x16x32_bf16 v[52:55], v[128:131], v[172:175], v[52:55]
	v_mfma_f32_16x16x32_bf16 v[48:51], v[132:135], v[172:175], v[48:51]
	v_mfma_f32_16x16x32_bf16 v[44:47], v[136:139], v[172:175], v[44:47]
	v_mfma_f32_16x16x32_bf16 v[172:175], v[104:107], v[36:39], 0
	v_mfma_f32_16x16x32_bf16 v[176:179], v[108:111], v[40:43], v[172:175]
	v_mfma_f32_16x16x32_bf16 v[172:175], v[116:119], v[40:43], v[238:241]
	s_cbranch_vccnz .LBB0_1034
	v_cmp_lt_u32_e32 vcc, s72, v0
	s_nop 4
	v_cndmask_b32_e32 v176, v245, v176, vcc
	v_cmp_lt_u32_e32 vcc, s72, v244
	s_nop 1
	v_cndmask_b32_e32 v177, v245, v177, vcc
	v_cmp_lt_u32_e32 vcc, s72, v252
	s_nop 1
	v_cndmask_b32_e32 v178, v245, v178, vcc
	v_cmp_lt_u32_e32 vcc, s72, v251
	s_nop 1
	v_cndmask_b32_e32 v179, v245, v179, vcc
	v_cmp_lt_u32_e32 vcc, s72, v249
	s_nop 1
	v_cndmask_b32_e32 v172, v245, v172, vcc
	v_cmp_lt_u32_e32 vcc, s72, v248
	s_nop 1
	v_cndmask_b32_e32 v173, v245, v173, vcc
	v_cmp_lt_u32_e32 vcc, s72, v246
	s_nop 1
	v_cndmask_b32_e32 v174, v245, v174, vcc
	v_cmp_lt_u32_e32 vcc, s72, v201
	s_nop 1
	v_cndmask_b32_e32 v175, v245, v175, vcc
.LBB0_1034:
	s_nop 5
	v_max_f32_e32 v0, v177, v177
	v_max_f32_e32 v184, v176, v176
	v_max_f32_e32 v0, v184, v0
	v_max_f32_e32 v184, v179, v179
	v_max_f32_e32 v185, v178, v178
	v_max_f32_e32 v184, v185, v184
	v_max_f32_e32 v185, v175, v175
	v_max_f32_e32 v186, v174, v174
	v_max_f32_e32 v185, v186, v185
	v_max3_f32 v185, v172, v173, v185
	v_max3_f32 v0, v0, v184, v185
	v_mov_b32_e32 v184, v0
	s_nop 1
	v_permlane16_swap_b32_e32 v184, v0
	s_add_i32 s6, s56, 2
	s_cmp_ge_i32 s6, s1
	s_waitcnt lgkmcnt(0)
	v_max_f32_e32 v184, v184, v184
	v_max_f32_e32 v0, v0, v184
	v_mov_b32_e32 v184, v0
	s_nop 1
	v_permlane32_swap_b32_e32 v184, v0
	s_waitcnt lgkmcnt(0)
	v_max3_f32 v213, v181, v0, v184
	v_sub_f32_e32 v172, v172, v213
	v_mul_f32_e32 v172, 0x3fb8aa3b, v172
	v_sub_f32_e32 v0, v181, v213
	v_exp_f32_e32 v181, v172
	v_sub_f32_e32 v172, v173, v213
	v_sub_f32_e32 v176, v176, v213
	v_sub_f32_e32 v177, v177, v213
	v_mul_f32_e32 v172, 0x3fb8aa3b, v172
	v_mul_f32_e32 v176, 0x3fb8aa3b, v176
	v_mul_f32_e32 v177, 0x3fb8aa3b, v177
	v_sub_f32_e32 v178, v178, v213
	v_sub_f32_e32 v179, v179, v213
	v_exp_f32_e32 v173, v172
	v_sub_f32_e32 v172, v174, v213
	v_exp_f32_e32 v176, v176
	v_exp_f32_e32 v177, v177
	v_mul_f32_e32 v178, 0x3fb8aa3b, v178
	v_mul_f32_e32 v179, 0x3fb8aa3b, v179
	v_mul_f32_e32 v172, 0x3fb8aa3b, v172
	v_exp_f32_e32 v178, v178
	v_exp_f32_e32 v179, v179
	v_exp_f32_e32 v174, v172
	v_sub_f32_e32 v172, v175, v213
	v_mul_f32_e32 v172, 0x3fb8aa3b, v172
	v_mul_f32_e32 v0, 0x3fb8aa3b, v0
	v_exp_f32_e32 v175, v172
	v_exp_f32_e32 v172, v0
	v_cvt_pk_bf16_f32 v238, v176, v177
	v_cvt_pk_bf16_f32 v239, v178, v179
	v_cvt_pk_bf16_f32 v240, v181, v173
	v_cvt_pk_bf16_f32 v241, v174, v175
	v_pk_mul_f32 v[18:19], v[18:19], v[172:173] op_sel_hi:[1,0]
	v_pk_mul_f32 v[16:17], v[16:17], v[172:173] op_sel_hi:[1,0]
	v_pk_mul_f32 v[14:15], v[14:15], v[172:173] op_sel_hi:[1,0]
	v_pk_mul_f32 v[12:13], v[12:13], v[172:173] op_sel_hi:[1,0]
	v_pk_mul_f32 v[10:11], v[10:11], v[172:173] op_sel_hi:[1,0]
	v_pk_mul_f32 v[8:9], v[8:9], v[172:173] op_sel_hi:[1,0]
	v_pk_mul_f32 v[6:7], v[6:7], v[172:173] op_sel_hi:[1,0]
	v_pk_mul_f32 v[4:5], v[4:5], v[172:173] op_sel_hi:[1,0]
	v_mfma_f32_16x16x32_bf16 v[16:19], v[124:127], v[238:241], v[16:19]
	v_mfma_f32_16x16x32_bf16 v[12:15], v[128:131], v[238:241], v[12:15]
	v_mfma_f32_16x16x32_bf16 v[8:11], v[132:135], v[238:241], v[8:11]
	v_mfma_f32_16x16x32_bf16 v[4:7], v[136:139], v[238:241], v[4:7]
	s_cbranch_scc1 .LBB0_1040
	s_cmp_lt_i32 s6, s0
	s_mov_b64 s[10:11], -1
	s_cbranch_scc1 .LBB0_1037
	s_add_i32 s6, s3, s56
	s_add_i32 s8, s6, 2
	s_add_i32 s6, s33, s2
	s_add_i32 s44, s6, 0x80
	s_lshl_b64 s[6:7], s[44:45], 8
	s_add_u32 s6, s30, s6
	s_addc_u32 s7, s31, s7
	s_mov_b64 s[10:11], 0
	s_mov_b32 s44, s8

.LBB0_1046:
	v_max_f32_e32 v2, v177, v177
	v_max_f32_e32 v3, v176, v176
	v_max_f32_e32 v2, v3, v2
	v_max_f32_e32 v3, v179, v179
	v_max_f32_e32 v180, v178, v178
	v_max_f32_e32 v3, v180, v3
	v_max_f32_e32 v180, v175, v175
	v_max_f32_e32 v181, v174, v174
	v_max_f32_e32 v180, v181, v180
	v_max3_f32 v180, v172, v173, v180
	v_max3_f32 v2, v2, v3, v180
	v_mov_b32_e32 v3, v2
	s_nop 1
	v_permlane16_swap_b32_e32 v3, v2
	s_xor_b64 s[8:9], s[46:47], -1
	v_cndmask_b32_e64 v181, 0, 1, s[8:9]
	v_cmp_ne_u32_e64 s[6:7], 1, v181
	s_andn2_b64 vcc, exec, s[8:9]
	s_waitcnt lgkmcnt(0)
	v_max_f32_e32 v3, v3, v3
	v_max_f32_e32 v2, v2, v3
	v_mov_b32_e32 v3, v2
	s_nop 1
	v_permlane32_swap_b32_e32 v3, v2
	s_waitcnt lgkmcnt(0)
	v_max3_f32 v180, v202, v2, v3
	v_sub_f32_e32 v3, v176, v180
	v_sub_f32_e32 v176, v177, v180
	v_sub_f32_e32 v172, v172, v180
	v_mul_f32_e32 v176, 0x3fb8aa3b, v176
	v_mul_f32_e32 v172, 0x3fb8aa3b, v172
	v_exp_f32_e32 v212, v176
	v_sub_f32_e32 v176, v178, v180
	v_exp_f32_e32 v216, v172
	v_sub_f32_e32 v172, v173, v180
	v_mul_f32_e32 v176, 0x3fb8aa3b, v176
	v_mul_f32_e32 v172, 0x3fb8aa3b, v172
	v_mul_f32_e32 v3, 0x3fb8aa3b, v3
	v_exp_f32_e32 v214, v176
	v_sub_f32_e32 v176, v179, v180
	v_exp_f32_e32 v217, v172
	v_sub_f32_e32 v172, v174, v180
	v_exp_f32_e32 v3, v3
	v_mul_f32_e32 v176, 0x3fb8aa3b, v176
	v_mul_f32_e32 v172, 0x3fb8aa3b, v172
	v_exp_f32_e32 v215, v176
	v_exp_f32_e32 v218, v172
	v_sub_f32_e32 v172, v175, v180
	v_sub_f32_e32 v2, v202, v180
	v_mul_f32_e32 v172, 0x3fb8aa3b, v172
	v_mul_f32_e32 v2, 0x3fb8aa3b, v2
	v_exp_f32_e32 v219, v172
	v_exp_f32_e32 v2, v2
	v_cvt_pk_bf16_f32 v172, v3, v212
	v_cvt_pk_bf16_f32 v173, v214, v215
	v_cvt_pk_bf16_f32 v174, v216, v217
	v_cvt_pk_bf16_f32 v175, v218, v219
	v_pk_mul_f32 v[122:123], v[122:123], v[2:3] op_sel_hi:[1,0]
	v_pk_mul_f32 v[120:121], v[120:121], v[2:3] op_sel_hi:[1,0]
	v_pk_mul_f32 v[102:103], v[102:103], v[2:3] op_sel_hi:[1,0]
	v_pk_mul_f32 v[100:101], v[100:101], v[2:3] op_sel_hi:[1,0]
	v_pk_mul_f32 v[98:99], v[98:99], v[2:3] op_sel_hi:[1,0]
	v_pk_mul_f32 v[96:97], v[96:97], v[2:3] op_sel_hi:[1,0]
	v_pk_mul_f32 v[94:95], v[94:95], v[2:3] op_sel_hi:[1,0]
	v_pk_mul_f32 v[92:93], v[92:93], v[2:3] op_sel_hi:[1,0]
	v_mfma_f32_16x16x32_bf16 v[120:123], v[156:159], v[172:175], v[120:123]
	v_mfma_f32_16x16x32_bf16 v[100:103], v[160:163], v[172:175], v[100:103]
	v_mfma_f32_16x16x32_bf16 v[96:99], v[164:167], v[172:175], v[96:99]
	v_mfma_f32_16x16x32_bf16 v[92:95], v[168:171], v[172:175], v[92:95]
	v_mfma_f32_16x16x32_bf16 v[172:175], v[140:143], v[28:31], 0
	v_mfma_f32_16x16x32_bf16 v[176:179], v[148:151], v[28:31], 0
	v_mfma_f32_16x16x32_bf16 v[172:175], v[144:147], v[32:35], v[172:175]
	v_mfma_f32_16x16x32_bf16 v[176:179], v[152:155], v[32:35], v[176:179]
	s_cbranch_vccnz .LBB0_1048
	v_cmp_lt_u32_e32 vcc, s72, v0
	s_nop 4
	v_cndmask_b32_e32 v172, v245, v172, vcc
	v_cmp_lt_u32_e32 vcc, s72, v253
	s_nop 1
	v_cndmask_b32_e32 v173, v245, v173, vcc
	v_cmp_lt_u32_e32 vcc, s72, v251
	s_nop 1
	v_cndmask_b32_e32 v174, v245, v174, vcc
	v_cmp_lt_u32_e32 vcc, s72, v250
	s_nop 1
	v_cndmask_b32_e32 v175, v245, v175, vcc
	v_cmp_lt_u32_e32 vcc, s72, v248
	s_nop 1
	v_cndmask_b32_e32 v176, v245, v176, vcc
	v_cmp_lt_u32_e32 vcc, s72, v247
	s_nop 1
	v_cndmask_b32_e32 v177, v245, v177, vcc
	v_cmp_lt_u32_e32 vcc, s72, v223
	s_nop 1
	v_cndmask_b32_e32 v178, v245, v178, vcc
	v_cmp_lt_u32_e32 vcc, s72, v201
	s_nop 1
	v_cndmask_b32_e32 v179, v245, v179, vcc
.LBB0_1048:
	s_nop 5
	v_max_f32_e32 v181, v173, v173
	v_max_f32_e32 v184, v172, v172
	v_max_f32_e32 v181, v184, v181
	v_max_f32_e32 v184, v175, v175
	v_max_f32_e32 v185, v174, v174
	v_max_f32_e32 v184, v185, v184
	v_max_f32_e32 v185, v179, v179
	v_max_f32_e32 v186, v178, v178
	v_max_f32_e32 v185, v186, v185
	v_max3_f32 v185, v176, v177, v185
	v_max3_f32 v181, v181, v184, v185
	v_mov_b32_e32 v184, v181
	s_nop 1
	v_permlane16_swap_b32_e32 v184, v181
	v_mfma_f32_16x16x32_bf16 v[238:241], v[148:151], v[36:39], 0
	s_and_b64 vcc, exec, s[6:7]
	s_waitcnt lgkmcnt(0)
	v_max_f32_e32 v184, v184, v184
	v_max_f32_e32 v181, v181, v184
	v_mov_b32_e32 v184, v181
	s_nop 1
	v_permlane32_swap_b32_e32 v184, v181
	s_waitcnt lgkmcnt(0)
	v_max3_f32 v181, v182, v181, v184
	v_sub_f32_e32 v172, v172, v181
	v_mul_f32_e32 v172, 0x3fb8aa3b, v172
	v_exp_f32_e32 v211, v172
	v_sub_f32_e32 v172, v173, v181
	v_mul_f32_e32 v172, 0x3fb8aa3b, v172
	v_exp_f32_e32 v220, v172
	v_sub_f32_e32 v172, v174, v181
	v_mul_f32_e32 v172, 0x3fb8aa3b, v172
	v_exp_f32_e32 v221, v172
	v_sub_f32_e32 v172, v175, v181
	v_mul_f32_e32 v172, 0x3fb8aa3b, v172
	v_exp_f32_e32 v222, v172
	v_sub_f32_e32 v172, v176, v181
	v_mul_f32_e32 v172, 0x3fb8aa3b, v172
	v_exp_f32_e32 v246, v172
	v_sub_f32_e32 v172, v177, v181
	v_mul_f32_e32 v172, 0x3fb8aa3b, v172
	v_exp_f32_e32 v249, v172
	v_sub_f32_e32 v172, v178, v181
	v_mul_f32_e32 v172, 0x3fb8aa3b, v172
	v_exp_f32_e32 v252, v172
	v_sub_f32_e32 v172, v179, v181
	v_sub_f32_e32 v182, v182, v181
	v_mul_f32_e32 v172, 0x3fb8aa3b, v172
	v_mul_f32_e32 v182, 0x3fb8aa3b, v182
	v_exp_f32_e32 v235, v172
	v_exp_f32_e32 v202, v182
	v_cvt_pk_bf16_f32 v172, v211, v220
	v_cvt_pk_bf16_f32 v173, v221, v222
	v_cvt_pk_bf16_f32 v174, v246, v249
	v_cvt_pk_bf16_f32 v175, v252, v235
	v_pk_mul_f32 v[58:59], v[58:59], v[202:203] op_sel_hi:[1,0]
	v_pk_mul_f32 v[56:57], v[56:57], v[202:203] op_sel_hi:[1,0]
	v_pk_mul_f32 v[54:55], v[54:55], v[202:203] op_sel_hi:[1,0]
	v_pk_mul_f32 v[52:53], v[52:53], v[202:203] op_sel_hi:[1,0]
	v_pk_mul_f32 v[50:51], v[50:51], v[202:203] op_sel_hi:[1,0]
	v_pk_mul_f32 v[48:49], v[48:49], v[202:203] op_sel_hi:[1,0]
	v_pk_mul_f32 v[46:47], v[46:47], v[202:203] op_sel_hi:[1,0]
	v_pk_mul_f32 v[44:45], v[44:45], v[202:203] op_sel_hi:[1,0]
	v_mfma_f32_16x16x32_bf16 v[56:59], v[156:159], v[172:175], v[56:59]
	v_mfma_f32_16x16x32_bf16 v[52:55], v[160:163], v[172:175], v[52:55]
	v_mfma_f32_16x16x32_bf16 v[48:51], v[164:167], v[172:175], v[48:51]
	v_mfma_f32_16x16x32_bf16 v[44:47], v[168:171], v[172:175], v[44:47]
	v_mfma_f32_16x16x32_bf16 v[172:175], v[140:143], v[36:39], 0
	v_mfma_f32_16x16x32_bf16 v[176:179], v[144:147], v[40:43], v[172:175]
	v_mfma_f32_16x16x32_bf16 v[172:175], v[152:155], v[40:43], v[238:241]
	s_cbranch_vccnz .LBB0_1050
	v_cmp_lt_u32_e32 vcc, s72, v0
	s_nop 4
	v_cndmask_b32_e32 v176, v245, v176, vcc
	v_cmp_lt_u32_e32 vcc, s72, v253
	s_nop 1
	v_cndmask_b32_e32 v177, v245, v177, vcc
	v_cmp_lt_u32_e32 vcc, s72, v251
	s_nop 1
	v_cndmask_b32_e32 v178, v245, v178, vcc
	v_cmp_lt_u32_e32 vcc, s72, v250
	s_nop 1
	v_cndmask_b32_e32 v179, v245, v179, vcc
	v_cmp_lt_u32_e32 vcc, s72, v248
	s_nop 1
	v_cndmask_b32_e32 v172, v245, v172, vcc
	v_cmp_lt_u32_e32 vcc, s72, v247
	s_nop 1
	v_cndmask_b32_e32 v173, v245, v173, vcc
	v_cmp_lt_u32_e32 vcc, s72, v223
	s_nop 1
	v_cndmask_b32_e32 v174, v245, v174, vcc
	v_cmp_lt_u32_e32 vcc, s72, v201
	s_nop 1
	v_cndmask_b32_e32 v175, v245, v175, vcc
.LBB0_1050:
	s_nop 5
	v_max_f32_e32 v0, v177, v177
	v_max_f32_e32 v182, v176, v176
	v_max_f32_e32 v0, v182, v0
	v_max_f32_e32 v182, v179, v179
	v_max_f32_e32 v184, v178, v178
	v_max_f32_e32 v182, v184, v182
	v_max_f32_e32 v184, v175, v175
	v_max_f32_e32 v185, v174, v174
	v_max_f32_e32 v184, v185, v184
	v_max3_f32 v184, v172, v173, v184
	v_max3_f32 v0, v0, v182, v184
	v_mov_b32_e32 v182, v0
	s_nop 1
	v_permlane16_swap_b32_e32 v182, v0
	s_add_i32 s12, s56, 3
	s_cmp_ge_i32 s12, s1
	s_waitcnt lgkmcnt(0)
	v_max_f32_e32 v182, v182, v182
	v_max_f32_e32 v0, v0, v182
	v_mov_b32_e32 v182, v0
	s_nop 1
	v_permlane32_swap_b32_e32 v182, v0
	s_waitcnt lgkmcnt(0)
	v_max3_f32 v182, v213, v0, v182
	v_sub_f32_e32 v172, v172, v182
	v_mul_f32_e32 v172, 0x3fb8aa3b, v172
	v_sub_f32_e32 v0, v213, v182
	v_exp_f32_e32 v213, v172
	v_sub_f32_e32 v172, v173, v182
	v_sub_f32_e32 v176, v176, v182
	v_sub_f32_e32 v177, v177, v182
	v_mul_f32_e32 v172, 0x3fb8aa3b, v172
	v_mul_f32_e32 v176, 0x3fb8aa3b, v176
	v_mul_f32_e32 v177, 0x3fb8aa3b, v177
	v_sub_f32_e32 v178, v178, v182
	v_sub_f32_e32 v179, v179, v182
	v_exp_f32_e32 v173, v172
	v_sub_f32_e32 v172, v174, v182
	v_exp_f32_e32 v176, v176
	v_exp_f32_e32 v177, v177
	v_mul_f32_e32 v178, 0x3fb8aa3b, v178
	v_mul_f32_e32 v179, 0x3fb8aa3b, v179
	v_mul_f32_e32 v172, 0x3fb8aa3b, v172
	v_exp_f32_e32 v178, v178
	v_exp_f32_e32 v179, v179
	v_exp_f32_e32 v174, v172
	v_sub_f32_e32 v172, v175, v182
	v_mul_f32_e32 v172, 0x3fb8aa3b, v172
	v_mul_f32_e32 v0, 0x3fb8aa3b, v0
	v_exp_f32_e32 v175, v172
	v_exp_f32_e32 v172, v0
	v_cvt_pk_bf16_f32 v238, v176, v177
	v_cvt_pk_bf16_f32 v239, v178, v179
	v_cvt_pk_bf16_f32 v240, v213, v173
	v_cvt_pk_bf16_f32 v241, v174, v175
	v_pk_mul_f32 v[18:19], v[18:19], v[172:173] op_sel_hi:[1,0]
	v_pk_mul_f32 v[16:17], v[16:17], v[172:173] op_sel_hi:[1,0]
	v_pk_mul_f32 v[14:15], v[14:15], v[172:173] op_sel_hi:[1,0]
	v_pk_mul_f32 v[12:13], v[12:13], v[172:173] op_sel_hi:[1,0]
	v_pk_mul_f32 v[10:11], v[10:11], v[172:173] op_sel_hi:[1,0]
	v_pk_mul_f32 v[8:9], v[8:9], v[172:173] op_sel_hi:[1,0]
	v_pk_mul_f32 v[6:7], v[6:7], v[172:173] op_sel_hi:[1,0]
	v_pk_mul_f32 v[4:5], v[4:5], v[172:173] op_sel_hi:[1,0]
	v_mfma_f32_16x16x32_bf16 v[16:19], v[156:159], v[238:241], v[16:19]
	v_mfma_f32_16x16x32_bf16 v[12:15], v[160:163], v[238:241], v[12:15]
	v_mfma_f32_16x16x32_bf16 v[8:11], v[164:167], v[238:241], v[8:11]
	v_mfma_f32_16x16x32_bf16 v[4:7], v[168:171], v[238:241], v[4:7]
	s_cbranch_scc1 .LBB0_1056
	s_cmp_lt_i32 s12, s0
	s_mov_b64 s[10:11], -1
	s_cbranch_scc1 .LBB0_1053
	s_add_i32 s6, s3, s56
	s_add_i32 s8, s6, 3
	s_add_i32 s6, s33, s2
	s_add_i32 s44, s6, 0xa0
	s_lshl_b64 s[6:7], s[44:45], 8
	s_add_u32 s6, s30, s6
	s_addc_u32 s7, s31, s7
	s_mov_b64 s[10:11], 0
	s_mov_b32 s44, s8

.LBB0_1062:
	s_or_b64 exec, exec, s[12:13]
	v_add_f32_e32 v94, 0, v153
	v_add_f32_e32 v94, v155, v94
	v_add_f32_e32 v11, 0, v11
	v_add_f32_e32 v94, v157, v94
	v_add_f32_e32 v11, v164, v11
	v_add_f32_e32 v94, v159, v94
	v_add_f32_e32 v11, v165, v11
	v_add_f32_e32 v94, v160, v94
	v_add_f32_e32 v11, v166, v11
	v_add_f32_e32 v94, v161, v94
	v_add_f32_e32 v11, v167, v11
	v_add_f32_e32 v94, v162, v94
	v_add_f32_e32 v11, v168, v11
	v_add_f32_e32 v94, v163, v94
	v_add_f32_e32 v11, v169, v11
	v_add_f32_e32 v10, v10, v94
	v_add_f32_e32 v11, v170, v11
	v_fmac_f32_e32 v11, v10, v152
	v_add_f32_e32 v10, 0, v171
	v_add_f32_e32 v10, v172, v10
	v_add_f32_e32 v10, v173, v10
	v_add_f32_e32 v10, v174, v10
	v_add_f32_e32 v10, v175, v10
	v_add_f32_e32 v10, v176, v10
	v_add_f32_e32 v10, v177, v10
	v_add_f32_e32 v10, v178, v10
	v_fmac_f32_e32 v10, v11, v154
	v_add_f32_e32 v11, 0, v191
	v_add_f32_e32 v11, v193, v11
	v_add_f32_e32 v11, v194, v11
	v_add_f32_e32 v11, v195, v11
	v_add_f32_e32 v11, v196, v11
	v_add_f32_e32 v11, v197, v11
	v_add_f32_e32 v11, v198, v11
	v_add_f32_e32 v11, v199, v11
	v_fmac_f32_e32 v11, v10, v156
	v_add_f32_e32 v10, 0, v200
	v_add_f32_e32 v10, v201, v10
	v_add_f32_e32 v10, v202, v10
	v_add_f32_e32 v10, v203, v10
	v_add_f32_e32 v10, v204, v10
	v_add_f32_e32 v10, v205, v10
	v_add_f32_e32 v10, v206, v10
	v_add_f32_e32 v10, v207, v10
	v_fmac_f32_e32 v10, v11, v158
	v_add_f32_e32 v11, 0, v125
	v_add_f32_e32 v11, v126, v11
	v_add_f32_e32 v11, v127, v11
	v_add_f32_e32 v11, v128, v11
	v_add_f32_e32 v11, v129, v11
	v_add_f32_e32 v11, v208, v11
	v_add_f32_e32 v11, v209, v11
	v_add_f32_e32 v11, v210, v11
	v_fmac_f32_e32 v11, v10, v0
	v_add_f32_e32 v0, 0, v213
	v_add_f32_e32 v0, v214, v0
	v_add_f32_e32 v0, v215, v0
	v_add_f32_e32 v0, v216, v0
	v_add_f32_e32 v0, v217, v0
	v_add_f32_e32 v0, v218, v0
	v_add_f32_e32 v0, v219, v0
	v_add_f32_e32 v101, v220, v0
	v_lshlrev_b32_e32 v0, 11, v141
	v_fmac_f32_e32 v101, v11, v124
	v_lshl_add_u64 v[10:11], s[8:9], 0, v[0:1]
	s_mov_b32 s31, s45
	v_lshl_add_u64 v[128:129], v[10:11], 0, s[30:31]
	v_max_f32_e32 v0, v100, v100
	v_max_f32_e32 v10, v211, v211
	v_max_f32_e32 v0, v10, v0
	v_max_f32_e32 v10, v98, v98
	v_max_f32_e32 v11, v96, v96
	v_max_f32_e32 v10, v11, v10
	v_max_f32_e32 v11, v93, v93
	v_max_f32_e32 v94, v92, v92
	v_max_f32_e32 v11, v94, v11
	v_max3_f32 v11, v97, v99, v11
	v_max3_f32 v0, v0, v10, v11
	v_mov_b32_e32 v10, v0
	s_nop 1
	v_permlane16_swap_b32_e32 v10, v0
	v_mov_b32_e32 v149, v1
	v_mov_b32_e32 v145, v1
	s_mov_b64 s[0:1], 0xc000
	s_waitcnt vmcnt(15)
	v_mfma_f32_16x16x32_bf16 v[88:91], v[88:91], v[6:9], 0
	s_waitcnt lgkmcnt(0)
	v_max_f32_e32 v10, v10, v10
	v_max_f32_e32 v0, v0, v10
	v_mov_b32_e32 v10, v0
	s_nop 1
	v_permlane32_swap_b32_e32 v10, v0
	v_mov_b32_e32 v143, v1
	s_waitcnt vmcnt(13)
	v_mfma_f32_16x16x32_bf16 v[84:87], v[84:87], v[6:9], 0
	v_mov_b32_e32 v147, v1
	s_waitcnt lgkmcnt(0)
	v_max3_f32 v124, v212, v0, v10
	v_sub_f32_e32 v94, v96, v124
	v_mul_f32_e32 v94, 0x3fb8aa3b, v94
	v_sub_f32_e32 v10, v211, v124
	v_sub_f32_e32 v11, v100, v124
	v_exp_f32_e32 v100, v94
	v_sub_f32_e32 v94, v98, v124
	v_mul_f32_e32 v10, 0x3fb8aa3b, v10
	v_mul_f32_e32 v94, 0x3fb8aa3b, v94
	v_exp_f32_e32 v10, v10
	v_mul_f32_e32 v11, 0x3fb8aa3b, v11
	v_exp_f32_e32 v102, v94
	v_sub_f32_e32 v94, v97, v124
	v_exp_f32_e32 v11, v11
	v_mul_f32_e32 v94, 0x3fb8aa3b, v94
	v_sub_f32_e32 v92, v92, v124
	v_exp_f32_e32 v103, v94
	v_sub_f32_e32 v94, v99, v124
	v_mul_f32_e32 v92, 0x3fb8aa3b, v92
	v_mul_f32_e32 v94, 0x3fb8aa3b, v94
	v_exp_f32_e32 v126, v92
	v_sub_f32_e32 v92, v93, v124
	v_sub_f32_e32 v0, v212, v124
	v_exp_f32_e32 v125, v94
	v_mul_f32_e32 v92, 0x3fb8aa3b, v92
	v_add_u32_e32 v93, 0x8000, v10
	v_add_f32_e32 v10, 0, v10
	v_mul_f32_e32 v0, 0x3fb8aa3b, v0
	v_exp_f32_e32 v127, v92
	v_add_f32_e32 v10, v11, v10
	v_exp_f32_e32 v0, v0
	v_add_u32_e32 v92, 0x8000, v11
	v_add_f32_e32 v10, v100, v10
	v_perm_b32 v92, v92, v93, s87
	v_add_f32_e32 v10, v102, v10
	v_cvt_pk_bf16_f32 v93, v100, v102
	v_add_f32_e32 v10, v103, v10
	v_cvt_pk_bf16_f32 v94, v103, v125
	v_add_f32_e32 v10, v125, v10
	v_cvt_pk_bf16_f32 v95, v126, v127
	v_pk_mul_f32 v[98:99], v[122:123], v[0:1] op_sel_hi:[1,0]
	v_pk_mul_f32 v[96:97], v[120:121], v[0:1] op_sel_hi:[1,0]
	v_add_f32_e32 v10, v126, v10
	v_add_f32_e32 v125, v127, v10
	v_mfma_f32_16x16x32_bf16 v[120:123], v[60:63], v[92:95], v[96:99]
	v_mul_f32_e64 v62, v118, v0
	v_mul_f32_e64 v63, v119, v0
	v_pk_mul_f32 v[60:61], v[116:117], v[0:1] op_sel_hi:[1,0]
	v_lshl_add_u64 v[10:11], s[28:29], 0, v[148:149]
	v_lshl_add_u64 v[144:145], v[10:11], 0, v[144:145]
	v_mfma_f32_16x16x32_bf16 v[108:111], v[52:55], v[92:95], v[60:63]
	v_mul_f32_e64 v54, v114, v0
	v_mul_f32_e64 v55, v115, v0
	v_pk_mul_f32 v[52:53], v[112:113], v[0:1] op_sel_hi:[1,0]
	v_lshl_add_u64 v[10:11], v[144:145], 0, s[0:1]
	s_mov_b32 s0, 0xc000
	v_mfma_f32_16x16x32_bf16 v[112:115], v[48:51], v[92:95], v[52:55]
	v_mul_f32_e64 v50, v106, v0
	v_mul_f32_e64 v51, v107, v0
	v_pk_mul_f32 v[48:49], v[104:105], v[0:1] op_sel_hi:[1,0]
	v_fmac_f32_e32 v125, v101, v0
	v_mfma_f32_16x16x32_bf16 v[80:83], v[80:83], v[2:5], v[88:91]
	v_mfma_f32_16x16x32_bf16 v[116:119], v[44:47], v[92:95], v[48:51]
	v_add_co_u32_e32 v44, vcc, s0, v144
	s_mov_b64 s[0:1], 0x2000
	s_nop 0
	v_addc_co_u32_e32 v45, vcc, 0, v145, vcc
	global_load_dwordx4 v[104:107], v[44:45], off
	global_load_dwordx4 v[96:99], v[10:11], off offset:16
	global_load_dwordx4 v[100:103], v[10:11], off offset:3072
	global_load_dwordx4 v[92:95], v[10:11], off offset:3088
	v_lshl_add_u64 v[10:11], s[26:27], 0, v[142:143]
	v_lshl_add_u64 v[142:143], v[10:11], 0, v[146:147]
	v_lshl_add_u64 v[10:11], v[142:143], 0, s[0:1]
	s_movk_i32 s0, 0x2000
	v_add_co_u32_e32 v44, vcc, s0, v142
	s_waitcnt vmcnt(16)
	v_mfma_f32_16x16x32_bf16 v[68:71], v[68:71], v[2:5], v[84:87]
	v_addc_co_u32_e32 v45, vcc, 0, v143, vcc
	global_load_dwordx4 v[60:63], v[44:45], off
	global_load_dwordx4 v[52:55], v[10:11], off offset:256
	global_load_dwordx4 v[48:51], v[10:11], off offset:512
	s_nop 0
	global_load_dwordx4 v[44:47], v[10:11], off offset:768
	v_max_f32_e32 v0, v81, v81
	v_max_f32_e32 v10, v80, v80
	v_max_f32_e32 v0, v10, v0
	v_max_f32_e32 v10, v83, v83
	v_max_f32_e32 v11, v82, v82
	v_max_f32_e32 v10, v11, v10
	v_max_f32_e32 v11, v71, v71
	v_max_f32_e32 v84, v70, v70
	v_max_f32_e32 v11, v84, v11
	v_max3_f32 v11, v68, v69, v11
	v_max3_f32 v0, v0, v10, v11
	v_mov_b32_e32 v10, v0
	s_nop 1
	v_permlane16_swap_b32_e32 v10, v0
	s_waitcnt vmcnt(13)
	v_mfma_f32_16x16x32_bf16 v[76:79], v[76:79], v[6:9], 0
	s_mov_b32 s0, 0x12000
	s_waitcnt lgkmcnt(0)
	v_max_f32_e32 v10, v10, v10
	v_max_f32_e32 v0, v0, v10
	v_mov_b32_e32 v10, v0
	s_nop 1
	v_permlane32_swap_b32_e32 v10, v0
	v_mfma_f32_16x16x32_bf16 v[72:75], v[72:75], v[6:9], 0
	s_waitcnt lgkmcnt(0)
	v_max3_f32 v11, v124, v0, v10
	v_sub_f32_e32 v10, v80, v11
	v_sub_f32_e32 v68, v68, v11
	v_mul_f32_e32 v10, 0x3fb8aa3b, v10
	v_mul_f32_e32 v68, 0x3fb8aa3b, v68
	v_exp_f32_e32 v88, v10
	v_sub_f32_e32 v10, v81, v11
	v_exp_f32_e32 v148, v68
	v_sub_f32_e32 v68, v69, v11
	v_mul_f32_e32 v10, 0x3fb8aa3b, v10
	v_mul_f32_e32 v68, 0x3fb8aa3b, v68
	v_exp_f32_e32 v89, v10
	v_sub_f32_e32 v10, v82, v11
	v_sub_f32_e32 v80, v83, v11
	v_exp_f32_e32 v152, v68
	v_sub_f32_e32 v68, v70, v11
	v_mul_f32_e32 v10, 0x3fb8aa3b, v10
	v_mul_f32_e32 v80, 0x3fb8aa3b, v80
	v_mul_f32_e32 v68, 0x3fb8aa3b, v68
	v_exp_f32_e32 v10, v10
	v_exp_f32_e32 v146, v80
	v_exp_f32_e32 v154, v68
	v_sub_f32_e32 v68, v71, v11
	v_sub_f32_e32 v0, v124, v11
	v_mul_f32_e32 v68, 0x3fb8aa3b, v68
	v_mul_f32_e32 v0, 0x3fb8aa3b, v0
	v_exp_f32_e32 v156, v68
	v_exp_f32_e32 v0, v0
	v_cvt_pk_bf16_f32 v68, v88, v89
	v_cvt_pk_bf16_f32 v69, v10, v146
	v_cvt_pk_bf16_f32 v70, v148, v152
	v_cvt_pk_bf16_f32 v71, v154, v156
	v_pk_mul_f32 v[82:83], v[122:123], v[0:1] op_sel_hi:[1,0]
	v_pk_mul_f32 v[80:81], v[120:121], v[0:1] op_sel_hi:[1,0]
	v_mfma_f32_16x16x32_bf16 v[64:67], v[64:67], v[2:5], v[76:79]
	v_mul_f32_e32 v158, v125, v0
	v_mfma_f32_16x16x32_bf16 v[120:123], v[40:43], v[68:71], v[80:83]
	v_mul_f32_e64 v42, v110, v0
	v_mul_f32_e64 v43, v111, v0
	v_pk_mul_f32 v[40:41], v[108:109], v[0:1] op_sel_hi:[1,0]
	s_waitcnt vmcnt(12)
	v_mfma_f32_16x16x32_bf16 v[56:59], v[56:59], v[2:5], v[72:75]
	v_mfma_f32_16x16x32_bf16 v[124:127], v[36:39], v[68:71], v[40:43]
	v_mul_f32_e64 v38, v114, v0
	v_mul_f32_e64 v39, v115, v0
	v_pk_mul_f32 v[36:37], v[112:113], v[0:1] op_sel_hi:[1,0]
	v_max_f32_e32 v72, v65, v65
	v_max_f32_e32 v73, v64, v64
	v_mfma_f32_16x16x32_bf16 v[40:43], v[32:35], v[68:71], v[36:39]
	v_mul_f32_e64 v34, v118, v0
	v_mul_f32_e64 v35, v119, v0
	v_pk_mul_f32 v[32:33], v[116:117], v[0:1] op_sel_hi:[1,0]
	v_add_f32_e32 v0, 0, v88
	v_add_f32_e32 v0, v89, v0
	v_mfma_f32_16x16x32_bf16 v[84:87], v[28:31], v[68:71], v[32:35]
	v_add_co_u32_e32 v28, vcc, s0, v130
	v_max_f32_e32 v72, v73, v72
	s_nop 0
	v_addc_co_u32_e32 v29, vcc, 0, v131, vcc
	global_load_dwordx4 v[112:115], v[28:29], off
	global_load_dwordx4 v[88:91], v[28:29], off offset:16
	global_load_dwordx4 v[108:111], v[28:29], off offset:3072
	global_load_dwordx4 v[80:83], v[28:29], off offset:3088
	v_max_f32_e32 v73, v67, v67
	v_max_f32_e32 v74, v66, v66
	v_max_f32_e32 v73, v74, v73
	v_max_f32_e32 v74, v59, v59
	v_max_f32_e32 v75, v58, v58
	v_max_f32_e32 v74, v75, v74
	v_max3_f32 v74, v56, v57, v74
	v_max3_f32 v72, v72, v73, v74
	v_mov_b32_e32 v73, v72
	s_nop 1
	v_permlane16_swap_b32_e32 v73, v72
	s_waitcnt vmcnt(11)
	v_mfma_f32_16x16x32_bf16 v[104:107], v[104:107], v[6:9], 0
	s_movk_i32 s0, 0x3000
	v_add_co_u32_e32 v28, vcc, s0, v150
	s_waitcnt lgkmcnt(0)
	v_max_f32_e32 v73, v73, v73
	v_max_f32_e32 v72, v72, v73
	v_mov_b32_e32 v73, v72
	s_nop 1
	v_permlane32_swap_b32_e32 v73, v72
	s_waitcnt vmcnt(9)
	v_mfma_f32_16x16x32_bf16 v[100:103], v[100:103], v[6:9], 0
	s_mov_b64 s[0:1], 0x18000
	v_addc_co_u32_e32 v29, vcc, 0, v151, vcc
	s_waitcnt lgkmcnt(0)
	v_max3_f32 v141, v11, v72, v73
	v_sub_f32_e32 v11, v11, v141
	v_mul_f32_e32 v72, 0x3fb8aa3b, v11
	v_sub_f32_e32 v11, v64, v141
	v_sub_f32_e32 v64, v65, v141
	v_sub_f32_e32 v56, v56, v141
	v_mul_f32_e32 v64, 0x3fb8aa3b, v64
	v_mul_f32_e32 v56, 0x3fb8aa3b, v56
	v_exp_f32_e32 v147, v64
	v_sub_f32_e32 v64, v66, v141
	v_exp_f32_e32 v155, v56
	v_sub_f32_e32 v56, v57, v141
	v_mul_f32_e32 v11, 0x3fb8aa3b, v11
	v_mul_f32_e32 v64, 0x3fb8aa3b, v64
	v_mul_f32_e32 v56, 0x3fb8aa3b, v56
	v_exp_f32_e32 v11, v11
	v_exp_f32_e32 v149, v64
	v_sub_f32_e32 v64, v67, v141
	v_exp_f32_e32 v157, v56
	v_sub_f32_e32 v56, v58, v141
	v_mul_f32_e32 v64, 0x3fb8aa3b, v64
	v_mul_f32_e32 v56, 0x3fb8aa3b, v56
	v_exp_f32_e32 v153, v64
	v_exp_f32_e32 v159, v56
	v_sub_f32_e32 v56, v59, v141
	v_mul_f32_e32 v56, 0x3fb8aa3b, v56
	v_exp_f32_e32 v73, v56
	v_add_u32_e32 v57, 0x8000, v11
	v_pk_add_f32 v[10:11], v[10:11], v[0:1]
	v_exp_f32_e32 v72, v72
	v_add_u32_e32 v56, 0x8000, v147
	v_pk_add_f32 v[10:11], v[146:147], v[10:11]
	v_perm_b32 v56, v56, v57, s87
	v_pk_add_f32 v[10:11], v[148:149], v[10:11]
	v_cvt_pk_bf16_f32 v57, v149, v153
	v_pk_add_f32 v[10:11], v[152:153], v[10:11]
	v_cvt_pk_bf16_f32 v58, v155, v157
	v_pk_add_f32 v[10:11], v[154:155], v[10:11]
	v_mfma_f32_16x16x32_bf16 v[96:99], v[96:99], v[2:5], v[104:107]
	v_cvt_pk_bf16_f32 v59, v159, v73
	v_pk_mul_f32 v[66:67], v[122:123], v[72:73] op_sel_hi:[1,0]
	v_pk_mul_f32 v[64:65], v[120:121], v[72:73] op_sel_hi:[1,0]
	v_pk_add_f32 v[10:11], v[156:157], v[10:11]
	s_waitcnt vmcnt(8)
	v_mfma_f32_16x16x32_bf16 v[92:95], v[92:95], v[2:5], v[100:103]
	v_add_f32_e64 v10, v158, v10
	v_add_f32_e64 v11, v159, v11
	v_max_f32_e32 v0, v97, v97
	global_load_dwordx4 v[68:71], v[28:29], off
	global_load_dwordx4 v[36:39], v[28:29], off offset:256
	global_load_dwordx4 v[32:35], v[28:29], off offset:512
	s_nop 0
	global_load_dwordx4 v[28:31], v[28:29], off offset:768
	v_mfma_f32_16x16x32_bf16 v[120:123], v[24:27], v[56:59], v[64:67]
	v_mul_f32_e64 v26, v126, v72
	v_mul_f32_e64 v27, v127, v72
	v_pk_mul_f32 v[24:25], v[124:125], v[72:73] op_sel_hi:[1,0]
	v_max_f32_e32 v100, v98, v98
	v_max_f32_e32 v101, v94, v94
	v_mfma_f32_16x16x32_bf16 v[116:119], v[20:23], v[56:59], v[24:27]
	v_mul_f32_e64 v22, v42, v72
	v_mul_f32_e64 v23, v43, v72
	v_pk_mul_f32 v[20:21], v[40:41], v[72:73] op_sel_hi:[1,0]
	v_add_f32_e32 v27, v11, v73
	s_nop 0
	v_mfma_f32_16x16x32_bf16 v[40:43], v[16:19], v[56:59], v[20:23]
	v_mul_f32_e64 v18, v86, v72
	v_mul_f32_e64 v19, v87, v72
	v_pk_mul_f32 v[16:17], v[84:85], v[72:73] op_sel_hi:[1,0]
	v_fmac_f32_e32 v27, v10, v72
	v_lshl_add_u64 v[10:11], v[144:145], 0, s[0:1]
	s_mov_b32 s0, 0x18000
	v_max_f32_e32 v26, v96, v96
	v_mfma_f32_16x16x32_bf16 v[56:59], v[12:15], v[56:59], v[16:19]
	v_add_co_u32_e32 v12, vcc, s0, v144
	v_max_f32_e32 v0, v26, v0
	v_max_f32_e32 v26, v99, v99
	v_addc_co_u32_e32 v13, vcc, 0, v145, vcc
	v_max_f32_e32 v26, v100, v26
	v_max_f32_e32 v100, v95, v95
	global_load_dwordx4 v[84:87], v[12:13], off
	global_load_dwordx4 v[72:75], v[10:11], off offset:16
	global_load_dwordx4 v[76:79], v[10:11], off offset:3072
	global_load_dwordx4 v[64:67], v[10:11], off offset:3088
	v_max_f32_e32 v100, v101, v100
	v_max3_f32 v100, v92, v93, v100
	v_max3_f32 v0, v0, v26, v100
	v_mov_b32_e32 v26, v0
	s_nop 1
	v_permlane16_swap_b32_e32 v26, v0
	s_mov_b64 s[0:1], 0x4000
	v_lshl_add_u64 v[10:11], v[142:143], 0, s[0:1]
	s_movk_i32 s0, 0x5000
	v_add_co_u32_e32 v156, vcc, s0, v142
	s_waitcnt lgkmcnt(0)
	v_max_f32_e32 v26, v26, v26
	v_max_f32_e32 v0, v0, v26
	v_mov_b32_e32 v26, v0
	s_nop 1
	v_permlane32_swap_b32_e32 v26, v0
	s_mov_b64 s[0:1], 0x1e000
	v_addc_co_u32_e32 v157, vcc, 0, v143, vcc
	global_load_dwordx4 v[22:25], v[156:157], off offset:-4096
	global_load_dwordx4 v[18:21], v[10:11], off offset:256
	global_load_dwordx4 v[14:17], v[10:11], off offset:512
	s_nop 0
	global_load_dwordx4 v[10:13], v[10:11], off offset:768
	s_waitcnt lgkmcnt(0)
	v_max3_f32 v125, v141, v0, v26
	v_sub_f32_e32 v26, v96, v125
	v_sub_f32_e32 v92, v92, v125
	v_mul_f32_e32 v26, 0x3fb8aa3b, v26
	v_mul_f32_e32 v92, 0x3fb8aa3b, v92
	v_exp_f32_e32 v100, v26
	v_sub_f32_e32 v26, v97, v125
	v_exp_f32_e32 v126, v92
	v_sub_f32_e32 v92, v93, v125
	v_sub_f32_e32 v0, v141, v125
	v_mul_f32_e32 v26, 0x3fb8aa3b, v26
	v_mul_f32_e32 v92, 0x3fb8aa3b, v92
	v_mul_f32_e32 v0, 0x3fb8aa3b, v0
	v_exp_f32_e32 v101, v26
	v_sub_f32_e32 v26, v98, v125
	v_sub_f32_e32 v96, v99, v125
	v_exp_f32_e32 v146, v92
	v_sub_f32_e32 v92, v94, v125
	v_mul_f32_e32 v26, 0x3fb8aa3b, v26
	v_mul_f32_e32 v96, 0x3fb8aa3b, v96
	v_mul_f32_e32 v92, 0x3fb8aa3b, v92
	v_exp_f32_e32 v0, v0
	v_exp_f32_e32 v26, v26
	v_exp_f32_e32 v124, v96
	v_exp_f32_e32 v148, v92
	v_sub_f32_e32 v92, v95, v125
	v_mul_f32_e32 v92, 0x3fb8aa3b, v92
	v_exp_f32_e32 v152, v92
	v_mul_f32_e32 v154, v27, v0
	v_cvt_pk_bf16_f32 v92, v100, v101
	v_cvt_pk_bf16_f32 v93, v26, v124
	v_cvt_pk_bf16_f32 v94, v126, v146
	v_cvt_pk_bf16_f32 v95, v148, v152
	v_pk_mul_f32 v[42:43], v[42:43], v[0:1] op_sel_hi:[1,0]
	v_pk_mul_f32 v[40:41], v[40:41], v[0:1] op_sel_hi:[1,0]
	v_pk_mul_f32 v[98:99], v[122:123], v[0:1] op_sel_hi:[1,0]
	v_pk_mul_f32 v[96:97], v[120:121], v[0:1] op_sel_hi:[1,0]
	s_waitcnt vmcnt(17)
	v_mfma_f32_16x16x32_bf16 v[104:107], v[48:51], v[92:95], v[40:43]
	s_nop 2
	v_mul_f32_e64 v42, v58, v0
	v_mul_f32_e64 v43, v59, v0
	v_pk_mul_f32 v[40:41], v[56:57], v[0:1] op_sel_hi:[1,0]
	v_mfma_f32_16x16x32_bf16 v[120:123], v[60:63], v[92:95], v[96:99]
	v_mul_f32_e64 v62, v118, v0
	v_mul_f32_e64 v63, v119, v0
	v_pk_mul_f32 v[60:61], v[116:117], v[0:1] op_sel_hi:[1,0]
	v_add_f32_e32 v0, 0, v100
	s_waitcnt vmcnt(16)
	v_mfma_f32_16x16x32_bf16 v[56:59], v[44:47], v[92:95], v[40:43]
	v_add_f32_e32 v0, v101, v0
	s_nop 1
	v_lshl_add_u64 v[40:41], v[144:145], 0, s[0:1]
	s_mov_b32 s0, 0x1e000
	v_add_co_u32_e32 v42, vcc, s0, v144
	v_mfma_f32_16x16x32_bf16 v[116:119], v[52:55], v[92:95], v[60:63]
	s_nop 0
	v_addc_co_u32_e32 v43, vcc, 0, v145, vcc
	global_load_dwordx4 v[100:103], v[42:43], off
	global_load_dwordx4 v[92:95], v[40:41], off offset:16
	global_load_dwordx4 v[96:99], v[40:41], off offset:3072
	global_load_dwordx4 v[60:63], v[40:41], off offset:3088
	s_waitcnt vmcnt(19)
	v_mfma_f32_16x16x32_bf16 v[112:115], v[112:115], v[6:9], 0
	s_mov_b64 s[0:1], 0x5000
	v_lshl_add_u64 v[40:41], v[142:143], 0, s[0:1]
	global_load_dwordx4 v[52:55], v[156:157], off
	global_load_dwordx4 v[48:51], v[40:41], off offset:256
	global_load_dwordx4 v[44:47], v[40:41], off offset:512
	s_nop 0
	global_load_dwordx4 v[40:43], v[40:41], off offset:768
	s_waitcnt vmcnt(21)
	v_mfma_f32_16x16x32_bf16 v[108:111], v[108:111], v[6:9], 0
	s_mov_b32 s0, 0x24000
	v_mfma_f32_16x16x32_bf16 v[88:91], v[88:91], v[2:5], v[112:115]
	s_waitcnt vmcnt(20)
	v_mfma_f32_16x16x32_bf16 v[80:83], v[80:83], v[2:5], v[108:111]
	s_waitcnt vmcnt(15)
	v_mfma_f32_16x16x32_bf16 v[84:87], v[84:87], v[6:9], 0
	s_nop 3
	v_max_f32_e32 v27, v89, v89
	v_max_f32_e32 v108, v88, v88
	v_max_f32_e32 v27, v108, v27
	v_max_f32_e32 v108, v91, v91
	v_max_f32_e32 v109, v90, v90
	v_max_f32_e32 v108, v109, v108
	v_max_f32_e32 v109, v83, v83
	v_max_f32_e32 v110, v82, v82
	v_max_f32_e32 v109, v110, v109
	v_max3_f32 v109, v80, v81, v109
	v_max3_f32 v27, v27, v108, v109
	v_mov_b32_e32 v108, v27
	s_nop 1
	v_permlane16_swap_b32_e32 v108, v27
	s_waitcnt vmcnt(13)
	v_mfma_f32_16x16x32_bf16 v[76:79], v[76:79], v[6:9], 0
	s_waitcnt lgkmcnt(0)
	v_max_f32_e32 v108, v108, v108
	v_max_f32_e32 v27, v27, v108
	v_mov_b32_e32 v108, v27
	s_nop 1
	v_permlane32_swap_b32_e32 v108, v27
	v_mfma_f32_16x16x32_bf16 v[72:75], v[72:75], v[2:5], v[84:87]
	s_waitcnt lgkmcnt(0)
	v_max3_f32 v141, v125, v27, v108
	v_sub_f32_e32 v27, v125, v141
	v_mul_f32_e32 v108, 0x3fb8aa3b, v27
	v_sub_f32_e32 v27, v88, v141
	v_sub_f32_e32 v88, v89, v141
	v_sub_f32_e32 v80, v80, v141
	v_mul_f32_e32 v88, 0x3fb8aa3b, v88
	v_mul_f32_e32 v80, 0x3fb8aa3b, v80
	v_exp_f32_e32 v125, v88
	v_sub_f32_e32 v88, v90, v141
	v_exp_f32_e32 v149, v80
	v_sub_f32_e32 v80, v81, v141
	v_mul_f32_e32 v88, 0x3fb8aa3b, v88
	v_mul_f32_e32 v80, 0x3fb8aa3b, v80
	v_mul_f32_e32 v27, 0x3fb8aa3b, v27
	v_exp_f32_e32 v127, v88
	v_sub_f32_e32 v88, v91, v141
	v_exp_f32_e32 v153, v80
	v_sub_f32_e32 v80, v82, v141
	v_exp_f32_e32 v27, v27
	v_mul_f32_e32 v88, 0x3fb8aa3b, v88
	v_mul_f32_e32 v80, 0x3fb8aa3b, v80
	v_exp_f32_e32 v147, v88
	v_exp_f32_e32 v155, v80
	v_sub_f32_e32 v80, v83, v141
	v_mul_f32_e32 v80, 0x3fb8aa3b, v80
	v_exp_f32_e32 v157, v80
	v_exp_f32_e32 v156, v108
	v_add_u32_e32 v80, 0x8000, v125
	v_add_u32_e32 v81, 0x8000, v27
	v_pk_add_f32 v[26:27], v[26:27], v[0:1]
	v_perm_b32 v80, v80, v81, s87
	v_pk_add_f32 v[26:27], v[124:125], v[26:27]
	v_cvt_pk_bf16_f32 v81, v127, v147
	v_pk_add_f32 v[26:27], v[126:127], v[26:27]
	v_cvt_pk_bf16_f32 v82, v149, v153
	v_pk_add_f32 v[26:27], v[146:147], v[26:27]
	v_cvt_pk_bf16_f32 v83, v155, v157
	v_pk_mul_f32 v[90:91], v[122:123], v[156:157] op_sel_hi:[1,0]
	v_pk_mul_f32 v[88:89], v[120:121], v[156:157] op_sel_hi:[1,0]
	v_pk_add_f32 v[26:27], v[148:149], v[26:27]
	s_waitcnt vmcnt(12)
	v_mfma_f32_16x16x32_bf16 v[64:67], v[64:67], v[2:5], v[76:79]
	v_add_f32_e64 v26, v152, v26
	v_add_f32_e64 v27, v153, v27
	v_max_f32_e32 v0, v73, v73
	v_pk_add_f32 v[26:27], v[154:155], v[26:27]
	v_mfma_f32_16x16x32_bf16 v[112:115], v[68:71], v[80:83], v[88:91]
	v_mul_f32_e64 v70, v118, v156
	v_mul_f32_e64 v71, v119, v156
	v_pk_mul_f32 v[68:69], v[116:117], v[156:157] op_sel_hi:[1,0]
	v_max_f32_e32 v76, v74, v74
	v_max_f32_e32 v77, v66, v66
	v_mfma_f32_16x16x32_bf16 v[120:123], v[36:39], v[80:83], v[68:71]
	v_mul_f32_e64 v38, v106, v156
	v_mul_f32_e64 v39, v107, v156
	v_pk_mul_f32 v[36:37], v[104:105], v[156:157] op_sel_hi:[1,0]
	s_waitcnt vmcnt(7)
	v_mfma_f32_16x16x32_bf16 v[100:103], v[100:103], v[6:9], 0
	v_mfma_f32_16x16x32_bf16 v[108:111], v[32:35], v[80:83], v[36:39]
	v_mul_f32_e64 v34, v58, v156
	v_mul_f32_e64 v35, v59, v156
	v_pk_mul_f32 v[32:33], v[56:57], v[156:157] op_sel_hi:[1,0]
	v_add_f32_e32 v38, v27, v157
	v_fmac_f32_e32 v38, v26, v156
	v_add_co_u32_e32 v26, vcc, s0, v130
	v_max_f32_e32 v39, v72, v72
	s_nop 0
	v_addc_co_u32_e32 v27, vcc, 0, v131, vcc
	v_mfma_f32_16x16x32_bf16 v[116:119], v[28:31], v[80:83], v[32:35]
	global_load_dwordx4 v[104:107], v[26:27], off
	global_load_dwordx4 v[80:83], v[26:27], off offset:16
	global_load_dwordx4 v[88:91], v[26:27], off offset:3072
	global_load_dwordx4 v[68:71], v[26:27], off offset:3088
	v_max_f32_e32 v0, v39, v0
	v_max_f32_e32 v39, v75, v75
	v_max_f32_e32 v39, v76, v39
	v_max_f32_e32 v76, v67, v67
	v_max_f32_e32 v76, v77, v76
	v_max3_f32 v76, v64, v65, v76
	v_max3_f32 v0, v0, v39, v76
	v_mov_b32_e32 v39, v0
	s_nop 1
	v_permlane16_swap_b32_e32 v39, v0
	s_movk_i32 s0, 0x6000
	v_add_co_u32_e32 v26, vcc, s0, v150
	s_waitcnt vmcnt(9)
	v_mfma_f32_16x16x32_bf16 v[96:99], v[96:99], v[6:9], 0
	s_waitcnt lgkmcnt(0)
	v_max_f32_e32 v39, v39, v39
	v_max_f32_e32 v0, v0, v39
	v_mov_b32_e32 v39, v0
	s_nop 1
	v_permlane32_swap_b32_e32 v39, v0
	v_mfma_f32_16x16x32_bf16 v[92:95], v[92:95], v[2:5], v[100:103]
	v_addc_co_u32_e32 v27, vcc, 0, v151, vcc
	s_mov_b64 s[0:1], 0x2a000
	s_waitcnt lgkmcnt(0)
	v_max3_f32 v39, v141, v0, v39
	v_sub_f32_e32 v72, v72, v39
	v_mul_f32_e32 v72, 0x3fb8aa3b, v72
	v_exp_f32_e32 v76, v72
	v_sub_f32_e32 v72, v73, v39
	v_sub_f32_e32 v64, v64, v39
	v_mul_f32_e32 v72, 0x3fb8aa3b, v72
	v_mul_f32_e32 v64, 0x3fb8aa3b, v64
	v_exp_f32_e32 v77, v72
	v_sub_f32_e32 v72, v74, v39
	v_exp_f32_e32 v148, v64
	v_sub_f32_e32 v64, v65, v39
	v_sub_f32_e32 v0, v141, v39
	v_mul_f32_e32 v72, 0x3fb8aa3b, v72
	v_mul_f32_e32 v64, 0x3fb8aa3b, v64
	v_mul_f32_e32 v0, 0x3fb8aa3b, v0
	v_exp_f32_e32 v130, v72
	v_sub_f32_e32 v72, v75, v39
	v_exp_f32_e32 v150, v64
	v_sub_f32_e32 v64, v66, v39
	v_mul_f32_e32 v72, 0x3fb8aa3b, v72
	v_mul_f32_e32 v64, 0x3fb8aa3b, v64
	v_exp_f32_e32 v0, v0
	v_exp_f32_e32 v146, v72
	v_exp_f32_e32 v152, v64
	v_sub_f32_e32 v64, v67, v39
	v_mul_f32_e32 v64, 0x3fb8aa3b, v64
	v_exp_f32_e32 v154, v64
	v_mul_f32_e32 v156, v38, v0
	v_cvt_pk_bf16_f32 v64, v76, v77
	v_cvt_pk_bf16_f32 v65, v130, v146
	s_waitcnt vmcnt(8)
	v_mfma_f32_16x16x32_bf16 v[60:63], v[60:63], v[2:5], v[96:99]
	v_cvt_pk_bf16_f32 v66, v148, v150
	v_cvt_pk_bf16_f32 v67, v152, v154
	v_max_f32_e32 v38, v93, v93
	v_max_f32_e32 v96, v92, v92
	v_max_f32_e32 v38, v96, v38
	v_max_f32_e32 v96, v95, v95
	v_max_f32_e32 v97, v94, v94
	v_max_f32_e32 v96, v97, v96
	v_max_f32_e32 v97, v63, v63
	v_max_f32_e32 v98, v62, v62
	v_max_f32_e32 v97, v98, v97
	v_max3_f32 v97, v60, v61, v97
	v_max3_f32 v38, v38, v96, v97
	v_mov_b32_e32 v96, v38
	s_nop 1
	v_permlane16_swap_b32_e32 v96, v38
	v_pk_mul_f32 v[74:75], v[114:115], v[0:1] op_sel_hi:[1,0]
	v_pk_mul_f32 v[72:73], v[112:113], v[0:1] op_sel_hi:[1,0]
	global_load_dwordx4 v[56:59], v[26:27], off
	global_load_dwordx4 v[34:37], v[26:27], off offset:256
	global_load_dwordx4 v[30:33], v[26:27], off offset:512
	s_nop 0
	global_load_dwordx4 v[26:29], v[26:27], off offset:768
	v_mfma_f32_16x16x32_bf16 v[124:127], v[22:25], v[64:67], v[72:75]
	v_mul_f32_e64 v24, v122, v0
	v_mul_f32_e64 v25, v123, v0
	v_pk_mul_f32 v[22:23], v[120:121], v[0:1] op_sel_hi:[1,0]
	s_waitcnt lgkmcnt(0)
	v_max_f32_e32 v96, v96, v96
	v_max_f32_e32 v38, v38, v96
	v_mfma_f32_16x16x32_bf16 v[120:123], v[18:21], v[64:67], v[22:25]
	v_mul_f32_e64 v20, v110, v0
	v_mul_f32_e64 v21, v111, v0
	v_pk_mul_f32 v[18:19], v[108:109], v[0:1] op_sel_hi:[1,0]
	v_mov_b32_e32 v96, v38
	s_nop 1
	v_permlane32_swap_b32_e32 v96, v38
	s_waitcnt vmcnt(5)
	v_mfma_f32_16x16x32_bf16 v[88:91], v[88:91], v[6:9], 0
	v_mov_b32_e32 v141, v1
	s_waitcnt lgkmcnt(0)
	v_max3_f32 v97, v39, v38, v96
	v_mfma_f32_16x16x32_bf16 v[108:111], v[14:17], v[64:67], v[18:21]
	v_mul_f32_e64 v16, v118, v0
	v_mul_f32_e64 v17, v119, v0
	v_pk_mul_f32 v[14:15], v[116:117], v[0:1] op_sel_hi:[1,0]
	v_add_f32_e32 v0, 0, v76
	v_add_f32_e32 v0, v77, v0
	v_mfma_f32_16x16x32_bf16 v[112:115], v[10:13], v[64:67], v[14:17]
	v_lshl_add_u64 v[10:11], v[144:145], 0, s[0:1]
	s_mov_b32 s0, 0x2a000
	v_add_co_u32_e32 v12, vcc, s0, v144
	v_sub_f32_e32 v38, v39, v97
	s_nop 0
	v_addc_co_u32_e32 v13, vcc, 0, v145, vcc
	global_load_dwordx4 v[84:87], v[12:13], off
	global_load_dwordx4 v[72:75], v[10:11], off offset:16
	global_load_dwordx4 v[76:79], v[10:11], off offset:3072
	global_load_dwordx4 v[64:67], v[10:11], off offset:3088
	v_sub_f32_e32 v39, v92, v97
	v_mul_f32_e32 v39, 0x3fb8aa3b, v39
	v_exp_f32_e32 v131, v39
	v_sub_f32_e32 v39, v93, v97
	v_mul_f32_e32 v39, 0x3fb8aa3b, v39
	v_exp_f32_e32 v147, v39
	v_sub_f32_e32 v39, v94, v97
	v_mul_f32_e32 v39, 0x3fb8aa3b, v39
	v_exp_f32_e32 v149, v39
	v_sub_f32_e32 v39, v95, v97
	v_mul_f32_e32 v39, 0x3fb8aa3b, v39
	v_exp_f32_e32 v151, v39
	v_sub_f32_e32 v39, v60, v97
	v_mul_f32_e32 v39, 0x3fb8aa3b, v39
	v_exp_f32_e32 v153, v39
	v_sub_f32_e32 v39, v61, v97
	v_mul_f32_e32 v39, 0x3fb8aa3b, v39
	v_exp_f32_e32 v155, v39
	v_sub_f32_e32 v39, v62, v97
	v_mul_f32_e32 v39, 0x3fb8aa3b, v39
	v_exp_f32_e32 v157, v39
	v_sub_f32_e32 v39, v63, v97
	v_mul_f32_e32 v39, 0x3fb8aa3b, v39
	v_mul_f32_e32 v38, 0x3fb8aa3b, v38
	v_exp_f32_e32 v98, v39
	v_exp_f32_e32 v96, v38
	v_cvt_pk_bf16_f32 v60, v131, v147
	v_cvt_pk_bf16_f32 v61, v149, v151
	v_cvt_pk_bf16_f32 v62, v153, v155
	v_cvt_pk_bf16_f32 v63, v157, v98
	v_pk_mul_f32 v[94:95], v[126:127], v[96:97] op_sel_hi:[1,0]
	v_pk_mul_f32 v[92:93], v[124:125], v[96:97] op_sel_hi:[1,0]
	s_waitcnt vmcnt(8)
	v_mfma_f32_16x16x32_bf16 v[88:91], v[68:71], v[2:5], v[88:91]
	s_mov_b64 s[0:1], 0x7000
	v_lshl_add_u64 v[10:11], v[142:143], 0, s[0:1]
	s_movk_i32 s0, 0x7000
	v_mfma_f32_16x16x32_bf16 v[52:55], v[52:55], v[60:63], v[92:95]
	v_add_co_u32_e32 v12, vcc, s0, v142
	s_nop 2
	v_max_f32_e32 v69, v90, v90
	v_pk_mul_f32 v[94:95], v[122:123], v[96:97] op_sel_hi:[1,0]
	v_pk_mul_f32 v[92:93], v[120:121], v[96:97] op_sel_hi:[1,0]
	v_addc_co_u32_e32 v13, vcc, 0, v143, vcc
	s_nop 0
	v_mfma_f32_16x16x32_bf16 v[48:51], v[48:51], v[60:63], v[92:95]
	global_load_dwordx4 v[22:25], v[12:13], off
	global_load_dwordx4 v[18:21], v[10:11], off offset:256
	global_load_dwordx4 v[14:17], v[10:11], off offset:512
	s_nop 0
	global_load_dwordx4 v[10:13], v[10:11], off offset:768
	v_pk_mul_f32 v[94:95], v[110:111], v[96:97] op_sel_hi:[1,0]
	v_pk_mul_f32 v[92:93], v[108:109], v[96:97] op_sel_hi:[1,0]
	s_mov_b64 s[0:1], 0xd800200
	s_nop 0
	v_mfma_f32_16x16x32_bf16 v[44:47], v[44:47], v[60:63], v[92:95]
	s_nop 2
	v_mul_f32_e64 v94, v114, v96
	v_mul_f32_e64 v95, v115, v96
	v_pk_mul_f32 v[92:93], v[112:113], v[96:97] op_sel_hi:[1,0]
	s_nop 1
	v_mfma_f32_16x16x32_bf16 v[38:41], v[40:43], v[60:63], v[92:95]
	v_add_f32_e64 v42, v130, v0
	v_add_f32_e64 v43, v131, v1
	v_pk_add_f32 v[42:43], v[146:147], v[42:43]
	v_mfma_f32_16x16x32_bf16 v[60:63], v[104:107], v[6:9], 0
	v_add_f32_e64 v42, v148, v42
	v_add_f32_e64 v43, v149, v43
	v_pk_add_f32 v[42:43], v[150:151], v[42:43]
	v_mfma_f32_16x16x32_bf16 v[60:63], v[80:83], v[2:5], v[60:63]
	v_add_f32_e64 v42, v152, v42
	v_add_f32_e64 v43, v153, v43
	v_pk_add_f32 v[42:43], v[154:155], v[42:43]
	s_nop 0
	v_pk_add_f32 v[42:43], v[156:157], v[42:43]
	s_nop 2
	v_max_f32_e32 v0, v61, v61
	v_add_f32_e32 v43, v43, v98
	v_fmac_f32_e32 v43, v42, v96
	v_max_f32_e32 v42, v60, v60
	v_max_f32_e32 v0, v42, v0
	v_max_f32_e32 v42, v63, v63
	v_max_f32_e32 v68, v62, v62
	v_max_f32_e32 v42, v68, v42
	v_max_f32_e32 v68, v91, v91
	v_max_f32_e32 v68, v69, v68
	v_max3_f32 v68, v88, v89, v68
	v_max3_f32 v0, v0, v42, v68
	v_mov_b32_e32 v42, v0
	s_nop 1
	v_permlane16_swap_b32_e32 v42, v0
	s_waitcnt lgkmcnt(0)
	v_max_f32_e32 v42, v42, v42
	v_max_f32_e32 v0, v0, v42
	v_mov_b32_e32 v42, v0
	s_nop 1
	v_permlane32_swap_b32_e32 v42, v0
	s_waitcnt lgkmcnt(0)
	v_max3_f32 v69, v97, v0, v42
	v_sub_f32_e32 v42, v60, v69
	v_mul_f32_e32 v42, 0x3fb8aa3b, v42
	v_exp_f32_e32 v71, v42
	v_sub_f32_e32 v42, v61, v69
	v_mul_f32_e32 v42, 0x3fb8aa3b, v42
	v_exp_f32_e32 v61, v42
	v_sub_f32_e32 v42, v62, v69
	v_mul_f32_e32 v42, 0x3fb8aa3b, v42
	v_exp_f32_e32 v82, v42
	v_sub_f32_e32 v42, v63, v69
	v_mul_f32_e32 v42, 0x3fb8aa3b, v42
	v_exp_f32_e32 v80, v42
	v_sub_f32_e32 v42, v88, v69
	v_mul_f32_e32 v42, 0x3fb8aa3b, v42
	v_exp_f32_e32 v70, v42
	v_sub_f32_e32 v42, v89, v69
	v_sub_f32_e32 v0, v97, v69
	v_mul_f32_e32 v42, 0x3fb8aa3b, v42
	v_mul_f32_e32 v0, 0x3fb8aa3b, v0
	v_exp_f32_e32 v68, v42
	v_sub_f32_e32 v42, v90, v69
	v_mul_f32_e32 v42, 0x3fb8aa3b, v42
	v_exp_f32_e32 v0, v0
	v_exp_f32_e32 v62, v42
	v_sub_f32_e32 v42, v91, v69
	v_mul_f32_e32 v42, 0x3fb8aa3b, v42
	v_exp_f32_e32 v60, v42
	v_mul_f32_e32 v42, v43, v0
	v_cvt_pk_bf16_f32 v88, v71, v61
	v_cvt_pk_bf16_f32 v89, v82, v80
	v_cvt_pk_bf16_f32 v90, v70, v68
	v_cvt_pk_bf16_f32 v91, v62, v60
	v_pk_mul_f32 v[40:41], v[40:41], v[0:1] op_sel_hi:[1,0]
	v_pk_mul_f32 v[38:39], v[38:39], v[0:1] op_sel_hi:[1,0]
	v_pk_mul_f32 v[54:55], v[54:55], v[0:1] op_sel_hi:[1,0]
	v_pk_mul_f32 v[52:53], v[52:53], v[0:1] op_sel_hi:[1,0]
	s_waitcnt vmcnt(8)
	v_mfma_f32_16x16x32_bf16 v[26:29], v[26:29], v[88:91], v[38:41]
	v_mul_f32_e64 v50, v50, v0
	v_mul_f32_e64 v51, v51, v0
	v_pk_mul_f32 v[48:49], v[48:49], v[0:1] op_sel_hi:[1,0]
	v_pk_mul_f32 v[46:47], v[46:47], v[0:1] op_sel_hi:[1,0]
	s_waitcnt vmcnt(7)
	v_mfma_f32_16x16x32_bf16 v[38:41], v[84:87], v[6:9], 0
	v_mul_f32_e64 v44, v44, v0
	v_mul_f32_e64 v45, v45, v0
	v_add_f32_e32 v0, 0, v71
	v_add_f32_e32 v0, v61, v0
	s_waitcnt vmcnt(5)
	v_mfma_f32_16x16x32_bf16 v[6:9], v[76:79], v[6:9], 0
	v_mfma_f32_16x16x32_bf16 v[38:41], v[72:75], v[2:5], v[38:41]
	s_waitcnt vmcnt(4)
	v_mfma_f32_16x16x32_bf16 v[2:5], v[64:67], v[2:5], v[6:9]
	v_mfma_f32_16x16x32_bf16 v[52:55], v[56:59], v[88:91], v[52:55]
	s_nop 4
	v_max_f32_e32 v6, v39, v39
	v_max_f32_e32 v7, v38, v38
	v_max_f32_e32 v6, v7, v6
	v_max_f32_e32 v7, v41, v41
	v_max_f32_e32 v8, v40, v40
	v_max_f32_e32 v7, v8, v7
	v_max_f32_e32 v8, v5, v5
	v_max_f32_e32 v9, v4, v4
	v_max_f32_e32 v8, v9, v8
	v_max3_f32 v8, v2, v3, v8
	v_max3_f32 v6, v6, v7, v8
	v_mov_b32_e32 v7, v6
	s_nop 1
	v_permlane16_swap_b32_e32 v7, v6
	v_mfma_f32_16x16x32_bf16 v[34:37], v[34:37], v[88:91], v[48:51]
	s_waitcnt lgkmcnt(0)
	v_max_f32_e32 v7, v7, v7
	v_max_f32_e32 v6, v6, v7
	v_mov_b32_e32 v7, v6
	s_nop 1
	v_permlane32_swap_b32_e32 v7, v6
	v_mfma_f32_16x16x32_bf16 v[30:33], v[30:33], v[88:91], v[44:47]
	s_waitcnt lgkmcnt(0)
	v_max3_f32 v6, v69, v6, v7
	v_sub_f32_e32 v8, v38, v6
	v_mul_f32_e32 v8, 0x3fb8aa3b, v8
	v_exp_f32_e32 v83, v8
	v_sub_f32_e32 v8, v39, v6
	v_sub_f32_e32 v2, v2, v6
	v_mul_f32_e32 v8, 0x3fb8aa3b, v8
	v_mul_f32_e32 v2, 0x3fb8aa3b, v2
	v_exp_f32_e32 v81, v8
	v_sub_f32_e32 v8, v40, v6
	v_exp_f32_e32 v63, v2
	v_sub_f32_e32 v2, v3, v6
	v_mul_f32_e32 v8, 0x3fb8aa3b, v8
	v_mul_f32_e32 v2, 0x3fb8aa3b, v2
	v_exp_f32_e32 v71, v8
	v_sub_f32_e32 v8, v41, v6
	v_exp_f32_e32 v61, v2
	v_sub_f32_e32 v2, v4, v6
	v_mul_f32_e32 v8, 0x3fb8aa3b, v8
	v_mul_f32_e32 v2, 0x3fb8aa3b, v2
	v_sub_f32_e32 v7, v69, v6
	v_exp_f32_e32 v69, v8
	v_exp_f32_e32 v43, v2
	v_sub_f32_e32 v2, v5, v6
	v_mul_f32_e32 v2, 0x3fb8aa3b, v2
	v_mul_f32_e32 v7, 0x3fb8aa3b, v7
	v_exp_f32_e32 v39, v2
	v_exp_f32_e32 v38, v7
	v_cvt_pk_bf16_f32 v2, v83, v81
	v_cvt_pk_bf16_f32 v3, v71, v69
	v_cvt_pk_bf16_f32 v4, v63, v61
	v_cvt_pk_bf16_f32 v5, v43, v39
	v_pk_mul_f32 v[8:9], v[54:55], v[38:39] op_sel_hi:[1,0]
	v_pk_mul_f32 v[6:7], v[52:53], v[38:39] op_sel_hi:[1,0]
	s_waitcnt vmcnt(3)
	s_nop 0
	v_mfma_f32_16x16x32_bf16 v[6:9], v[22:25], v[2:5], v[6:9]
	v_mul_f32_e64 v24, v36, v38
	v_mul_f32_e64 v25, v37, v38
	v_pk_mul_f32 v[22:23], v[34:35], v[38:39] op_sel_hi:[1,0]
	s_waitcnt vmcnt(2)
	s_nop 0
	v_mfma_f32_16x16x32_bf16 v[18:21], v[18:21], v[2:5], v[22:25]
	s_nop 2
	v_mul_f32_e64 v24, v32, v38
	v_mul_f32_e64 v25, v33, v38
	v_pk_mul_f32 v[22:23], v[30:31], v[38:39] op_sel_hi:[1,0]
	s_waitcnt vmcnt(1)
	s_nop 0
	v_mfma_f32_16x16x32_bf16 v[14:17], v[14:17], v[2:5], v[22:25]
	s_nop 2
	v_mul_f32_e64 v24, v28, v38
	v_mul_f32_e64 v25, v29, v38
	v_pk_mul_f32 v[22:23], v[26:27], v[38:39] op_sel_hi:[1,0]
	s_waitcnt vmcnt(0)
	s_nop 0
	v_mfma_f32_16x16x32_bf16 v[2:5], v[10:13], v[2:5], v[22:25]
	v_add_f32_e64 v10, v82, v0
	v_add_f32_e64 v11, v83, v1
	v_pk_add_f32 v[10:11], v[80:81], v[10:11]
	s_nop 0
	v_pk_add_f32 v[10:11], v[70:71], v[10:11]
	s_nop 0
	v_pk_add_f32 v[10:11], v[68:69], v[10:11]
	s_nop 0
	v_pk_add_f32 v[10:11], v[62:63], v[10:11]
	s_nop 0
	v_pk_add_f32 v[10:11], v[60:61], v[10:11]
	s_nop 0
	v_pk_add_f32 v[10:11], v[42:43], v[10:11]
	s_nop 0
	v_add_f32_e32 v0, v11, v39
	v_fmac_f32_e32 v0, v10, v38
	v_mov_b32_e32 v22, v0
	s_nop 1
	v_permlane16_swap_b32_e32 v22, v0
	v_lshl_add_u64 v[10:11], v[128:129], 0, v[140:141]
	v_lshl_add_u64 v[12:13], v[10:11], 0, s[0:1]
	s_waitcnt lgkmcnt(0)
	v_add_f32_e32 v0, v0, v22
	v_mov_b32_e32 v22, v0
	s_nop 1
	v_permlane32_swap_b32_e32 v22, v0
	s_waitcnt lgkmcnt(0)
	v_add_f32_e32 v0, v0, v22
	v_div_scale_f32 v22, s[0:1], v0, v0, 1.0
	v_rcp_f32_e32 v23, v22
	s_mov_b32 s0, 0xd800000
	v_fma_f32 v24, -v22, v23, 1.0
	v_fmac_f32_e32 v23, v24, v23
	v_div_scale_f32 v24, vcc, 1.0, v0, 1.0
	v_mul_f32_e32 v25, v24, v23
	v_fma_f32 v26, -v22, v25, v24
	v_fmac_f32_e32 v25, v26, v23
	v_fma_f32 v22, -v22, v25, v24
	v_div_fmas_f32 v22, v22, v23, v25
	v_div_fixup_f32 v0, v22, v0, 1.0
	v_mov_b32_e32 v22, v6
	v_mov_b32_e32 v23, v8
	v_pk_mul_f32 v[22:23], v[22:23], v[0:1] op_sel_hi:[1,0]
	v_mov_b32_e32 v8, v7
	v_pk_mul_f32 v[6:7], v[8:9], v[0:1] op_sel_hi:[1,0]
	v_and_b32_sdwa v9, v22, v236 dst_sel:DWORD dst_unused:UNUSED_PAD src0_sel:WORD_1 src1_sel:DWORD
	v_and_b32_sdwa v8, v23, v236 dst_sel:DWORD dst_unused:UNUSED_PAD src0_sel:WORD_1 src1_sel:DWORD
	v_add3_u32 v9, v22, v9, s60
	v_and_b32_sdwa v22, v7, v236 dst_sel:DWORD dst_unused:UNUSED_PAD src0_sel:WORD_1 src1_sel:DWORD
	v_add3_u32 v8, v23, v8, s60
	v_and_b32_sdwa v23, v6, v236 dst_sel:DWORD dst_unused:UNUSED_PAD src0_sel:WORD_1 src1_sel:DWORD
	v_add3_u32 v7, v7, v22, s60
	v_add3_u32 v6, v6, v23, s60
	v_and_b32_e32 v7, 0xffff0000, v7
	v_and_b32_e32 v6, 0xffff0000, v6
	v_or_b32_sdwa v7, v7, v8 dst_sel:DWORD dst_unused:UNUSED_PAD src0_sel:DWORD src1_sel:WORD_1
	v_add_co_u32_e32 v8, vcc, s0, v10
	v_or_b32_sdwa v6, v6, v9 dst_sel:DWORD dst_unused:UNUSED_PAD src0_sel:DWORD src1_sel:WORD_1
	s_nop 0
	v_addc_co_u32_e32 v9, vcc, 0, v11, vcc
	global_store_dwordx2 v[8:9], v[6:7], off offset:512
	v_mov_b32_e32 v6, v18
	v_mov_b32_e32 v7, v20
	v_pk_mul_f32 v[6:7], v[6:7], v[0:1] op_sel_hi:[1,0]
	v_mov_b32_e32 v20, v19
	v_pk_mul_f32 v[8:9], v[20:21], v[0:1] op_sel_hi:[1,0]
	v_and_b32_sdwa v10, v7, v236 dst_sel:DWORD dst_unused:UNUSED_PAD src0_sel:WORD_1 src1_sel:DWORD
	v_and_b32_sdwa v11, v6, v236 dst_sel:DWORD dst_unused:UNUSED_PAD src0_sel:WORD_1 src1_sel:DWORD
	v_add3_u32 v6, v6, v11, s60
	v_add3_u32 v7, v7, v10, s60
	v_and_b32_sdwa v10, v9, v236 dst_sel:DWORD dst_unused:UNUSED_PAD src0_sel:WORD_1 src1_sel:DWORD
	v_and_b32_sdwa v11, v8, v236 dst_sel:DWORD dst_unused:UNUSED_PAD src0_sel:WORD_1 src1_sel:DWORD
	v_add3_u32 v9, v9, v10, s60
	v_add3_u32 v8, v8, v11, s60
	v_and_b32_e32 v9, 0xffff0000, v9
	v_and_b32_e32 v8, 0xffff0000, v8
	v_or_b32_sdwa v7, v9, v7 dst_sel:DWORD dst_unused:UNUSED_PAD src0_sel:DWORD src1_sel:WORD_1
	v_or_b32_sdwa v6, v8, v6 dst_sel:DWORD dst_unused:UNUSED_PAD src0_sel:DWORD src1_sel:WORD_1
	global_store_dwordx2 v[12:13], v[6:7], off offset:32
	v_mov_b32_e32 v6, v14
	v_mov_b32_e32 v7, v16
	v_pk_mul_f32 v[6:7], v[6:7], v[0:1] op_sel_hi:[1,0]
	v_mov_b32_e32 v16, v15
	v_pk_mul_f32 v[8:9], v[16:17], v[0:1] op_sel_hi:[1,0]
	v_and_b32_sdwa v10, v7, v236 dst_sel:DWORD dst_unused:UNUSED_PAD src0_sel:WORD_1 src1_sel:DWORD
	v_and_b32_sdwa v11, v6, v236 dst_sel:DWORD dst_unused:UNUSED_PAD src0_sel:WORD_1 src1_sel:DWORD
	v_add3_u32 v6, v6, v11, s60
	v_add3_u32 v7, v7, v10, s60
	v_and_b32_sdwa v10, v9, v236 dst_sel:DWORD dst_unused:UNUSED_PAD src0_sel:WORD_1 src1_sel:DWORD
	v_and_b32_sdwa v11, v8, v236 dst_sel:DWORD dst_unused:UNUSED_PAD src0_sel:WORD_1 src1_sel:DWORD
	v_add3_u32 v9, v9, v10, s60
	v_add3_u32 v8, v8, v11, s60
	v_and_b32_e32 v9, 0xffff0000, v9
	v_and_b32_e32 v8, 0xffff0000, v8
	v_or_b32_sdwa v7, v9, v7 dst_sel:DWORD dst_unused:UNUSED_PAD src0_sel:DWORD src1_sel:WORD_1
	v_or_b32_sdwa v6, v8, v6 dst_sel:DWORD dst_unused:UNUSED_PAD src0_sel:DWORD src1_sel:WORD_1
	global_store_dwordx2 v[12:13], v[6:7], off offset:64
	v_mov_b32_e32 v6, v2
	v_mov_b32_e32 v7, v4
	v_pk_mul_f32 v[6:7], v[6:7], v[0:1] op_sel_hi:[1,0]
	v_mov_b32_e32 v4, v3
	v_pk_mul_f32 v[2:3], v[4:5], v[0:1] op_sel_hi:[1,0]
	v_and_b32_sdwa v4, v6, v236 dst_sel:DWORD dst_unused:UNUSED_PAD src0_sel:WORD_1 src1_sel:DWORD
	v_add3_u32 v4, v6, v4, s60
	v_and_b32_sdwa v5, v3, v236 dst_sel:DWORD dst_unused:UNUSED_PAD src0_sel:WORD_1 src1_sel:DWORD
	v_and_b32_sdwa v6, v2, v236 dst_sel:DWORD dst_unused:UNUSED_PAD src0_sel:WORD_1 src1_sel:DWORD
	v_and_b32_sdwa v0, v7, v236 dst_sel:DWORD dst_unused:UNUSED_PAD src0_sel:WORD_1 src1_sel:DWORD
	v_add3_u32 v3, v3, v5, s60
	v_add3_u32 v2, v2, v6, s60
	v_add3_u32 v0, v7, v0, s60
	v_and_b32_e32 v3, 0xffff0000, v3
	v_and_b32_e32 v2, 0xffff0000, v2
	v_or_b32_sdwa v3, v3, v0 dst_sel:DWORD dst_unused:UNUSED_PAD src0_sel:DWORD src1_sel:WORD_1
	v_or_b32_sdwa v2, v2, v4 dst_sel:DWORD dst_unused:UNUSED_PAD src0_sel:DWORD src1_sel:WORD_1
	global_store_dwordx2 v[12:13], v[2:3], off offset:96

.LBB0_1081:
	s_or_b64 exec, exec, s[34:35]
	v_cmp_lt_i32_e32 vcc, v231, v226
	v_max_f32_e32 v13, v66, v66
	v_max_f32_e32 v67, v77, v77
	v_cndmask_b32_e32 v12, v225, v231, vcc
	v_lshlrev_b32_e32 v137, 2, v12
	v_max_f32_e32 v12, v0, v0
	v_max_f32_e32 v12, v13, v12
	v_max_f32_e32 v13, v76, v76
	v_max_f32_e32 v13, v67, v13
	v_max_f32_e32 v67, v10, v10
	v_max_f32_e32 v92, v11, v11
	v_max_f32_e32 v67, v92, v67
	v_max3_f32 v67, v79, v78, v67
	v_max3_f32 v12, v12, v13, v67
	v_mov_b32_e32 v13, v12
	s_nop 1
	v_permlane16_swap_b32_e32 v13, v12
	v_cmp_lt_i32_e32 vcc, v232, v226
	s_mov_b32 s1, 0xf149f2ca
	v_mov_b32_e32 v149, v1
	v_cndmask_b32_e32 v67, v225, v232, vcc
	s_waitcnt lgkmcnt(0)
	v_max_f32_e32 v13, v13, v13
	v_lshlrev_b32_e32 v139, 2, v67
	v_max_f32_e32 v12, v12, v13
	v_mov_b32_e32 v13, v12
	s_nop 1
	v_permlane32_swap_b32_e32 v13, v12
	v_mov_b32_e32 v145, v1
	v_mfma_f32_16x16x32_bf16 v[34:37], v[34:37], v[6:9], 0
	v_mov_b32_e32 v143, v1
	v_mov_b32_e32 v147, v1
	s_waitcnt lgkmcnt(0)
	v_max3_f32 v121, v12, v13, s1
	v_sub_f32_e32 v0, v0, v121
	v_mul_f32_e32 v0, 0x3fb8aa3b, v0
	v_exp_f32_e32 v155, v0
	v_sub_f32_e32 v0, v77, v121
	v_mul_f32_e32 v0, 0x3fb8aa3b, v0
	v_exp_f32_e32 v157, v0
	v_sub_f32_e32 v0, v76, v121
	v_mul_f32_e32 v0, 0x3fb8aa3b, v0
	v_exp_f32_e32 v159, v0
	v_sub_f32_e32 v0, v79, v121
	v_mul_f32_e32 v0, 0x3fb8aa3b, v0
	v_exp_f32_e32 v160, v0
	v_sub_f32_e32 v0, v78, v121
	v_mul_f32_e32 v0, 0x3fb8aa3b, v0
	v_sub_f32_e32 v12, 0xf149f2ca, v121
	v_sub_f32_e32 v13, v66, v121
	v_exp_f32_e32 v161, v0
	v_sub_f32_e32 v0, v11, v121
	v_mul_f32_e32 v12, 0x3fb8aa3b, v12
	v_mul_f32_e32 v13, 0x3fb8aa3b, v13
	v_mul_f32_e32 v0, 0x3fb8aa3b, v0
	v_exp_f32_e32 v153, v13
	v_exp_f32_e32 v162, v0
	v_exp_f32_e32 v0, v12
	v_sub_f32_e32 v10, v10, v121
	v_mul_f32_e32 v10, 0x3fb8aa3b, v10
	v_exp_f32_e32 v163, v10
	v_mul_f32_e32 v10, 0, v0
	v_cvt_pk_bf16_f32 v76, v153, v155
	v_cvt_pk_bf16_f32 v77, v157, v159
	v_cvt_pk_bf16_f32 v78, v160, v161
	v_cvt_pk_bf16_f32 v79, v162, v163
	v_mov_b32_e32 v11, v10
	v_mov_b32_e32 v12, v10
	v_mov_b32_e32 v13, v10
	v_mfma_f32_16x16x32_bf16 v[122:125], v[100:103], v[6:9], 0
	s_nop 0
	v_mfma_f32_16x16x32_bf16 v[116:119], v[50:53], v[76:79], v[10:13]
	v_add_u32_e32 v50, 0xc0, v150
	v_lshlrev_b32_e32 v0, 7, v50
	v_mfma_f32_16x16x32_bf16 v[104:107], v[62:65], v[76:79], v[10:13]
	v_mfma_f32_16x16x32_bf16 v[108:111], v[72:75], v[76:79], v[10:13]
	v_mfma_f32_16x16x32_bf16 v[112:115], v[42:45], v[76:79], v[10:13]
	s_nop 2
	v_lshl_add_u64 v[12:13], s[30:31], 0, v[0:1]
	v_mul_lo_u32 v0, v50, s33
	v_lshl_add_u64 v[42:43], s[28:29], 0, v[0:1]
	v_lshl_add_u64 v[42:43], v[42:43], 0, v[148:149]
	v_lshl_add_u64 v[42:43], v[42:43], 0, v[144:145]
	global_load_dwordx4 v[92:95], v[42:43], off
	global_load_dwordx4 v[72:75], v[42:43], off offset:16
	global_load_dwordx4 v[76:79], v[42:43], off offset:3072
	global_load_dwordx4 v[64:67], v[42:43], off offset:3088
	v_lshl_add_u64 v[12:13], v[12:13], 0, v[142:143]
	v_lshl_add_u64 v[12:13], v[12:13], 0, v[146:147]
	global_load_dwordx4 v[50:53], v[12:13], off
	global_load_dwordx4 v[42:45], v[12:13], off offset:256
	v_mfma_f32_16x16x32_bf16 v[100:103], v[30:33], v[2:5], v[34:37]
	s_nop 2
	global_load_dwordx4 v[34:37], v[12:13], off offset:512
	global_load_dwordx4 v[30:33], v[12:13], off offset:768
	v_mov_b32_e32 v0, 0xff800000
	v_mov_b32_e32 v11, 0xff800000
	v_mfma_f32_16x16x32_bf16 v[96:99], v[96:99], v[2:5], v[122:125]
	s_and_saveexec_b64 s[34:35], s[12:13]
	s_cbranch_execz .LBB0_1083
	v_lshl_add_u32 v11, v156, 2, v151
	ds_read_b32 v11, v11 offset:1052
	s_waitcnt lgkmcnt(0)
	v_add_f32_e32 v11, v100, v11

.LBB0_1097:
	s_or_b64 exec, exec, s[34:35]
	v_max_f32_e32 v12, v0, v0
	v_max_f32_e32 v98, v11, v11
	v_max_f32_e32 v12, v98, v12
	v_max_f32_e32 v98, v13, v13
	v_max_f32_e32 v99, v62, v62
	v_max_f32_e32 v98, v99, v98
	v_max_f32_e32 v99, v96, v96
	v_max_f32_e32 v101, v97, v97
	v_max_f32_e32 v99, v101, v99
	v_max3_f32 v99, v100, v63, v99
	v_max3_f32 v12, v12, v98, v99
	v_mov_b32_e32 v98, v12
	s_nop 1
	v_permlane16_swap_b32_e32 v98, v12
	v_mov_b32_e32 v149, v1
	v_mov_b32_e32 v145, v1
	v_mov_b32_e32 v143, v1
	v_mov_b32_e32 v147, v1
	s_waitcnt lgkmcnt(0)
	v_max_f32_e32 v98, v98, v98
	v_max_f32_e32 v12, v12, v98
	v_mov_b32_e32 v98, v12
	s_nop 1
	v_permlane32_swap_b32_e32 v98, v12
	s_waitcnt vmcnt(14)
	v_mfma_f32_16x16x32_bf16 v[122:125], v[46:49], v[6:9], 0
	s_waitcnt lgkmcnt(0)
	v_max3_f32 v12, v121, v12, v98
	v_sub_f32_e32 v0, v0, v12
	v_mul_f32_e32 v0, 0x3fb8aa3b, v0
	v_exp_f32_e32 v164, v0
	v_sub_f32_e32 v0, v62, v12
	v_mul_f32_e32 v0, 0x3fb8aa3b, v0
	v_exp_f32_e32 v165, v0
	v_sub_f32_e32 v0, v13, v12
	v_mul_f32_e32 v0, 0x3fb8aa3b, v0
	v_exp_f32_e32 v166, v0
	v_sub_f32_e32 v0, v100, v12
	v_mul_f32_e32 v0, 0x3fb8aa3b, v0
	v_exp_f32_e32 v167, v0
	v_sub_f32_e32 v0, v63, v12
	v_sub_f32_e32 v11, v11, v12
	v_mul_f32_e32 v0, 0x3fb8aa3b, v0
	v_mul_f32_e32 v11, 0x3fb8aa3b, v11
	v_exp_f32_e32 v168, v0
	v_sub_f32_e32 v0, v97, v12
	v_exp_f32_e32 v11, v11
	v_mul_f32_e32 v0, 0x3fb8aa3b, v0
	v_exp_f32_e32 v169, v0
	v_sub_f32_e32 v0, v96, v12
	v_sub_f32_e32 v98, v121, v12
	v_mul_f32_e32 v0, 0x3fb8aa3b, v0
	v_mul_f32_e32 v98, 0x3fb8aa3b, v98
	v_exp_f32_e32 v170, v0
	v_exp_f32_e32 v152, v98
	v_cvt_pk_bf16_f32 v96, v11, v164
	v_cvt_pk_bf16_f32 v97, v165, v166
	v_cvt_pk_bf16_f32 v98, v167, v168
	v_cvt_pk_bf16_f32 v99, v169, v170
	v_pk_mul_f32 v[102:103], v[118:119], v[152:153] op_sel_hi:[1,0]
	v_pk_mul_f32 v[100:101], v[116:117], v[152:153] op_sel_hi:[1,0]
	v_add_u32_e32 v13, 0x100, v150
	v_lshlrev_b32_e32 v0, 7, v13
	v_mfma_f32_16x16x32_bf16 v[100:103], v[88:91], v[96:99], v[100:103]
	v_mul_f32_e64 v90, v106, v152
	v_mul_f32_e64 v91, v107, v152
	v_pk_mul_f32 v[88:89], v[104:105], v[152:153] op_sel_hi:[1,0]
	v_lshl_add_u64 v[62:63], s[30:31], 0, v[0:1]
	v_mul_lo_u32 v0, v13, s33
	v_mfma_f32_16x16x32_bf16 v[104:107], v[84:87], v[96:99], v[88:91]
	v_mul_f32_e64 v86, v110, v152
	v_mul_f32_e64 v87, v111, v152
	v_pk_mul_f32 v[84:85], v[108:109], v[152:153] op_sel_hi:[1,0]
	v_mov_b32_e32 v13, 0xff800000
	s_waitcnt vmcnt(13)
	v_mfma_f32_16x16x32_bf16 v[116:119], v[58:61], v[6:9], 0
	v_lshl_add_u64 v[58:59], v[62:63], 0, v[142:143]
	v_lshl_add_u64 v[58:59], v[58:59], 0, v[146:147]
	v_mfma_f32_16x16x32_bf16 v[108:111], v[80:83], v[96:99], v[84:87]
	v_mul_f32_e64 v82, v114, v152
	v_mul_f32_e64 v83, v115, v152
	v_pk_mul_f32 v[80:81], v[112:113], v[152:153] op_sel_hi:[1,0]
	v_mfma_f32_16x16x32_bf16 v[116:119], v[38:41], v[2:5], v[116:119]
	s_nop 0
	v_mfma_f32_16x16x32_bf16 v[112:115], v[68:71], v[96:99], v[80:83]
	v_lshl_add_u64 v[68:69], s[28:29], 0, v[0:1]
	v_lshl_add_u64 v[68:69], v[68:69], 0, v[148:149]
	v_lshl_add_u64 v[68:69], v[68:69], 0, v[144:145]
	global_load_dwordx4 v[96:99], v[68:69], off
	global_load_dwordx4 v[84:87], v[68:69], off offset:16
	global_load_dwordx4 v[88:91], v[68:69], off offset:3072
	global_load_dwordx4 v[80:83], v[68:69], off offset:3088
	s_nop 0
	global_load_dwordx4 v[68:71], v[58:59], off
	global_load_dwordx4 v[60:63], v[58:59], off offset:256
	global_load_dwordx4 v[46:49], v[58:59], off offset:512
	global_load_dwordx4 v[38:41], v[58:59], off offset:768
	s_waitcnt vmcnt(20)
	v_mfma_f32_16x16x32_bf16 v[54:57], v[54:57], v[2:5], v[122:125]
	v_mov_b32_e32 v0, 0xff800000
	s_and_saveexec_b64 s[34:35], s[12:13]
	s_cbranch_execz .LBB0_1099
	v_lshl_add_u32 v13, v156, 2, v151
	ds_read_b32 v13, v13 offset:1176
	s_waitcnt lgkmcnt(0)
	v_add_f32_e32 v13, v116, v13

.LBB0_1113:
	s_or_b64 exec, exec, s[34:35]
	v_max_f32_e32 v56, v0, v0
	v_max_f32_e32 v57, v13, v13
	v_max_f32_e32 v56, v57, v56
	v_max_f32_e32 v57, v58, v58
	v_max_f32_e32 v119, v59, v59
	v_max_f32_e32 v57, v119, v57
	v_max_f32_e32 v119, v55, v55
	v_max_f32_e32 v120, v118, v118
	v_max_f32_e32 v119, v120, v119
	v_max3_f32 v119, v117, v116, v119
	v_max3_f32 v56, v56, v57, v119
	v_mov_b32_e32 v57, v56
	s_nop 1
	v_permlane16_swap_b32_e32 v57, v56
	v_mov_b32_e32 v149, v1
	v_mov_b32_e32 v145, v1
	v_mov_b32_e32 v143, v1
	v_mov_b32_e32 v147, v1
	s_waitcnt lgkmcnt(0)
	v_max_f32_e32 v57, v57, v57
	v_max_f32_e32 v56, v56, v57
	v_mov_b32_e32 v57, v56
	s_nop 1
	v_permlane32_swap_b32_e32 v57, v56
	s_waitcnt vmcnt(13)
	v_mfma_f32_16x16x32_bf16 v[76:79], v[76:79], v[6:9], 0
	v_lshl_add_u32 v179, v156, 2, v151
	s_waitcnt lgkmcnt(0)
	v_max3_f32 v193, v12, v56, v57
	v_sub_f32_e32 v0, v0, v193
	v_mul_f32_e32 v0, 0x3fb8aa3b, v0
	v_exp_f32_e32 v172, v0
	v_sub_f32_e32 v0, v59, v193
	v_mul_f32_e32 v0, 0x3fb8aa3b, v0
	v_exp_f32_e32 v173, v0
	v_sub_f32_e32 v0, v58, v193
	v_mul_f32_e32 v0, 0x3fb8aa3b, v0
	v_exp_f32_e32 v174, v0
	v_sub_f32_e32 v0, v117, v193
	v_mul_f32_e32 v0, 0x3fb8aa3b, v0
	v_exp_f32_e32 v175, v0
	v_sub_f32_e32 v0, v116, v193
	v_sub_f32_e32 v13, v13, v193
	v_mul_f32_e32 v0, 0x3fb8aa3b, v0
	v_mul_f32_e32 v13, 0x3fb8aa3b, v13
	v_exp_f32_e32 v176, v0
	v_sub_f32_e32 v0, v118, v193
	v_exp_f32_e32 v171, v13
	v_mul_f32_e32 v0, 0x3fb8aa3b, v0
	v_exp_f32_e32 v177, v0
	v_sub_f32_e32 v0, v55, v193
	v_sub_f32_e32 v12, v12, v193
	v_mul_f32_e32 v0, 0x3fb8aa3b, v0
	v_mul_f32_e32 v12, 0x3fb8aa3b, v12
	v_exp_f32_e32 v178, v0
	v_exp_f32_e32 v154, v12
	v_cvt_pk_bf16_f32 v56, v171, v172
	v_cvt_pk_bf16_f32 v57, v173, v174
	v_cvt_pk_bf16_f32 v58, v175, v176
	v_cvt_pk_bf16_f32 v59, v177, v178
	v_pk_mul_f32 v[102:103], v[102:103], v[154:155] op_sel_hi:[1,0]
	v_pk_mul_f32 v[100:101], v[100:101], v[154:155] op_sel_hi:[1,0]
	v_add_u32_e32 v12, 0x140, v150
	v_lshlrev_b32_e32 v0, 7, v12
	v_mfma_f32_16x16x32_bf16 v[26:29], v[26:29], v[56:59], v[100:103]
	s_nop 2
	v_mul_f32_e64 v102, v106, v154
	v_mul_f32_e64 v103, v107, v154
	v_pk_mul_f32 v[100:101], v[104:105], v[154:155] op_sel_hi:[1,0]
	s_waitcnt vmcnt(12)
	v_mfma_f32_16x16x32_bf16 v[64:67], v[64:67], v[2:5], v[76:79]
	v_mfma_f32_16x16x32_bf16 v[100:103], v[22:25], v[56:59], v[100:103]
	v_mul_f32_e64 v24, v110, v154
	v_mul_f32_e64 v25, v111, v154
	v_pk_mul_f32 v[22:23], v[108:109], v[154:155] op_sel_hi:[1,0]
	s_nop 1
	v_mfma_f32_16x16x32_bf16 v[104:107], v[18:21], v[56:59], v[22:25]
	v_mul_f32_e64 v20, v114, v154
	v_mul_f32_e64 v21, v115, v154
	v_pk_mul_f32 v[18:19], v[112:113], v[154:155] op_sel_hi:[1,0]
	s_nop 1
	v_mfma_f32_16x16x32_bf16 v[108:111], v[14:17], v[56:59], v[18:21]
	v_lshl_add_u64 v[16:17], s[30:31], 0, v[0:1]
	v_mul_lo_u32 v0, v12, s33
	v_lshl_add_u64 v[12:13], s[28:29], 0, v[0:1]
	v_lshl_add_u64 v[12:13], v[12:13], 0, v[148:149]
	v_lshl_add_u64 v[12:13], v[12:13], 0, v[144:145]
	global_load_dwordx4 v[128:131], v[12:13], off
	global_load_dwordx4 v[120:123], v[12:13], off offset:16
	global_load_dwordx4 v[124:127], v[12:13], off offset:3072
	global_load_dwordx4 v[116:119], v[12:13], off offset:3088
	v_mfma_f32_16x16x32_bf16 v[12:15], v[92:95], v[6:9], 0
	v_lshl_add_u64 v[16:17], v[16:17], 0, v[142:143]
	v_lshl_add_u64 v[24:25], v[16:17], 0, v[146:147]
	global_load_dwordx4 v[56:59], v[24:25], off
	global_load_dwordx4 v[20:23], v[24:25], off offset:256
	v_mfma_f32_16x16x32_bf16 v[72:75], v[72:75], v[2:5], v[12:15]
	global_load_dwordx4 v[16:19], v[24:25], off offset:512
	s_nop 1
	global_load_dwordx4 v[12:15], v[24:25], off offset:768
	s_and_saveexec_b64 s[34:35], s[12:13]
	s_cbranch_execz .LBB0_1115
	ds_read_b32 v0, v179 offset:1300
	s_waitcnt lgkmcnt(0)
	v_add_f32_e32 v54, v72, v0

.LBB0_1129:
	s_or_b64 exec, exec, s[34:35]
	v_max_f32_e32 v66, v24, v24
	v_max_f32_e32 v67, v54, v54
	v_max_f32_e32 v66, v67, v66
	v_max_f32_e32 v67, v72, v72
	v_max_f32_e32 v74, v0, v0
	v_max_f32_e32 v67, v74, v67
	v_max_f32_e32 v74, v65, v65
	v_max_f32_e32 v75, v64, v64
	v_max_f32_e32 v74, v75, v74
	v_max3_f32 v74, v25, v73, v74
	v_max3_f32 v66, v66, v67, v74
	v_mov_b32_e32 v67, v66
	s_nop 1
	v_permlane16_swap_b32_e32 v67, v66
	v_mov_b32_e32 v149, v1
	v_mov_b32_e32 v145, v1
	v_mov_b32_e32 v143, v1
	v_mov_b32_e32 v147, v1
	s_waitcnt lgkmcnt(0)
	v_max_f32_e32 v67, v67, v67
	v_max_f32_e32 v66, v66, v67
	v_mov_b32_e32 v67, v66
	s_nop 1
	v_permlane32_swap_b32_e32 v67, v66
	s_waitcnt vmcnt(13)
	v_mfma_f32_16x16x32_bf16 v[88:91], v[88:91], v[6:9], 0
	s_waitcnt lgkmcnt(0)
	v_max3_f32 v158, v193, v66, v67
	v_sub_f32_e32 v0, v0, v158
	v_mul_f32_e32 v0, 0x3fb8aa3b, v0
	v_exp_f32_e32 v194, v0
	v_sub_f32_e32 v0, v72, v158
	v_mul_f32_e32 v0, 0x3fb8aa3b, v0
	v_exp_f32_e32 v195, v0
	v_sub_f32_e32 v0, v25, v158
	v_mul_f32_e32 v0, 0x3fb8aa3b, v0
	v_exp_f32_e32 v196, v0
	v_sub_f32_e32 v0, v73, v158
	v_sub_f32_e32 v54, v54, v158
	v_sub_f32_e32 v24, v24, v158
	v_mul_f32_e32 v0, 0x3fb8aa3b, v0
	v_mul_f32_e32 v54, 0x3fb8aa3b, v54
	v_mul_f32_e32 v24, 0x3fb8aa3b, v24
	v_exp_f32_e32 v197, v0
	v_sub_f32_e32 v0, v64, v158
	v_sub_f32_e32 v66, v193, v158
	v_exp_f32_e32 v191, v54
	v_exp_f32_e32 v193, v24
	v_mul_f32_e32 v0, 0x3fb8aa3b, v0
	v_exp_f32_e32 v198, v0
	v_sub_f32_e32 v0, v65, v158
	v_mul_f32_e32 v0, 0x3fb8aa3b, v0
	v_mul_f32_e32 v66, 0x3fb8aa3b, v66
	v_exp_f32_e32 v199, v0
	v_exp_f32_e32 v156, v66
	v_cvt_pk_bf16_f32 v64, v191, v193
	v_cvt_pk_bf16_f32 v65, v194, v195
	v_cvt_pk_bf16_f32 v66, v196, v197
	v_cvt_pk_bf16_f32 v67, v198, v199
	v_pk_mul_f32 v[28:29], v[28:29], v[156:157] op_sel_hi:[1,0]
	v_pk_mul_f32 v[26:27], v[26:27], v[156:157] op_sel_hi:[1,0]
	v_pk_mul_f32 v[24:25], v[100:101], v[156:157] op_sel_hi:[1,0]
	s_waitcnt vmcnt(12)
	v_mfma_f32_16x16x32_bf16 v[80:83], v[80:83], v[2:5], v[88:91]
	v_mfma_f32_16x16x32_bf16 v[50:53], v[50:53], v[64:67], v[26:29]
	s_nop 2
	v_mul_f32_e64 v26, v102, v156
	v_mul_f32_e64 v27, v103, v156
	s_nop 1
	v_mfma_f32_16x16x32_bf16 v[42:45], v[42:45], v[64:67], v[24:27]
	s_nop 2
	v_mul_f32_e64 v26, v106, v156
	v_mul_f32_e64 v27, v107, v156
	v_pk_mul_f32 v[24:25], v[104:105], v[156:157] op_sel_hi:[1,0]
	s_nop 1
	v_mfma_f32_16x16x32_bf16 v[92:95], v[34:37], v[64:67], v[24:27]
	s_nop 2
	v_mul_f32_e64 v26, v110, v156
	v_mul_f32_e64 v27, v111, v156
	v_pk_mul_f32 v[24:25], v[108:109], v[156:157] op_sel_hi:[1,0]
	s_nop 1
	v_mfma_f32_16x16x32_bf16 v[100:103], v[30:33], v[64:67], v[24:27]
	s_nop 2
	v_add_u32_e32 v24, 0x180, v150
	v_lshlrev_b32_e32 v0, 7, v24
	v_lshl_add_u64 v[36:37], s[30:31], 0, v[0:1]
	v_mul_lo_u32 v0, v24, s33
	v_lshl_add_u64 v[24:25], s[28:29], 0, v[0:1]
	v_lshl_add_u64 v[24:25], v[24:25], 0, v[148:149]
	v_lshl_add_u64 v[24:25], v[24:25], 0, v[144:145]
	global_load_dwordx4 v[112:115], v[24:25], off
	global_load_dwordx4 v[28:31], v[24:25], off offset:16
	global_load_dwordx4 v[32:35], v[24:25], off offset:3072
	global_load_dwordx4 v[104:107], v[24:25], off offset:3088
	v_mfma_f32_16x16x32_bf16 v[24:27], v[96:99], v[6:9], 0
	v_lshl_add_u64 v[36:37], v[36:37], 0, v[142:143]
	v_lshl_add_u64 v[36:37], v[36:37], 0, v[146:147]
	global_load_dwordx4 v[76:79], v[36:37], off
	global_load_dwordx4 v[72:75], v[36:37], off offset:256
	v_mfma_f32_16x16x32_bf16 v[84:87], v[84:87], v[2:5], v[24:27]
	global_load_dwordx4 v[64:67], v[36:37], off offset:512
	s_nop 1
	global_load_dwordx4 v[24:27], v[36:37], off offset:768
	s_and_saveexec_b64 s[34:35], s[12:13]
	s_cbranch_execz .LBB0_1131
	ds_read_b32 v0, v179 offset:1424
	s_waitcnt lgkmcnt(0)
	v_add_f32_e32 v55, v84, v0

.LBB0_1145:
	s_or_b64 exec, exec, s[34:35]
	v_max_f32_e32 v82, v36, v36
	v_max_f32_e32 v83, v55, v55
	v_max_f32_e32 v82, v83, v82
	v_max_f32_e32 v83, v54, v54
	v_max_f32_e32 v85, v0, v0
	v_max_f32_e32 v83, v85, v83
	v_max_f32_e32 v85, v81, v81
	v_max_f32_e32 v86, v80, v80
	v_max_f32_e32 v85, v86, v85
	v_max3_f32 v85, v37, v84, v85
	v_max3_f32 v82, v82, v83, v85
	v_mov_b32_e32 v83, v82
	s_nop 1
	v_permlane16_swap_b32_e32 v83, v82
	v_mov_b32_e32 v149, v1
	v_mov_b32_e32 v145, v1
	v_mov_b32_e32 v143, v1
	v_mov_b32_e32 v147, v1
	s_waitcnt lgkmcnt(0)
	v_max_f32_e32 v83, v83, v83
	v_max_f32_e32 v82, v82, v83
	v_mov_b32_e32 v83, v82
	s_nop 1
	v_permlane32_swap_b32_e32 v83, v82
	s_waitcnt vmcnt(13)
	v_mfma_f32_16x16x32_bf16 v[124:127], v[124:127], v[6:9], 0
	s_waitcnt lgkmcnt(0)
	v_max3_f32 v208, v158, v82, v83
	v_sub_f32_e32 v0, v0, v208
	v_mul_f32_e32 v0, 0x3fb8aa3b, v0
	v_exp_f32_e32 v202, v0
	v_sub_f32_e32 v0, v54, v208
	v_mul_f32_e32 v0, 0x3fb8aa3b, v0
	v_exp_f32_e32 v203, v0
	v_sub_f32_e32 v0, v37, v208
	v_mul_f32_e32 v0, 0x3fb8aa3b, v0
	v_exp_f32_e32 v204, v0
	v_sub_f32_e32 v0, v84, v208
	v_sub_f32_e32 v55, v55, v208
	v_sub_f32_e32 v36, v36, v208
	v_mul_f32_e32 v0, 0x3fb8aa3b, v0
	v_mul_f32_e32 v55, 0x3fb8aa3b, v55
	v_mul_f32_e32 v36, 0x3fb8aa3b, v36
	v_exp_f32_e32 v205, v0
	v_sub_f32_e32 v0, v80, v208
	v_exp_f32_e32 v200, v55
	v_exp_f32_e32 v201, v36
	v_mul_f32_e32 v0, 0x3fb8aa3b, v0
	v_exp_f32_e32 v206, v0
	v_sub_f32_e32 v0, v81, v208
	v_sub_f32_e32 v82, v158, v208
	v_mul_f32_e32 v0, 0x3fb8aa3b, v0
	v_mul_f32_e32 v82, 0x3fb8aa3b, v82
	v_exp_f32_e32 v207, v0
	v_exp_f32_e32 v158, v82
	v_cvt_pk_bf16_f32 v88, v200, v201
	v_cvt_pk_bf16_f32 v89, v202, v203
	v_cvt_pk_bf16_f32 v90, v204, v205
	v_cvt_pk_bf16_f32 v91, v206, v207
	v_pk_mul_f32 v[44:45], v[44:45], v[158:159] op_sel_hi:[1,0]
	v_pk_mul_f32 v[42:43], v[42:43], v[158:159] op_sel_hi:[1,0]
	v_pk_mul_f32 v[52:53], v[52:53], v[158:159] op_sel_hi:[1,0]
	v_pk_mul_f32 v[50:51], v[50:51], v[158:159] op_sel_hi:[1,0]
	v_mfma_f32_16x16x32_bf16 v[80:83], v[60:63], v[88:91], v[42:45]
	s_nop 2
	v_mul_f32_e64 v44, v94, v158
	v_mul_f32_e64 v45, v95, v158
	v_pk_mul_f32 v[42:43], v[92:93], v[158:159] op_sel_hi:[1,0]
	v_mfma_f32_16x16x32_bf16 v[84:87], v[68:71], v[88:91], v[50:53]
	s_nop 0
	v_mfma_f32_16x16x32_bf16 v[68:71], v[46:49], v[88:91], v[42:45]
	s_nop 2
	v_mul_f32_e64 v44, v102, v158
	v_mul_f32_e64 v45, v103, v158
	v_pk_mul_f32 v[42:43], v[100:101], v[158:159] op_sel_hi:[1,0]
	s_nop 1
	v_mfma_f32_16x16x32_bf16 v[36:39], v[38:41], v[88:91], v[42:45]
	v_add_u32_e32 v40, 0x1c0, v150
	v_lshlrev_b32_e32 v0, 7, v40
	s_nop 0
	v_lshl_add_u64 v[44:45], s[30:31], 0, v[0:1]
	v_mul_lo_u32 v0, v40, s33
	v_lshl_add_u64 v[40:41], s[28:29], 0, v[0:1]
	v_lshl_add_u64 v[40:41], v[40:41], 0, v[148:149]
	v_lshl_add_u64 v[40:41], v[40:41], 0, v[144:145]
	global_load_dwordx4 v[108:111], v[40:41], off
	global_load_dwordx4 v[96:99], v[40:41], off offset:16
	global_load_dwordx4 v[100:103], v[40:41], off offset:3072
	global_load_dwordx4 v[92:95], v[40:41], off offset:3088
	v_lshl_add_u64 v[44:45], v[44:45], 0, v[142:143]
	v_lshl_add_u64 v[44:45], v[44:45], 0, v[146:147]
	global_load_dwordx4 v[60:63], v[44:45], off
	global_load_dwordx4 v[52:55], v[44:45], off offset:256
	global_load_dwordx4 v[48:51], v[44:45], off offset:512
	s_nop 0
	global_load_dwordx4 v[44:47], v[44:45], off offset:768
	v_mfma_f32_16x16x32_bf16 v[40:43], v[128:131], v[6:9], 0
	v_mfma_f32_16x16x32_bf16 v[88:91], v[120:123], v[2:5], v[40:43]
	s_waitcnt vmcnt(20)
	v_mfma_f32_16x16x32_bf16 v[40:43], v[116:119], v[2:5], v[124:127]
	s_and_saveexec_b64 s[28:29], s[12:13]
	s_cbranch_execz .LBB0_1147
	ds_read_b32 v0, v179 offset:1548
	s_waitcnt lgkmcnt(0)
	s_nop 1
	v_add_f32_e32 v151, v88, v0

.LBB0_1161:
	s_or_b64 exec, exec, s[28:29]
	v_max_f32_e32 v42, v88, v88
	v_max_f32_e32 v43, v151, v151
	v_max_f32_e32 v42, v43, v42
	v_max_f32_e32 v43, v90, v90
	v_max_f32_e32 v117, v0, v0
	v_max_f32_e32 v43, v117, v43
	v_max_f32_e32 v117, v41, v41
	v_max_f32_e32 v118, v40, v40
	v_max_f32_e32 v117, v118, v117
	v_max3_f32 v117, v89, v91, v117
	v_max3_f32 v42, v42, v43, v117
	v_mov_b32_e32 v43, v42
	s_nop 1
	v_permlane16_swap_b32_e32 v43, v42
	s_lshl_b32 s1, s0, 6
	s_and_b64 s[2:3], s[26:27], exec
	s_cselect_b32 s2, 2, 0
	v_readlane_b32 s3, v255, 21
	s_waitcnt lgkmcnt(0)
	v_max_f32_e32 v43, v43, v43
	v_max_f32_e32 v42, v42, v43
	v_mov_b32_e32 v43, v42
	s_nop 1
	v_permlane32_swap_b32_e32 v43, v42
	s_or_b32 s26, s2, s3
	s_mul_i32 s44, s26, 0x18000
	s_lshl_b64 s[2:3], s[44:45], 1
	s_add_u32 s2, s42, s2
	s_waitcnt lgkmcnt(0)
	v_max3_f32 v117, v208, v42, v43
	v_sub_f32_e32 v0, v0, v117
	v_mul_f32_e32 v0, 0x3fb8aa3b, v0
	v_exp_f32_e32 v127, v0
	v_sub_f32_e32 v0, v90, v117
	v_mul_f32_e32 v0, 0x3fb8aa3b, v0
	v_exp_f32_e32 v128, v0
	v_sub_f32_e32 v0, v89, v117
	v_sub_f32_e32 v43, v151, v117
	v_mul_f32_e32 v0, 0x3fb8aa3b, v0
	v_mul_f32_e32 v43, 0x3fb8aa3b, v43
	v_exp_f32_e32 v129, v0
	v_sub_f32_e32 v0, v91, v117
	v_exp_f32_e32 v125, v43
	v_sub_f32_e32 v43, v88, v117
	v_mul_f32_e32 v0, 0x3fb8aa3b, v0
	v_sub_f32_e32 v42, v208, v117
	v_mul_f32_e32 v43, 0x3fb8aa3b, v43
	v_exp_f32_e32 v208, v0
	v_sub_f32_e32 v0, v40, v117
	v_exp_f32_e32 v126, v43
	v_mul_f32_e32 v0, 0x3fb8aa3b, v0
	v_exp_f32_e32 v209, v0
	v_sub_f32_e32 v0, v41, v117
	v_mul_f32_e32 v0, 0x3fb8aa3b, v0
	v_mul_f32_e32 v42, 0x3fb8aa3b, v42
	v_exp_f32_e32 v210, v0
	s_addc_u32 s3, s43, s3
	s_lshl_b32 s30, s1, 1
	v_exp_f32_e32 v0, v42
	s_add_u32 s28, s2, s30
	s_mul_i32 s1, s26, 6
	v_cvt_pk_bf16_f32 v40, v125, v126
	s_addc_u32 s29, s3, 0
	s_add_i32 s44, s1, s0
	v_cvt_pk_bf16_f32 v41, v127, v128
	s_lshl_b64 s[0:1], s[44:45], 15
	v_cvt_pk_bf16_f32 v42, v129, v208
	s_add_u32 s26, s46, s0
	v_mov_b32_e32 v149, v1
	v_cvt_pk_bf16_f32 v43, v209, v210
	v_pk_mul_f32 v[86:87], v[86:87], v[0:1] op_sel_hi:[1,0]
	v_pk_mul_f32 v[84:85], v[84:85], v[0:1] op_sel_hi:[1,0]
	s_addc_u32 s27, s47, s1
	v_mov_b32_e32 v145, v1
	s_waitcnt vmcnt(19)
	v_mfma_f32_16x16x32_bf16 v[56:59], v[56:59], v[40:43], v[84:87]
	v_mul_f32_e64 v38, v38, v0
	v_mul_f32_e64 v39, v39, v0
	v_pk_mul_f32 v[36:37], v[36:37], v[0:1] op_sel_hi:[1,0]
	v_mov_b32_e32 v143, v1
	v_lshl_add_u64 v[84:85], s[28:29], 0, v[148:149]
	s_waitcnt vmcnt(15)
	v_mfma_f32_16x16x32_bf16 v[112:115], v[112:115], v[6:9], 0
	v_mul_f32_e64 v82, v82, v0
	v_mul_f32_e64 v83, v83, v0
	v_pk_mul_f32 v[80:81], v[80:81], v[0:1] op_sel_hi:[1,0]
	v_pk_mul_f32 v[70:71], v[70:71], v[0:1] op_sel_hi:[1,0]
	v_pk_mul_f32 v[68:69], v[68:69], v[0:1] op_sel_hi:[1,0]
	v_lshl_add_u64 v[130:131], v[84:85], 0, v[144:145]
	v_mfma_f32_16x16x32_bf16 v[12:15], v[12:15], v[40:43], v[36:39]
	v_mov_b32_e32 v147, v1
	s_nop 1
	v_lshl_add_u64 v[36:37], s[26:27], 0, v[142:143]
	v_mfma_f32_16x16x32_bf16 v[20:23], v[20:23], v[40:43], v[80:83]
	v_lshl_add_u64 v[150:151], v[36:37], 0, v[146:147]
	global_load_dwordx4 v[88:91], v[130:131], off
	s_nop 0
	global_load_dwordx4 v[80:83], v[130:131], off offset:16
	v_mfma_f32_16x16x32_bf16 v[16:19], v[16:19], v[40:43], v[68:71]
	global_load_dwordx4 v[84:87], v[130:131], off offset:3072
	s_nop 1
	global_load_dwordx4 v[68:71], v[130:131], off offset:3088
	global_load_dwordx4 v[40:43], v[150:151], off
	global_load_dwordx4 v[36:39], v[150:151], off offset:256
	s_waitcnt vmcnt(19)
	v_mfma_f32_16x16x32_bf16 v[118:121], v[32:35], v[6:9], 0
	v_mfma_f32_16x16x32_bf16 v[112:115], v[28:31], v[2:5], v[112:115]
	global_load_dwordx4 v[32:35], v[150:151], off offset:512
	global_load_dwordx4 v[28:31], v[150:151], off offset:768
	s_waitcnt vmcnt(20)
	v_mfma_f32_16x16x32_bf16 v[104:107], v[104:107], v[2:5], v[118:121]
	s_and_saveexec_b64 s[34:35], s[12:13]
	s_cbranch_execz .LBB0_1163
	ds_read_b32 v116, v179 offset:1672
	s_waitcnt lgkmcnt(0)
	v_add_f32_e32 v116, v112, v116

.LBB0_1177:
	s_or_b64 exec, exec, s[34:35]
	v_max_f32_e32 v106, v118, v118
	v_max_f32_e32 v107, v116, v116
	v_max_f32_e32 v106, v107, v106
	v_max_f32_e32 v107, v114, v114
	v_max_f32_e32 v119, v112, v112
	v_max_f32_e32 v107, v119, v107
	v_max_f32_e32 v119, v105, v105
	v_max_f32_e32 v120, v104, v104
	v_max_f32_e32 v119, v120, v119
	v_max3_f32 v119, v113, v115, v119
	v_max3_f32 v106, v106, v107, v119
	v_mov_b32_e32 v107, v106
	s_nop 1
	v_permlane16_swap_b32_e32 v107, v106
	v_mov_b32_e32 v149, v1
	v_mov_b32_e32 v145, v1
	s_mov_b64 s[0:1], 0x6000
	v_mov_b32_e32 v143, v1
	s_waitcnt lgkmcnt(0)
	v_max_f32_e32 v107, v107, v107
	v_max_f32_e32 v106, v106, v107
	v_mov_b32_e32 v107, v106
	s_nop 1
	v_permlane32_swap_b32_e32 v107, v106
	v_mov_b32_e32 v147, v1
	s_waitcnt vmcnt(13)
	v_mfma_f32_16x16x32_bf16 v[100:103], v[100:103], v[6:9], 0
	s_waitcnt lgkmcnt(0)
	v_max3_f32 v212, v117, v106, v107
	v_sub_f32_e32 v107, v116, v212
	v_mul_f32_e32 v107, 0x3fb8aa3b, v107
	v_exp_f32_e32 v213, v107
	v_sub_f32_e32 v107, v118, v212
	v_mul_f32_e32 v107, 0x3fb8aa3b, v107
	v_exp_f32_e32 v214, v107
	v_sub_f32_e32 v107, v112, v212
	v_mul_f32_e32 v107, 0x3fb8aa3b, v107
	v_exp_f32_e32 v215, v107
	v_sub_f32_e32 v107, v114, v212
	v_mul_f32_e32 v107, 0x3fb8aa3b, v107
	v_exp_f32_e32 v216, v107
	v_sub_f32_e32 v107, v113, v212
	v_mul_f32_e32 v107, 0x3fb8aa3b, v107
	v_sub_f32_e32 v104, v104, v212
	v_exp_f32_e32 v217, v107
	v_sub_f32_e32 v107, v115, v212
	v_mul_f32_e32 v104, 0x3fb8aa3b, v104
	v_mul_f32_e32 v107, 0x3fb8aa3b, v107
	v_exp_f32_e32 v219, v104
	v_sub_f32_e32 v104, v105, v212
	v_sub_f32_e32 v106, v117, v212
	v_exp_f32_e32 v218, v107
	v_mul_f32_e32 v104, 0x3fb8aa3b, v104
	v_mul_f32_e32 v106, 0x3fb8aa3b, v106
	v_exp_f32_e32 v220, v104
	v_exp_f32_e32 v124, v106
	v_cvt_pk_bf16_f32 v104, v213, v214
	v_cvt_pk_bf16_f32 v105, v215, v216
	v_cvt_pk_bf16_f32 v106, v217, v218
	v_cvt_pk_bf16_f32 v107, v219, v220
	v_pk_mul_f32 v[58:59], v[58:59], v[124:125] op_sel_hi:[1,0]
	v_pk_mul_f32 v[56:57], v[56:57], v[124:125] op_sel_hi:[1,0]
	v_pk_mul_f32 v[22:23], v[22:23], v[124:125] op_sel_hi:[1,0]
	v_pk_mul_f32 v[20:21], v[20:21], v[124:125] op_sel_hi:[1,0]
	v_pk_mul_f32 v[18:19], v[18:19], v[124:125] op_sel_hi:[1,0]
	v_pk_mul_f32 v[16:17], v[16:17], v[124:125] op_sel_hi:[1,0]
	v_pk_mul_f32 v[14:15], v[14:15], v[124:125] op_sel_hi:[1,0]
	v_pk_mul_f32 v[12:13], v[12:13], v[124:125] op_sel_hi:[1,0]
	v_mfma_f32_16x16x32_bf16 v[120:123], v[76:79], v[104:107], v[56:59]
	v_mfma_f32_16x16x32_bf16 v[116:119], v[72:75], v[104:107], v[20:23]
	v_mfma_f32_16x16x32_bf16 v[112:115], v[64:67], v[104:107], v[16:19]
	v_mfma_f32_16x16x32_bf16 v[104:107], v[24:27], v[104:107], v[12:15]
	s_nop 2
	v_lshl_add_u64 v[12:13], s[28:29], 0, v[148:149]
	v_lshl_add_u64 v[12:13], v[12:13], 0, v[144:145]
	v_lshl_add_u64 v[14:15], v[12:13], 0, s[0:1]
	s_movk_i32 s0, 0x6000
	v_add_co_u32_e32 v12, vcc, s0, v12
	s_mov_b64 s[0:1], 0x1000
	s_nop 0
	v_addc_co_u32_e32 v13, vcc, 0, v13, vcc
	global_load_dwordx4 v[64:67], v[14:15], off offset:16
	global_load_dwordx4 v[72:75], v[14:15], off offset:3072
	global_load_dwordx4 v[76:79], v[12:13], off
	global_load_dwordx4 v[56:59], v[14:15], off offset:3088
	v_lshl_add_u64 v[12:13], s[26:27], 0, v[142:143]
	v_lshl_add_u64 v[16:17], v[12:13], 0, v[146:147]
	v_mfma_f32_16x16x32_bf16 v[12:15], v[108:111], v[6:9], 0
	v_lshl_add_u64 v[108:109], v[16:17], 0, s[0:1]
	s_movk_i32 s0, 0x1000
	v_add_co_u32_e32 v24, vcc, s0, v16
	v_mfma_f32_16x16x32_bf16 v[96:99], v[96:99], v[2:5], v[12:15]
	s_nop 0
	v_addc_co_u32_e32 v25, vcc, 0, v17, vcc
	global_load_dwordx4 v[20:23], v[108:109], off offset:256
	global_load_dwordx4 v[16:19], v[108:109], off offset:512
	s_nop 0
	global_load_dwordx4 v[24:27], v[24:25], off
	s_nop 0
	global_load_dwordx4 v[12:15], v[108:109], off offset:768
	s_waitcnt vmcnt(20)
	v_mfma_f32_16x16x32_bf16 v[92:95], v[92:95], v[2:5], v[100:103]
	s_and_saveexec_b64 s[34:35], s[12:13]
	s_cbranch_execz .LBB0_1179
	s_nop 0
	ds_read_b32 v100, v179 offset:1796
	s_waitcnt lgkmcnt(0)
	v_add_f32_e32 v211, v96, v100

.LBB0_1197:
	s_bitcmp0_b32 s17, 0
	s_cselect_b32 s0, s11, s16
	s_add_i32 s0, s0, s10
	s_add_i32 s1, s0, 0xfffff900
	s_cmp_lt_u32 s1, 0xfffffd00
	s_cbranch_scc1 .LBB0_1196
	s_add_i32 s0, s0, 0xfc00
	s_and_b32 s1, s0, 0xffff
	s_mul_i32 s1, s1, 0xaaab
	s_lshr_b32 s2, s1, 21
	s_mul_i32 s1, s2, 48
	s_sub_i32 s0, s0, s1
	s_bfe_u32 s3, s0, 0xd0003
	s_lshl_b32 s0, s0, 5
	s_lshl_b32 s1, s2, 8
	s_and_b32 s0, s0, 0xe0
	s_or_b32 s0, s0, s1
	v_or_b32_e32 v0, s0, v149
	v_mov_b64_e32 v[6:7], s[8:9]
	v_mad_u64_u32 v[8:9], s[0:1], v0, s33, v[6:7]
	s_lshl_b32 s44, s3, 7
	s_mul_i32 s2, s2, 0x30000
	s_add_u32 s0, s12, s2
	s_addc_u32 s1, s13, 0
	s_add_u32 s0, s0, s44
	s_addc_u32 s1, s1, 0
	v_mov_b32_e32 v83, v1
	v_mov_b32_e32 v81, v1
	v_lshl_add_u64 v[2:3], s[0:1], 0, v[82:83]
	v_lshl_add_u64 v[204:205], v[2:3], 0, v[80:81]
	global_load_dwordx4 v[2:5], v[204:205], off
	v_lshl_add_u64 v[8:9], v[8:9], 0, s[44:45]
	v_lshl_add_u64 v[8:9], v[8:9], 0, v[80:81]
	global_load_dwordx4 v[48:51], v[8:9], off
	global_load_dwordx4 v[16:19], v[204:205], off offset:3072
	v_or_b32_e32 v89, 16, v0
	v_mad_u64_u32 v[6:7], s[0:1], v89, s33, v[6:7]
	v_lshl_add_u64 v[6:7], v[6:7], 0, s[44:45]
	v_lshl_add_u64 v[6:7], v[6:7], 0, v[80:81]
	global_load_dwordx4 v[12:15], v[6:7], off
	global_load_dwordx4 v[20:23], v[204:205], off offset:16
	global_load_dwordx4 v[64:67], v[8:9], off offset:16
	global_load_dwordx4 v[24:27], v[204:205], off offset:3088
	s_nop 0
	global_load_dwordx4 v[8:11], v[6:7], off offset:16
	s_add_u32 s0, s14, s2
	s_addc_u32 s1, s15, 0
	s_lshl_b32 s2, s3, 15
	s_add_u32 s0, s0, s2
	v_mov_b32_e32 v85, v1
	s_addc_u32 s1, s1, 0
	v_mov_b32_e32 v87, v1
	v_lshl_add_u64 v[6:7], s[0:1], 0, v[84:85]
	v_lshl_add_u64 v[202:203], v[6:7], 0, v[86:87]
	global_load_dwordx4 v[28:31], v[202:203], off
	global_load_dwordx4 v[44:47], v[202:203], off offset:256
	v_cmp_lt_i32_e32 vcc, v231, v226
	global_load_dwordx4 v[52:55], v[202:203], off offset:768
	global_load_dwordx4 v[40:43], v[202:203], off offset:512
	v_cndmask_b32_e32 v6, v225, v231, vcc
	v_lshlrev_b32_e32 v81, 2, v6
	v_cmp_lt_i32_e32 vcc, v232, v226
	s_movk_i32 s1, 0x6000
	s_mov_b32 s0, 0xf149f2ca
	v_lshlrev_b32_e32 v0, 11, v0
	s_mov_b64 s[18:19], 0xd800200
	s_mov_b32 s2, 0xd800000
	s_waitcnt vmcnt(9)
	v_mfma_f32_16x16x32_bf16 v[36:39], v[16:19], v[48:51], 0
	v_mfma_f32_16x16x32_bf16 v[32:35], v[2:5], v[48:51], 0
	s_waitcnt vmcnt(6)
	v_mfma_f32_16x16x32_bf16 v[56:59], v[20:23], v[64:67], v[32:35]
	s_waitcnt vmcnt(5)
	v_mfma_f32_16x16x32_bf16 v[36:39], v[24:27], v[64:67], v[36:39]
	v_mfma_f32_16x16x32_bf16 v[2:5], v[2:5], v[12:15], 0
	s_nop 4
	v_max_f32_e32 v6, v57, v57
	v_max_f32_e32 v7, v56, v56
	v_max_f32_e32 v32, v59, v59
	v_max_f32_e32 v33, v58, v58
	v_max_f32_e32 v34, v39, v39
	v_max_f32_e32 v35, v38, v38
	v_max_f32_e32 v6, v7, v6
	v_max_f32_e32 v7, v33, v32
	v_max_f32_e32 v32, v35, v34
	v_max3_f32 v32, v36, v37, v32
	v_max3_f32 v6, v6, v7, v32
	ds_bpermute_b32 v7, v81, v6
	v_cndmask_b32_e32 v32, v225, v232, vcc
	v_lshlrev_b32_e32 v83, 2, v32
	s_waitcnt vmcnt(4)
	v_mfma_f32_16x16x32_bf16 v[32:35], v[20:23], v[8:11], v[2:5]
	v_add_co_u32_e32 v72, vcc, s1, v204
	s_waitcnt lgkmcnt(0)
	s_nop 0
	v_max_f32_e32 v2, v7, v7
	v_max_f32_e32 v2, v6, v2
	v_mov_b32_e32 v3, v2
	s_nop 1
	v_permlane32_swap_b32_e32 v3, v2
	v_mfma_f32_16x16x32_bf16 v[16:19], v[16:19], v[12:15], 0
	v_addc_co_u32_e32 v73, vcc, 0, v205, vcc
	global_load_dwordx4 v[68:71], v[72:73], off offset:16
	s_waitcnt lgkmcnt(0)
	v_max3_f32 v91, v2, v3, s0
	v_mfma_f32_16x16x32_bf16 v[60:63], v[24:27], v[8:11], v[16:19]
	v_sub_f32_e32 v20, v39, v91
	v_max_f32_e32 v6, v33, v33
	v_max_f32_e32 v7, v32, v32
	v_sub_f32_e32 v17, v36, v91
	v_sub_f32_e32 v18, v37, v91
	v_sub_f32_e32 v19, v38, v91
	global_load_dwordx4 v[36:39], v[72:73], off
	v_max_f32_e32 v24, v35, v35
	v_max_f32_e32 v25, v34, v34
	v_max_f32_e32 v6, v7, v6
	v_max_f32_e32 v7, v25, v24
	v_max_f32_e32 v24, v63, v63
	v_max_f32_e32 v25, v62, v62
	v_max_f32_e32 v24, v25, v24
	v_max3_f32 v24, v60, v61, v24
	v_max3_f32 v6, v6, v7, v24
	v_mov_b32_e32 v7, v6
	s_nop 1
	v_permlane16_swap_b32_e32 v7, v6
	v_sub_f32_e32 v2, 0xf149f2ca, v91
	v_sub_f32_e32 v3, v56, v91
	v_sub_f32_e32 v4, v57, v91
	v_sub_f32_e32 v5, v58, v91
	v_sub_f32_e32 v16, v59, v91
	s_waitcnt lgkmcnt(0)
	v_max_f32_e32 v7, v7, v7
	v_mul_f32_e32 v2, 0x3fb8aa3b, v2
	v_mul_f32_e32 v3, 0x3fb8aa3b, v3
	v_mul_f32_e32 v4, 0x3fb8aa3b, v4
	v_mul_f32_e32 v5, 0x3fb8aa3b, v5
	v_mul_f32_e32 v16, 0x3fb8aa3b, v16
	v_mul_f32_e32 v17, 0x3fb8aa3b, v17
	v_mul_f32_e32 v18, 0x3fb8aa3b, v18
	v_mul_f32_e32 v19, 0x3fb8aa3b, v19
	v_mul_f32_e32 v20, 0x3fb8aa3b, v20
	v_max_f32_e32 v6, v6, v7
	v_exp_f32_e32 v85, v3
	v_exp_f32_e32 v87, v4
	v_exp_f32_e32 v100, v5
	v_exp_f32_e32 v98, v16
	v_exp_f32_e32 v96, v17
	v_exp_f32_e32 v94, v18
	v_exp_f32_e32 v92, v19
	v_exp_f32_e32 v90, v20
	v_exp_f32_e32 v2, v2
	v_mov_b32_e32 v7, v6
	s_nop 1
	v_permlane32_swap_b32_e32 v7, v6
	v_mul_f32_e32 v2, 0, v2
	v_cvt_pk_bf16_f32 v20, v85, v87
	v_cvt_pk_bf16_f32 v21, v100, v98
	v_cvt_pk_bf16_f32 v22, v96, v94
	v_cvt_pk_bf16_f32 v23, v92, v90
	v_mov_b32_e32 v3, v2
	v_mov_b32_e32 v4, v2
	v_mov_b32_e32 v5, v2
	s_waitcnt lgkmcnt(0)
	v_max3_f32 v103, v6, v7, s0
	s_movk_i32 s0, 0x2000
	s_waitcnt vmcnt(5)
	v_mfma_f32_16x16x32_bf16 v[56:59], v[28:31], v[20:23], v[2:5]
	v_add_co_u32_e32 v120, vcc, s0, v202
	s_movk_i32 s0, 0x1000
	s_waitcnt vmcnt(4)
	v_mfma_f32_16x16x32_bf16 v[16:19], v[44:47], v[20:23], v[2:5]
	v_addc_co_u32_e32 v121, vcc, 0, v203, vcc
	global_load_dwordx4 v[136:139], v[120:121], off
	s_waitcnt vmcnt(3)
	v_mfma_f32_16x16x32_bf16 v[24:27], v[40:43], v[20:23], v[2:5]
	global_load_dwordx4 v[144:147], v[120:121], off offset:512
	global_load_dwordx4 v[154:157], v[120:121], off offset:768
	v_mfma_f32_16x16x32_bf16 v[20:23], v[52:55], v[20:23], v[2:5]
	s_nop 2
	v_sub_f32_e32 v4, v32, v103
	v_mul_f32_e32 v4, 0x3fb8aa3b, v4
	v_exp_f32_e32 v151, v4
	v_sub_f32_e32 v4, v33, v103
	v_mul_f32_e32 v4, 0x3fb8aa3b, v4
	v_exp_f32_e32 v153, v4
	v_sub_f32_e32 v4, v34, v103
	v_mul_f32_e32 v4, 0x3fb8aa3b, v4
	v_exp_f32_e32 v112, v4
	v_sub_f32_e32 v4, v35, v103
	v_mul_f32_e32 v4, 0x3fb8aa3b, v4
	v_exp_f32_e32 v110, v4
	v_sub_f32_e32 v4, v60, v103
	v_mul_f32_e32 v4, 0x3fb8aa3b, v4
	v_exp_f32_e32 v108, v4
	v_sub_f32_e32 v4, v61, v103
	v_mul_f32_e32 v4, 0x3fb8aa3b, v4
	v_exp_f32_e32 v106, v4
	v_sub_f32_e32 v4, v62, v103
	v_mul_f32_e32 v4, 0x3fb8aa3b, v4
	v_exp_f32_e32 v104, v4
	v_sub_f32_e32 v4, v63, v103
	v_sub_f32_e32 v3, 0xf149f2ca, v103
	v_mul_f32_e32 v4, 0x3fb8aa3b, v4
	v_mul_f32_e32 v3, 0x3fb8aa3b, v3
	v_exp_f32_e32 v102, v4
	v_exp_f32_e32 v3, v3
	v_cvt_pk_bf16_f32 v76, v151, v153
	v_cvt_pk_bf16_f32 v77, v112, v110
	v_cvt_pk_bf16_f32 v78, v108, v106
	v_cvt_pk_bf16_f32 v79, v104, v102
	v_mul_f32_e32 v4, 0, v3
	v_mov_b32_e32 v5, v4
	v_mov_b32_e32 v6, v4
	v_mov_b32_e32 v7, v4
	global_load_dwordx4 v[60:63], v[72:73], off offset:3072
	s_nop 0
	v_mfma_f32_16x16x32_bf16 v[32:35], v[28:31], v[76:79], v[4:7]
	v_mfma_f32_16x16x32_bf16 v[28:31], v[44:47], v[76:79], v[4:7]
	s_waitcnt vmcnt(4)
	v_mfma_f32_16x16x32_bf16 v[44:47], v[36:39], v[48:51], 0
	v_mfma_f32_16x16x32_bf16 v[122:125], v[68:71], v[64:67], v[44:47]
	v_mfma_f32_16x16x32_bf16 v[40:43], v[40:43], v[76:79], v[4:7]
	s_nop 5
	global_load_dwordx4 v[44:47], v[120:121], off offset:-4096
	v_max_f32_e32 v3, v123, v123
	global_load_dwordx4 v[72:75], v[72:73], off offset:3088
	s_waitcnt vmcnt(2)
	v_mfma_f32_16x16x32_bf16 v[114:117], v[60:63], v[48:51], 0
	v_max_f32_e32 v93, v122, v122
	v_max_f32_e32 v3, v93, v3
	v_max_f32_e32 v93, v125, v125
	s_waitcnt vmcnt(0)
	v_mfma_f32_16x16x32_bf16 v[126:129], v[72:75], v[64:67], v[114:117]
	v_max_f32_e32 v95, v124, v124
	v_max_f32_e32 v93, v95, v93
	s_nop 0
	v_add_co_u32_e32 v116, vcc, s0, v202
	s_nop 3
	v_max_f32_e32 v95, v129, v129
	v_max_f32_e32 v97, v128, v128
	v_max_f32_e32 v95, v97, v95
	v_max3_f32 v95, v126, v127, v95
	v_max3_f32 v3, v3, v93, v95
	v_mov_b32_e32 v93, v3
	s_nop 1
	v_permlane16_swap_b32_e32 v93, v3
	v_mfma_f32_16x16x32_bf16 v[52:55], v[52:55], v[76:79], v[4:7]
	v_addc_co_u32_e32 v117, vcc, 0, v203, vcc
	s_mov_b32 s0, 0xc000
	s_waitcnt lgkmcnt(0)
	v_max_f32_e32 v93, v93, v93
	v_max_f32_e32 v3, v3, v93
	v_mov_b32_e32 v93, v3
	s_nop 1
	v_permlane32_swap_b32_e32 v93, v3
	v_mfma_f32_16x16x32_bf16 v[36:39], v[36:39], v[12:15], 0
	s_waitcnt lgkmcnt(0)
	v_max3_f32 v6, v91, v3, v93
	v_sub_f32_e32 v3, v91, v6
	v_mul_f32_e32 v5, 0x3fb8aa3b, v3
	v_sub_f32_e32 v3, v122, v6
	v_mul_f32_e32 v3, 0x3fb8aa3b, v3
	v_exp_f32_e32 v101, v3
	v_sub_f32_e32 v3, v123, v6
	v_mul_f32_e32 v3, 0x3fb8aa3b, v3
	v_exp_f32_e32 v99, v3
	v_sub_f32_e32 v3, v124, v6
	v_mul_f32_e32 v3, 0x3fb8aa3b, v3
	v_exp_f32_e32 v97, v3
	v_sub_f32_e32 v3, v125, v6
	global_load_dwordx4 v[122:125], v[116:117], off offset:256
	v_mul_f32_e32 v3, 0x3fb8aa3b, v3
	v_exp_f32_e32 v95, v3
	v_sub_f32_e32 v3, v126, v6
	v_mul_f32_e32 v3, 0x3fb8aa3b, v3
	v_exp_f32_e32 v93, v3
	v_sub_f32_e32 v3, v127, v6
	v_mul_f32_e32 v3, 0x3fb8aa3b, v3
	v_exp_f32_e32 v91, v3
	v_sub_f32_e32 v3, v128, v6
	v_sub_f32_e32 v7, v129, v6
	v_mul_f32_e32 v3, 0x3fb8aa3b, v3
	v_mul_f32_e32 v7, 0x3fb8aa3b, v7
	v_mfma_f32_16x16x32_bf16 v[60:63], v[60:63], v[12:15], 0
	v_exp_f32_e32 v3, v3
	v_exp_f32_e32 v167, v7
	v_exp_f32_e32 v114, v5
	v_mfma_f32_16x16x32_bf16 v[36:39], v[68:71], v[8:11], v[36:39]
	v_cvt_pk_bf16_f32 v76, v101, v99
	v_cvt_pk_bf16_f32 v77, v97, v95
	v_mfma_f32_16x16x32_bf16 v[60:63], v[72:75], v[8:11], v[60:63]
	v_cvt_pk_bf16_f32 v78, v93, v91
	v_cvt_pk_bf16_f32 v79, v3, v167
	s_nop 2
	v_max_f32_e32 v5, v37, v37
	v_max_f32_e32 v7, v36, v36
	v_max_f32_e32 v5, v7, v5
	v_max_f32_e32 v7, v39, v39
	v_max_f32_e32 v72, v38, v38
	v_max_f32_e32 v7, v72, v7
	v_max_f32_e32 v72, v63, v63
	v_max_f32_e32 v73, v62, v62
	v_max_f32_e32 v72, v73, v72
	v_max3_f32 v72, v60, v61, v72
	v_max3_f32 v5, v5, v7, v72
	v_mov_b32_e32 v7, v5
	s_nop 1
	v_permlane16_swap_b32_e32 v7, v5
	v_pk_mul_f32 v[58:59], v[58:59], v[114:115] op_sel_hi:[1,0]
	v_pk_mul_f32 v[56:57], v[56:57], v[114:115] op_sel_hi:[1,0]
	v_pk_mul_f32 v[18:19], v[18:19], v[114:115] op_sel_hi:[1,0]
	v_pk_mul_f32 v[16:17], v[16:17], v[114:115] op_sel_hi:[1,0]
	s_waitcnt lgkmcnt(0)
	v_max_f32_e32 v7, v7, v7
	v_max_f32_e32 v5, v5, v7
	v_mov_b32_e32 v7, v5
	s_nop 1
	v_permlane32_swap_b32_e32 v7, v5
	v_pk_mul_f32 v[26:27], v[26:27], v[114:115] op_sel_hi:[1,0]
	v_pk_mul_f32 v[24:25], v[24:25], v[114:115] op_sel_hi:[1,0]
	v_pk_mul_f32 v[22:23], v[22:23], v[114:115] op_sel_hi:[1,0]
	v_pk_mul_f32 v[20:21], v[20:21], v[114:115] op_sel_hi:[1,0]
	s_waitcnt lgkmcnt(0)
	v_max3_f32 v115, v103, v5, v7
	v_sub_f32_e32 v5, v103, v115
	v_mul_f32_e32 v7, 0x3fb8aa3b, v5
	v_sub_f32_e32 v5, v36, v115
	v_mul_f32_e32 v5, 0x3fb8aa3b, v5
	v_exp_f32_e32 v113, v5
	v_sub_f32_e32 v5, v37, v115
	v_mul_f32_e32 v5, 0x3fb8aa3b, v5
	v_exp_f32_e32 v111, v5
	v_sub_f32_e32 v5, v38, v115
	v_mul_f32_e32 v5, 0x3fb8aa3b, v5
	v_exp_f32_e32 v109, v5
	v_sub_f32_e32 v5, v39, v115
	v_mul_f32_e32 v5, 0x3fb8aa3b, v5
	v_exp_f32_e32 v107, v5
	v_sub_f32_e32 v5, v60, v115
	v_mul_f32_e32 v5, 0x3fb8aa3b, v5
	v_exp_f32_e32 v105, v5
	v_sub_f32_e32 v5, v61, v115
	v_mul_f32_e32 v5, 0x3fb8aa3b, v5
	v_exp_f32_e32 v103, v5
	v_sub_f32_e32 v5, v62, v115
	v_sub_f32_e32 v36, v63, v115
	v_mul_f32_e32 v5, 0x3fb8aa3b, v5
	v_mul_f32_e32 v36, 0x3fb8aa3b, v36
	v_exp_f32_e32 v5, v5
	v_exp_f32_e32 v206, v36
	v_exp_f32_e32 v118, v7
	v_cvt_pk_bf16_f32 v36, v113, v111
	v_cvt_pk_bf16_f32 v37, v109, v107
	global_load_dwordx4 v[126:129], v[116:117], off offset:512
	global_load_dwordx4 v[68:71], v[116:117], off offset:768
	v_add_co_u32_e32 v116, vcc, s0, v204
	v_cvt_pk_bf16_f32 v38, v105, v103
	s_nop 0
	v_addc_co_u32_e32 v117, vcc, 0, v205, vcc
	v_cvt_pk_bf16_f32 v39, v5, v206
	v_pk_mul_f32 v[34:35], v[34:35], v[118:119] op_sel_hi:[1,0]
	v_pk_mul_f32 v[32:33], v[32:33], v[118:119] op_sel_hi:[1,0]
	v_mfma_f32_16x16x32_bf16 v[56:59], v[44:47], v[76:79], v[56:59]
	global_load_dwordx4 v[60:63], v[116:117], off offset:3072
	global_load_dwordx4 v[130:133], v[116:117], off offset:3088
	v_pk_mul_f32 v[30:31], v[30:31], v[118:119] op_sel_hi:[1,0]
	v_mfma_f32_16x16x32_bf16 v[32:35], v[44:47], v[36:39], v[32:35]
	global_load_dwordx4 v[44:47], v[116:117], off
	v_pk_mul_f32 v[28:29], v[28:29], v[118:119] op_sel_hi:[1,0]
	v_pk_mul_f32 v[42:43], v[42:43], v[118:119] op_sel_hi:[1,0]
	s_waitcnt vmcnt(5)
	v_mfma_f32_16x16x32_bf16 v[16:19], v[122:125], v[76:79], v[16:19]
	v_mul_f32_e64 v40, v40, v118
	v_mul_f32_e64 v41, v41, v118
	v_pk_mul_f32 v[54:55], v[54:55], v[118:119] op_sel_hi:[1,0]
	v_pk_mul_f32 v[52:53], v[52:53], v[118:119] op_sel_hi:[1,0]
	v_mfma_f32_16x16x32_bf16 v[28:31], v[122:125], v[36:39], v[28:31]
	global_load_dwordx4 v[122:125], v[116:117], off offset:16
	s_mov_b32 s0, 0x12000
	s_waitcnt vmcnt(1)
	v_mfma_f32_16x16x32_bf16 v[72:75], v[44:47], v[48:51], 0
	v_mfma_f32_16x16x32_bf16 v[24:27], v[126:129], v[76:79], v[24:27]
	v_mfma_f32_16x16x32_bf16 v[20:23], v[68:71], v[76:79], v[20:23]
	v_mfma_f32_16x16x32_bf16 v[76:79], v[60:63], v[48:51], 0
	s_waitcnt vmcnt(0)
	v_mfma_f32_16x16x32_bf16 v[72:75], v[122:125], v[64:67], v[72:75]
	v_mfma_f32_16x16x32_bf16 v[140:143], v[130:133], v[64:67], v[76:79]
	v_mfma_f32_16x16x32_bf16 v[40:43], v[126:129], v[36:39], v[40:43]
	s_nop 5
	v_max_f32_e32 v7, v73, v73
	v_max_f32_e32 v76, v72, v72
	v_max_f32_e32 v7, v76, v7
	v_max_f32_e32 v76, v75, v75
	v_max_f32_e32 v77, v74, v74
	v_max_f32_e32 v76, v77, v76
	v_max_f32_e32 v77, v143, v143
	v_max_f32_e32 v78, v142, v142
	v_max_f32_e32 v77, v78, v77
	v_max3_f32 v77, v140, v141, v77
	v_max3_f32 v7, v7, v76, v77
	v_mov_b32_e32 v76, v7
	s_nop 1
	v_permlane16_swap_b32_e32 v76, v7
	v_mfma_f32_16x16x32_bf16 v[36:39], v[68:71], v[36:39], v[52:55]
	s_waitcnt lgkmcnt(0)
	v_max_f32_e32 v76, v76, v76
	v_max_f32_e32 v7, v7, v76
	v_mov_b32_e32 v76, v7
	s_nop 1
	v_permlane32_swap_b32_e32 v76, v7
	v_mfma_f32_16x16x32_bf16 v[44:47], v[44:47], v[12:15], 0
	s_waitcnt lgkmcnt(0)
	v_max3_f32 v69, v6, v7, v76
	v_sub_f32_e32 v7, v72, v69
	v_mul_f32_e32 v7, 0x3fb8aa3b, v7
	v_exp_f32_e32 v181, v7
	v_sub_f32_e32 v7, v73, v69
	v_mul_f32_e32 v7, 0x3fb8aa3b, v7
	v_exp_f32_e32 v193, v7
	v_sub_f32_e32 v7, v74, v69
	v_mul_f32_e32 v7, 0x3fb8aa3b, v7
	v_exp_f32_e32 v78, v7
	v_sub_f32_e32 v7, v75, v69
	v_mul_f32_e32 v7, 0x3fb8aa3b, v7
	v_exp_f32_e32 v76, v7
	v_sub_f32_e32 v7, v140, v69
	v_mul_f32_e32 v7, 0x3fb8aa3b, v7
	v_exp_f32_e32 v74, v7
	v_sub_f32_e32 v7, v141, v69
	v_mul_f32_e32 v7, 0x3fb8aa3b, v7
	v_exp_f32_e32 v72, v7
	v_sub_f32_e32 v7, v142, v69
	v_mul_f32_e32 v7, 0x3fb8aa3b, v7
	v_exp_f32_e32 v70, v7
	v_sub_f32_e32 v7, v143, v69
	global_load_dwordx4 v[140:143], v[120:121], off offset:256
	v_mfma_f32_16x16x32_bf16 v[60:63], v[60:63], v[12:15], 0
	v_sub_f32_e32 v6, v6, v69
	v_mul_f32_e32 v6, 0x3fb8aa3b, v6
	v_exp_f32_e32 v116, v6
	v_mfma_f32_16x16x32_bf16 v[44:47], v[122:125], v[8:11], v[44:47]
	v_mul_f32_e32 v7, 0x3fb8aa3b, v7
	v_exp_f32_e32 v68, v7
	v_pk_mul_f32 v[58:59], v[58:59], v[116:117] op_sel_hi:[1,0]
	v_mfma_f32_16x16x32_bf16 v[60:63], v[130:133], v[8:11], v[60:63]
	v_mul_f32_e64 v56, v56, v116
	v_mul_f32_e64 v57, v57, v116
	s_nop 1
	v_max_f32_e32 v71, v45, v45
	v_max_f32_e32 v73, v44, v44
	v_max_f32_e32 v71, v73, v71
	v_max_f32_e32 v73, v47, v47
	v_max_f32_e32 v75, v46, v46
	v_max_f32_e32 v73, v75, v73
	v_max_f32_e32 v75, v63, v63
	v_max_f32_e32 v77, v62, v62
	v_max_f32_e32 v75, v77, v75
	v_max3_f32 v75, v60, v61, v75
	v_max3_f32 v71, v71, v73, v75
	v_mov_b32_e32 v73, v71
	s_nop 1
	v_permlane16_swap_b32_e32 v73, v71
	v_pk_mul_f32 v[18:19], v[18:19], v[116:117] op_sel_hi:[1,0]
	v_pk_mul_f32 v[16:17], v[16:17], v[116:117] op_sel_hi:[1,0]
	v_pk_mul_f32 v[26:27], v[26:27], v[116:117] op_sel_hi:[1,0]
	v_pk_mul_f32 v[24:25], v[24:25], v[116:117] op_sel_hi:[1,0]
	s_waitcnt lgkmcnt(0)
	v_max_f32_e32 v73, v73, v73
	v_max_f32_e32 v71, v71, v73
	v_mov_b32_e32 v73, v71
	s_nop 1
	v_permlane32_swap_b32_e32 v73, v71
	v_pk_mul_f32 v[22:23], v[22:23], v[116:117] op_sel_hi:[1,0]
	v_pk_mul_f32 v[20:21], v[20:21], v[116:117] op_sel_hi:[1,0]
	s_waitcnt lgkmcnt(0)
	v_max3_f32 v117, v115, v71, v73
	v_sub_f32_e32 v44, v44, v117
	v_mul_f32_e32 v44, 0x3fb8aa3b, v44
	v_exp_f32_e32 v207, v44
	v_sub_f32_e32 v44, v45, v117
	v_mul_f32_e32 v44, 0x3fb8aa3b, v44
	v_exp_f32_e32 v208, v44
	v_sub_f32_e32 v44, v46, v117
	v_mul_f32_e32 v44, 0x3fb8aa3b, v44
	v_exp_f32_e32 v132, v44
	v_sub_f32_e32 v44, v47, v117
	v_mul_f32_e32 v44, 0x3fb8aa3b, v44
	v_exp_f32_e32 v130, v44
	v_sub_f32_e32 v44, v60, v117
	v_mul_f32_e32 v44, 0x3fb8aa3b, v44
	v_exp_f32_e32 v128, v44
	v_sub_f32_e32 v44, v61, v117
	v_mul_f32_e32 v44, 0x3fb8aa3b, v44
	v_exp_f32_e32 v126, v44
	v_sub_f32_e32 v44, v62, v117
	v_mul_f32_e32 v44, 0x3fb8aa3b, v44
	v_cvt_pk_bf16_f32 v52, v181, v193
	v_exp_f32_e32 v124, v44
	v_sub_f32_e32 v44, v63, v117
	v_cvt_pk_bf16_f32 v53, v78, v76
	v_mul_f32_e32 v44, 0x3fb8aa3b, v44
	v_cvt_pk_bf16_f32 v54, v74, v72
	v_exp_f32_e32 v122, v44
	v_cvt_pk_bf16_f32 v55, v70, v68
	v_add_co_u32_e32 v6, vcc, s0, v204
	s_nop 0
	v_mfma_f32_16x16x32_bf16 v[56:59], v[136:139], v[52:55], v[56:59]
	s_nop 0
	v_addc_co_u32_e32 v7, vcc, 0, v205, vcc
	v_cvt_pk_bf16_f32 v44, v207, v208
	s_waitcnt vmcnt(0)
	v_mfma_f32_16x16x32_bf16 v[16:19], v[140:143], v[52:55], v[16:19]
	global_load_dwordx4 v[158:161], v[6:7], off
	global_load_dwordx4 v[60:63], v[6:7], off offset:16
	v_mfma_f32_16x16x32_bf16 v[24:27], v[144:147], v[52:55], v[24:27]
	v_cvt_pk_bf16_f32 v45, v132, v130
	v_mfma_f32_16x16x32_bf16 v[20:23], v[154:157], v[52:55], v[20:23]
	v_sub_f32_e32 v52, v115, v117
	v_mul_f32_e32 v52, 0x3fb8aa3b, v52
	v_exp_f32_e32 v134, v52
	v_cvt_pk_bf16_f32 v46, v128, v126
	v_cvt_pk_bf16_f32 v47, v124, v122
	global_load_dwordx4 v[52:55], v[6:7], off offset:3072
	v_pk_mul_f32 v[30:31], v[30:31], v[134:135] op_sel_hi:[1,0]
	v_pk_mul_f32 v[28:29], v[28:29], v[134:135] op_sel_hi:[1,0]
	v_pk_mul_f32 v[34:35], v[34:35], v[134:135] op_sel_hi:[1,0]
	v_pk_mul_f32 v[32:33], v[32:33], v[134:135] op_sel_hi:[1,0]
	v_mfma_f32_16x16x32_bf16 v[28:31], v[140:143], v[44:47], v[28:31]
	global_load_dwordx4 v[140:143], v[6:7], off offset:3088
	v_pk_mul_f32 v[42:43], v[42:43], v[134:135] op_sel_hi:[1,0]
	v_pk_mul_f32 v[40:41], v[40:41], v[134:135] op_sel_hi:[1,0]
	v_mfma_f32_16x16x32_bf16 v[32:35], v[136:139], v[44:47], v[32:35]
	v_mul_f32_e64 v38, v38, v134
	v_mul_f32_e64 v39, v39, v134
	v_pk_mul_f32 v[36:37], v[36:37], v[134:135] op_sel_hi:[1,0]
	s_movk_i32 s0, 0x4000
	s_waitcnt vmcnt(3)
	v_mfma_f32_16x16x32_bf16 v[136:139], v[158:161], v[48:51], 0
	v_add_co_u32_e32 v6, vcc, s0, v202
	s_movk_i32 s0, 0x3000
	s_waitcnt vmcnt(1)
	v_mfma_f32_16x16x32_bf16 v[162:165], v[52:55], v[48:51], 0
	v_addc_co_u32_e32 v7, vcc, 0, v203, vcc
	v_add_co_u32_e32 v172, vcc, s0, v202
	v_mfma_f32_16x16x32_bf16 v[136:139], v[60:63], v[64:67], v[136:139]
	s_nop 0
	v_addc_co_u32_e32 v173, vcc, 0, v203, vcc
	global_load_dwordx4 v[168:171], v[6:7], off offset:-4096
	global_load_dwordx4 v[176:179], v[6:7], off offset:512
	s_waitcnt vmcnt(2)
	v_mfma_f32_16x16x32_bf16 v[162:165], v[140:143], v[64:67], v[162:165]
	s_nop 1
	v_max_f32_e32 v71, v137, v137
	v_max_f32_e32 v73, v136, v136
	v_max_f32_e32 v71, v73, v71
	v_max_f32_e32 v73, v139, v139
	v_max_f32_e32 v75, v138, v138
	v_max_f32_e32 v73, v75, v73
	v_max_f32_e32 v75, v165, v165
	v_max_f32_e32 v77, v164, v164
	v_max_f32_e32 v75, v77, v75
	v_max3_f32 v75, v162, v163, v75
	v_max3_f32 v71, v71, v73, v75
	v_mov_b32_e32 v73, v71
	s_nop 1
	v_permlane16_swap_b32_e32 v73, v71
	v_mfma_f32_16x16x32_bf16 v[40:43], v[144:147], v[44:47], v[40:43]
	s_mov_b32 s0, 0x18000
	global_load_dwordx4 v[188:191], v[6:7], off offset:768
	s_waitcnt lgkmcnt(0)
	v_max_f32_e32 v73, v73, v73
	v_max_f32_e32 v71, v71, v73
	v_mov_b32_e32 v73, v71
	s_nop 1
	v_permlane32_swap_b32_e32 v73, v71
	v_mfma_f32_16x16x32_bf16 v[36:39], v[154:157], v[44:47], v[36:39]
	global_load_dwordx4 v[154:157], v[172:173], off offset:512
	s_waitcnt lgkmcnt(0)
	v_max3_f32 v135, v69, v71, v73
	v_sub_f32_e32 v45, v136, v135
	v_mul_f32_e32 v45, 0x3fb8aa3b, v45
	v_exp_f32_e32 v79, v45
	v_sub_f32_e32 v45, v137, v135
	v_mfma_f32_16x16x32_bf16 v[144:147], v[158:161], v[12:15], 0
	v_mul_f32_e32 v45, 0x3fb8aa3b, v45
	v_exp_f32_e32 v77, v45
	v_sub_f32_e32 v45, v138, v135
	v_mul_f32_e32 v45, 0x3fb8aa3b, v45
	v_exp_f32_e32 v75, v45
	v_sub_f32_e32 v45, v139, v135
	global_load_dwordx4 v[136:139], v[172:173], off offset:256
	v_mfma_f32_16x16x32_bf16 v[60:63], v[60:63], v[8:11], v[144:147]
	v_mul_f32_e32 v45, 0x3fb8aa3b, v45
	v_exp_f32_e32 v73, v45
	v_sub_f32_e32 v45, v162, v135
	global_load_dwordx4 v[144:147], v[172:173], off offset:768
	v_mul_f32_e32 v45, 0x3fb8aa3b, v45
	v_exp_f32_e32 v71, v45
	v_sub_f32_e32 v45, v163, v135
	v_mul_f32_e32 v45, 0x3fb8aa3b, v45
	v_sub_f32_e32 v44, v69, v135
	v_exp_f32_e32 v69, v45
	v_sub_f32_e32 v45, v164, v135
	v_mul_f32_e32 v45, 0x3fb8aa3b, v45
	v_exp_f32_e32 v115, v45
	v_sub_f32_e32 v45, v165, v135
	v_mul_f32_e32 v45, 0x3fb8aa3b, v45
	v_mfma_f32_16x16x32_bf16 v[52:55], v[52:55], v[12:15], 0
	v_mul_f32_e32 v44, 0x3fb8aa3b, v44
	v_exp_f32_e32 v121, v45
	v_exp_f32_e32 v120, v44
	v_cvt_pk_bf16_f32 v44, v79, v77
	v_cvt_pk_bf16_f32 v45, v75, v73
	v_mfma_f32_16x16x32_bf16 v[52:55], v[140:143], v[8:11], v[52:55]
	v_cvt_pk_bf16_f32 v46, v71, v69
	v_cvt_pk_bf16_f32 v47, v115, v121
	v_max_f32_e32 v119, v61, v61
	v_max_f32_e32 v123, v60, v60
	v_max_f32_e32 v119, v123, v119
	v_max_f32_e32 v123, v63, v63
	v_max_f32_e32 v125, v62, v62
	v_max_f32_e32 v123, v125, v123
	v_max_f32_e32 v125, v55, v55
	v_max_f32_e32 v127, v54, v54
	v_max_f32_e32 v125, v127, v125
	v_max3_f32 v125, v52, v53, v125
	v_max3_f32 v119, v119, v123, v125
	v_mov_b32_e32 v123, v119
	s_nop 1
	v_permlane16_swap_b32_e32 v123, v119
	v_pk_mul_f32 v[58:59], v[58:59], v[120:121] op_sel_hi:[1,0]
	v_pk_mul_f32 v[56:57], v[56:57], v[120:121] op_sel_hi:[1,0]
	v_pk_mul_f32 v[18:19], v[18:19], v[120:121] op_sel_hi:[1,0]
	v_pk_mul_f32 v[16:17], v[16:17], v[120:121] op_sel_hi:[1,0]
	s_waitcnt lgkmcnt(0)
	v_max_f32_e32 v123, v123, v123
	v_max_f32_e32 v119, v119, v123
	v_mov_b32_e32 v123, v119
	s_nop 1
	v_permlane32_swap_b32_e32 v123, v119
	v_pk_mul_f32 v[26:27], v[26:27], v[120:121] op_sel_hi:[1,0]
	v_pk_mul_f32 v[24:25], v[24:25], v[120:121] op_sel_hi:[1,0]
	v_pk_mul_f32 v[22:23], v[22:23], v[120:121] op_sel_hi:[1,0]
	v_pk_mul_f32 v[20:21], v[20:21], v[120:121] op_sel_hi:[1,0]
	s_waitcnt lgkmcnt(0)
	v_max3_f32 v152, v117, v119, v123
	s_waitcnt vmcnt(5)
	v_mfma_f32_16x16x32_bf16 v[56:59], v[168:171], v[44:47], v[56:59]
	v_add_co_u32_e32 v162, vcc, s0, v204
	s_mov_b32 s0, 0x1e000
	s_waitcnt vmcnt(1)
	v_mfma_f32_16x16x32_bf16 v[16:19], v[136:139], v[44:47], v[16:19]
	v_addc_co_u32_e32 v163, vcc, 0, v205, vcc
	global_load_dwordx4 v[158:161], v[162:163], off offset:16
	v_mfma_f32_16x16x32_bf16 v[24:27], v[154:157], v[44:47], v[24:27]
	s_waitcnt vmcnt(1)
	v_mfma_f32_16x16x32_bf16 v[20:23], v[144:147], v[44:47], v[20:23]
	v_sub_f32_e32 v45, v60, v152
	v_mul_f32_e32 v45, 0x3fb8aa3b, v45
	v_exp_f32_e32 v133, v45
	v_sub_f32_e32 v45, v61, v152
	v_mul_f32_e32 v45, 0x3fb8aa3b, v45
	v_exp_f32_e32 v131, v45
	v_sub_f32_e32 v45, v62, v152
	v_mul_f32_e32 v45, 0x3fb8aa3b, v45
	v_exp_f32_e32 v129, v45
	v_sub_f32_e32 v45, v63, v152
	v_mul_f32_e32 v45, 0x3fb8aa3b, v45
	v_exp_f32_e32 v127, v45
	v_sub_f32_e32 v45, v52, v152
	v_mul_f32_e32 v45, 0x3fb8aa3b, v45
	v_exp_f32_e32 v125, v45
	v_sub_f32_e32 v45, v53, v152
	v_mul_f32_e32 v45, 0x3fb8aa3b, v45
	v_exp_f32_e32 v123, v45
	v_sub_f32_e32 v45, v54, v152
	v_mul_f32_e32 v45, 0x3fb8aa3b, v45
	v_exp_f32_e32 v119, v45
	v_sub_f32_e32 v45, v55, v152
	v_sub_f32_e32 v44, v117, v152
	v_mul_f32_e32 v45, 0x3fb8aa3b, v45
	v_mul_f32_e32 v44, 0x3fb8aa3b, v44
	v_exp_f32_e32 v211, v45
	v_exp_f32_e32 v150, v44
	v_cvt_pk_bf16_f32 v44, v133, v131
	v_cvt_pk_bf16_f32 v45, v129, v127
	v_cvt_pk_bf16_f32 v46, v125, v123
	v_cvt_pk_bf16_f32 v47, v119, v211
	global_load_dwordx4 v[52:55], v[162:163], off
	global_load_dwordx4 v[60:63], v[162:163], off offset:3072
	v_pk_mul_f32 v[30:31], v[30:31], v[150:151] op_sel_hi:[1,0]
	global_load_dwordx4 v[162:165], v[162:163], off offset:3088
	v_pk_mul_f32 v[28:29], v[28:29], v[150:151] op_sel_hi:[1,0]
	s_waitcnt vmcnt(1)
	v_mfma_f32_16x16x32_bf16 v[140:143], v[60:63], v[48:51], 0
	v_mul_f32_e64 v34, v34, v150
	v_mul_f32_e64 v35, v35, v150
	v_pk_mul_f32 v[32:33], v[32:33], v[150:151] op_sel_hi:[1,0]
	v_pk_mul_f32 v[42:43], v[42:43], v[150:151] op_sel_hi:[1,0]
	v_mfma_f32_16x16x32_bf16 v[28:31], v[136:139], v[44:47], v[28:31]
	v_mul_f32_e64 v40, v40, v150
	v_mul_f32_e64 v41, v41, v150
	v_pk_mul_f32 v[38:39], v[38:39], v[150:151] op_sel_hi:[1,0]
	v_pk_mul_f32 v[36:37], v[36:37], v[150:151] op_sel_hi:[1,0]
	v_mfma_f32_16x16x32_bf16 v[136:139], v[52:55], v[48:51], 0
	v_mfma_f32_16x16x32_bf16 v[136:139], v[158:161], v[64:67], v[136:139]
	s_waitcnt vmcnt(0)
	v_mfma_f32_16x16x32_bf16 v[172:175], v[162:165], v[64:67], v[140:143]
	v_mfma_f32_16x16x32_bf16 v[32:35], v[168:171], v[44:47], v[32:35]
	s_nop 4
	v_max_f32_e32 v117, v137, v137
	v_max_f32_e32 v140, v136, v136
	v_max_f32_e32 v117, v140, v117
	v_max_f32_e32 v140, v139, v139
	v_max_f32_e32 v141, v138, v138
	v_max_f32_e32 v140, v141, v140
	v_max_f32_e32 v141, v175, v175
	v_max_f32_e32 v142, v174, v174
	v_max_f32_e32 v141, v142, v141
	v_max3_f32 v141, v172, v173, v141
	v_max3_f32 v117, v117, v140, v141
	v_mov_b32_e32 v140, v117
	s_nop 1
	v_permlane16_swap_b32_e32 v140, v117
	v_mfma_f32_16x16x32_bf16 v[40:43], v[154:157], v[44:47], v[40:43]
	global_load_dwordx4 v[168:171], v[6:7], off
	s_waitcnt lgkmcnt(0)
	v_max_f32_e32 v140, v140, v140
	v_max_f32_e32 v117, v117, v140
	v_mov_b32_e32 v140, v117
	s_nop 1
	v_permlane32_swap_b32_e32 v140, v117
	v_mfma_f32_16x16x32_bf16 v[36:39], v[144:147], v[44:47], v[36:39]
	s_waitcnt lgkmcnt(0)
	v_max3_f32 v117, v135, v117, v140
	v_sub_f32_e32 v45, v136, v117
	v_mul_f32_e32 v45, 0x3fb8aa3b, v45
	v_exp_f32_e32 v209, v45
	v_sub_f32_e32 v45, v137, v117
	v_mul_f32_e32 v45, 0x3fb8aa3b, v45
	v_exp_f32_e32 v210, v45
	v_sub_f32_e32 v45, v138, v117
	v_mul_f32_e32 v45, 0x3fb8aa3b, v45
	v_exp_f32_e32 v146, v45
	v_sub_f32_e32 v45, v139, v117
	v_mul_f32_e32 v45, 0x3fb8aa3b, v45
	v_exp_f32_e32 v144, v45
	v_sub_f32_e32 v45, v172, v117
	v_mul_f32_e32 v45, 0x3fb8aa3b, v45
	v_exp_f32_e32 v142, v45
	v_sub_f32_e32 v45, v173, v117
	v_mul_f32_e32 v45, 0x3fb8aa3b, v45
	v_exp_f32_e32 v140, v45
	v_sub_f32_e32 v45, v174, v117
	v_mul_f32_e32 v45, 0x3fb8aa3b, v45
	v_exp_f32_e32 v138, v45
	v_sub_f32_e32 v45, v175, v117
	global_load_dwordx4 v[172:175], v[6:7], off offset:256
	v_mfma_f32_16x16x32_bf16 v[52:55], v[52:55], v[12:15], 0
	v_sub_f32_e32 v44, v135, v117
	v_mul_f32_e32 v45, 0x3fb8aa3b, v45
	v_mul_f32_e32 v44, 0x3fb8aa3b, v44
	v_mfma_f32_16x16x32_bf16 v[60:63], v[60:63], v[12:15], 0
	v_exp_f32_e32 v136, v45
	v_exp_f32_e32 v148, v44
	v_mfma_f32_16x16x32_bf16 v[52:55], v[158:161], v[8:11], v[52:55]
	v_cvt_pk_bf16_f32 v44, v209, v210
	v_cvt_pk_bf16_f32 v45, v146, v144
	v_mfma_f32_16x16x32_bf16 v[60:63], v[162:165], v[8:11], v[60:63]
	v_cvt_pk_bf16_f32 v46, v142, v140
	v_cvt_pk_bf16_f32 v47, v138, v136
	s_nop 2
	v_max_f32_e32 v135, v53, v53
	v_max_f32_e32 v137, v52, v52
	v_max_f32_e32 v135, v137, v135
	v_max_f32_e32 v137, v55, v55
	v_max_f32_e32 v139, v54, v54
	v_max_f32_e32 v137, v139, v137
	v_max_f32_e32 v139, v63, v63
	v_max_f32_e32 v141, v62, v62
	v_max_f32_e32 v139, v141, v139
	v_max3_f32 v139, v60, v61, v139
	v_max3_f32 v135, v135, v137, v139
	v_mov_b32_e32 v137, v135
	s_nop 1
	v_permlane16_swap_b32_e32 v137, v135
	v_pk_mul_f32 v[58:59], v[58:59], v[148:149] op_sel_hi:[1,0]
	v_pk_mul_f32 v[56:57], v[56:57], v[148:149] op_sel_hi:[1,0]
	v_pk_mul_f32 v[18:19], v[18:19], v[148:149] op_sel_hi:[1,0]
	v_pk_mul_f32 v[16:17], v[16:17], v[148:149] op_sel_hi:[1,0]
	s_waitcnt lgkmcnt(0)
	v_max_f32_e32 v137, v137, v137
	v_max_f32_e32 v135, v135, v137
	v_mov_b32_e32 v137, v135
	s_nop 1
	v_permlane32_swap_b32_e32 v137, v135
	v_pk_mul_f32 v[26:27], v[26:27], v[148:149] op_sel_hi:[1,0]
	v_pk_mul_f32 v[24:25], v[24:25], v[148:149] op_sel_hi:[1,0]
	v_pk_mul_f32 v[22:23], v[22:23], v[148:149] op_sel_hi:[1,0]
	v_pk_mul_f32 v[20:21], v[20:21], v[148:149] op_sel_hi:[1,0]
	s_waitcnt lgkmcnt(0)
	v_max3_f32 v135, v152, v135, v137
	s_waitcnt vmcnt(1)
	v_mfma_f32_16x16x32_bf16 v[56:59], v[168:171], v[44:47], v[56:59]
	v_add_co_u32_e32 v6, vcc, s0, v204
	s_movk_i32 s0, 0x5000
	s_waitcnt vmcnt(0)
	v_mfma_f32_16x16x32_bf16 v[16:19], v[172:175], v[44:47], v[16:19]
	v_addc_co_u32_e32 v7, vcc, 0, v205, vcc
	global_load_dwordx4 v[194:197], v[6:7], off
	v_mfma_f32_16x16x32_bf16 v[24:27], v[176:179], v[44:47], v[24:27]
	v_add_co_u32_e32 v184, vcc, s1, v202
	v_mfma_f32_16x16x32_bf16 v[20:23], v[188:191], v[44:47], v[20:23]
	v_sub_f32_e32 v45, v52, v135
	v_mul_f32_e32 v45, 0x3fb8aa3b, v45
	v_exp_f32_e32 v213, v45
	v_sub_f32_e32 v45, v53, v135
	v_mul_f32_e32 v45, 0x3fb8aa3b, v45
	v_exp_f32_e32 v214, v45
	v_sub_f32_e32 v45, v54, v135
	v_mul_f32_e32 v45, 0x3fb8aa3b, v45
	v_exp_f32_e32 v164, v45
	v_sub_f32_e32 v45, v55, v135
	v_mul_f32_e32 v45, 0x3fb8aa3b, v45
	v_exp_f32_e32 v162, v45
	v_sub_f32_e32 v45, v60, v135
	v_mul_f32_e32 v45, 0x3fb8aa3b, v45
	v_exp_f32_e32 v160, v45
	v_sub_f32_e32 v45, v61, v135
	v_mul_f32_e32 v45, 0x3fb8aa3b, v45
	v_exp_f32_e32 v158, v45
	v_sub_f32_e32 v45, v62, v135
	v_mul_f32_e32 v45, 0x3fb8aa3b, v45
	v_exp_f32_e32 v156, v45
	v_sub_f32_e32 v45, v63, v135
	v_sub_f32_e32 v44, v152, v135
	v_mul_f32_e32 v45, 0x3fb8aa3b, v45
	v_mul_f32_e32 v44, 0x3fb8aa3b, v44
	v_exp_f32_e32 v154, v45
	v_exp_f32_e32 v166, v44
	v_cvt_pk_bf16_f32 v44, v213, v214
	v_cvt_pk_bf16_f32 v45, v164, v162
	v_cvt_pk_bf16_f32 v46, v160, v158
	v_cvt_pk_bf16_f32 v47, v156, v154
	global_load_dwordx4 v[52:55], v[6:7], off offset:3072
	global_load_dwordx4 v[60:63], v[6:7], off offset:16
	v_pk_mul_f32 v[30:31], v[30:31], v[166:167] op_sel_hi:[1,0]
	v_pk_mul_f32 v[28:29], v[28:29], v[166:167] op_sel_hi:[1,0]
	v_pk_mul_f32 v[34:35], v[34:35], v[166:167] op_sel_hi:[1,0]
	v_pk_mul_f32 v[32:33], v[32:33], v[166:167] op_sel_hi:[1,0]
	v_mfma_f32_16x16x32_bf16 v[28:31], v[172:175], v[44:47], v[28:31]
	global_load_dwordx4 v[172:175], v[6:7], off offset:3088
	v_pk_mul_f32 v[42:43], v[42:43], v[166:167] op_sel_hi:[1,0]
	v_pk_mul_f32 v[40:41], v[40:41], v[166:167] op_sel_hi:[1,0]
	v_mfma_f32_16x16x32_bf16 v[32:35], v[168:171], v[44:47], v[32:35]
	v_mul_f32_e64 v38, v38, v166
	v_mul_f32_e64 v39, v39, v166
	v_pk_mul_f32 v[36:37], v[36:37], v[166:167] op_sel_hi:[1,0]
	v_addc_co_u32_e32 v185, vcc, 0, v203, vcc
	s_waitcnt vmcnt(3)
	v_mfma_f32_16x16x32_bf16 v[168:171], v[194:197], v[48:51], 0
	global_load_dwordx4 v[216:219], v[184:185], off offset:-4096
	s_waitcnt vmcnt(3)
	v_mfma_f32_16x16x32_bf16 v[198:201], v[52:55], v[48:51], 0
	s_waitcnt vmcnt(2)
	v_mfma_f32_16x16x32_bf16 v[168:171], v[60:63], v[64:67], v[168:171]
	s_waitcnt vmcnt(1)
	v_mfma_f32_16x16x32_bf16 v[198:201], v[172:175], v[64:67], v[198:201]
	v_mfma_f32_16x16x32_bf16 v[40:43], v[176:179], v[44:47], v[40:43]
	s_nop 4
	v_max_f32_e32 v6, v169, v169
	v_max_f32_e32 v7, v168, v168
	v_max_f32_e32 v6, v7, v6
	v_max_f32_e32 v7, v171, v171
	v_max_f32_e32 v137, v170, v170
	v_max_f32_e32 v7, v137, v7
	v_max_f32_e32 v137, v201, v201
	v_max_f32_e32 v139, v200, v200
	v_max_f32_e32 v137, v139, v137
	v_max3_f32 v137, v198, v199, v137
	v_max3_f32 v7, v6, v7, v137
	v_mov_b32_e32 v137, v7
	s_nop 1
	v_permlane16_swap_b32_e32 v137, v7
	v_mfma_f32_16x16x32_bf16 v[36:39], v[188:191], v[44:47], v[36:39]
	v_add_co_u32_e32 v6, vcc, s0, v202
	s_mov_b32 s0, 0x24000
	s_waitcnt lgkmcnt(0)
	v_max_f32_e32 v137, v137, v137
	v_max_f32_e32 v137, v7, v137
	v_mov_b32_e32 v139, v137
	s_nop 1
	v_permlane32_swap_b32_e32 v139, v137
	v_mfma_f32_16x16x32_bf16 v[176:179], v[194:197], v[12:15], 0
	v_addc_co_u32_e32 v7, vcc, 0, v203, vcc
	global_load_dwordx4 v[188:191], v[6:7], off offset:512
	s_waitcnt lgkmcnt(0)
	v_max3_f32 v180, v117, v137, v139
	v_sub_f32_e32 v45, v168, v180
	v_mul_f32_e32 v45, 0x3fb8aa3b, v45
	v_exp_f32_e32 v147, v45
	v_sub_f32_e32 v45, v169, v180
	v_mul_f32_e32 v45, 0x3fb8aa3b, v45
	v_exp_f32_e32 v145, v45
	v_sub_f32_e32 v45, v170, v180
	v_mul_f32_e32 v45, 0x3fb8aa3b, v45
	v_exp_f32_e32 v143, v45
	v_sub_f32_e32 v45, v171, v180
	global_load_dwordx4 v[168:171], v[6:7], off offset:256
	v_mfma_f32_16x16x32_bf16 v[60:63], v[60:63], v[8:11], v[176:179]
	v_mul_f32_e32 v45, 0x3fb8aa3b, v45
	v_exp_f32_e32 v141, v45
	v_sub_f32_e32 v45, v198, v180
	global_load_dwordx4 v[176:179], v[6:7], off offset:768
	v_mul_f32_e32 v45, 0x3fb8aa3b, v45
	v_exp_f32_e32 v139, v45
	v_sub_f32_e32 v45, v199, v180
	v_mul_f32_e32 v45, 0x3fb8aa3b, v45
	v_exp_f32_e32 v137, v45
	v_sub_f32_e32 v45, v200, v180
	v_mul_f32_e32 v45, 0x3fb8aa3b, v45
	v_sub_f32_e32 v44, v117, v180
	v_exp_f32_e32 v117, v45
	v_sub_f32_e32 v45, v201, v180
	v_mfma_f32_16x16x32_bf16 v[52:55], v[52:55], v[12:15], 0
	v_mul_f32_e32 v45, 0x3fb8aa3b, v45
	v_mul_f32_e32 v44, 0x3fb8aa3b, v44
	v_exp_f32_e32 v212, v45
	v_exp_f32_e32 v152, v44
	v_cvt_pk_bf16_f32 v44, v147, v145
	v_mfma_f32_16x16x32_bf16 v[52:55], v[172:175], v[8:11], v[52:55]
	v_cvt_pk_bf16_f32 v45, v143, v141
	v_cvt_pk_bf16_f32 v46, v139, v137
	v_max_f32_e32 v6, v61, v61
	v_max_f32_e32 v7, v60, v60
	v_cvt_pk_bf16_f32 v47, v117, v212
	v_max_f32_e32 v6, v7, v6
	v_max_f32_e32 v7, v63, v63
	v_max_f32_e32 v155, v62, v62
	v_max_f32_e32 v7, v155, v7
	v_max_f32_e32 v155, v55, v55
	v_max_f32_e32 v157, v54, v54
	v_max_f32_e32 v155, v157, v155
	v_max3_f32 v155, v52, v53, v155
	v_max3_f32 v7, v6, v7, v155
	v_mov_b32_e32 v155, v7
	s_nop 1
	v_permlane16_swap_b32_e32 v155, v7
	v_pk_mul_f32 v[58:59], v[58:59], v[152:153] op_sel_hi:[1,0]
	v_pk_mul_f32 v[56:57], v[56:57], v[152:153] op_sel_hi:[1,0]
	v_pk_mul_f32 v[18:19], v[18:19], v[152:153] op_sel_hi:[1,0]
	v_pk_mul_f32 v[16:17], v[16:17], v[152:153] op_sel_hi:[1,0]
	s_waitcnt lgkmcnt(0)
	v_max_f32_e32 v155, v155, v155
	v_max_f32_e32 v155, v7, v155
	v_mov_b32_e32 v157, v155
	s_nop 1
	v_permlane32_swap_b32_e32 v157, v155
	v_pk_mul_f32 v[26:27], v[26:27], v[152:153] op_sel_hi:[1,0]
	v_pk_mul_f32 v[24:25], v[24:25], v[152:153] op_sel_hi:[1,0]
	v_pk_mul_f32 v[22:23], v[22:23], v[152:153] op_sel_hi:[1,0]
	v_pk_mul_f32 v[20:21], v[20:21], v[152:153] op_sel_hi:[1,0]
	s_waitcnt lgkmcnt(0)
	v_max3_f32 v173, v135, v155, v157
	s_waitcnt vmcnt(3)
	v_mfma_f32_16x16x32_bf16 v[56:59], v[216:219], v[44:47], v[56:59]
	v_add_co_u32_e32 v6, vcc, s0, v204
	s_mov_b32 s0, 0x2a000
	s_waitcnt vmcnt(1)
	v_mfma_f32_16x16x32_bf16 v[16:19], v[168:171], v[44:47], v[16:19]
	v_addc_co_u32_e32 v7, vcc, 0, v205, vcc
	global_load_dwordx4 v[194:197], v[6:7], off offset:16
	v_mfma_f32_16x16x32_bf16 v[24:27], v[188:191], v[44:47], v[24:27]
	global_load_dwordx4 v[198:201], v[6:7], off offset:3088
	v_add_co_u32_e32 v204, vcc, s0, v204
	s_waitcnt vmcnt(2)
	v_mfma_f32_16x16x32_bf16 v[20:23], v[176:179], v[44:47], v[20:23]
	v_sub_f32_e32 v45, v60, v173
	v_mul_f32_e32 v45, 0x3fb8aa3b, v45
	v_exp_f32_e32 v165, v45
	v_sub_f32_e32 v45, v61, v173
	v_mul_f32_e32 v45, 0x3fb8aa3b, v45
	v_exp_f32_e32 v163, v45
	v_sub_f32_e32 v45, v62, v173
	v_mul_f32_e32 v45, 0x3fb8aa3b, v45
	v_exp_f32_e32 v161, v45
	v_sub_f32_e32 v45, v63, v173
	v_mul_f32_e32 v45, 0x3fb8aa3b, v45
	v_exp_f32_e32 v159, v45
	v_sub_f32_e32 v45, v52, v173
	v_mul_f32_e32 v45, 0x3fb8aa3b, v45
	v_exp_f32_e32 v157, v45
	v_sub_f32_e32 v45, v53, v173
	v_mul_f32_e32 v45, 0x3fb8aa3b, v45
	v_exp_f32_e32 v155, v45
	v_sub_f32_e32 v45, v54, v173
	v_mul_f32_e32 v45, 0x3fb8aa3b, v45
	v_sub_f32_e32 v44, v135, v173
	v_exp_f32_e32 v135, v45
	v_sub_f32_e32 v45, v55, v173
	v_mul_f32_e32 v45, 0x3fb8aa3b, v45
	v_mul_f32_e32 v44, 0x3fb8aa3b, v44
	v_exp_f32_e32 v215, v45
	v_exp_f32_e32 v192, v44
	v_cvt_pk_bf16_f32 v44, v165, v163
	v_cvt_pk_bf16_f32 v45, v161, v159
	v_cvt_pk_bf16_f32 v46, v157, v155
	v_cvt_pk_bf16_f32 v47, v135, v215
	v_pk_mul_f32 v[30:31], v[30:31], v[192:193] op_sel_hi:[1,0]
	v_pk_mul_f32 v[28:29], v[28:29], v[192:193] op_sel_hi:[1,0]
	global_load_dwordx4 v[60:63], v[6:7], off
	v_pk_mul_f32 v[34:35], v[34:35], v[192:193] op_sel_hi:[1,0]
	v_mfma_f32_16x16x32_bf16 v[220:223], v[168:171], v[44:47], v[28:31]
	v_mul_f32_e64 v32, v32, v192
	v_mul_f32_e64 v33, v33, v192
	v_pk_mul_f32 v[38:39], v[38:39], v[192:193] op_sel_hi:[1,0]
	v_pk_mul_f32 v[36:37], v[36:37], v[192:193] op_sel_hi:[1,0]
	global_load_dwordx4 v[28:31], v[6:7], off offset:3072
	v_mfma_f32_16x16x32_bf16 v[52:55], v[216:219], v[44:47], v[32:35]
	v_mul_f32_e64 v42, v42, v192
	v_mul_f32_e64 v43, v43, v192
	v_pk_mul_f32 v[40:41], v[40:41], v[192:193] op_sel_hi:[1,0]
	v_addc_co_u32_e32 v205, vcc, 0, v205, vcc
	s_waitcnt vmcnt(1)
	v_mfma_f32_16x16x32_bf16 v[32:35], v[60:63], v[48:51], 0
	s_movk_i32 s0, 0x7000
	s_waitcnt vmcnt(0)
	v_mfma_f32_16x16x32_bf16 v[168:171], v[28:31], v[48:51], 0
	v_mfma_f32_16x16x32_bf16 v[32:35], v[194:197], v[64:67], v[32:35]
	v_mfma_f32_16x16x32_bf16 v[238:241], v[198:201], v[64:67], v[168:171]
	v_mfma_f32_16x16x32_bf16 v[250:253], v[176:179], v[44:47], v[36:39]
	s_nop 5
	v_max_f32_e32 v6, v33, v33
	v_max_f32_e32 v7, v32, v32
	v_max_f32_e32 v168, v241, v241
	v_max_f32_e32 v169, v240, v240
	v_max_f32_e32 v6, v7, v6
	v_max_f32_e32 v7, v35, v35
	v_max_f32_e32 v172, v34, v34
	v_max_f32_e32 v168, v169, v168
	v_max_f32_e32 v7, v172, v7
	v_max3_f32 v168, v238, v239, v168
	v_max3_f32 v6, v6, v7, v168
	v_mov_b32_e32 v7, v6
	s_nop 1
	v_permlane16_swap_b32_e32 v7, v6
	v_mfma_f32_16x16x32_bf16 v[246:249], v[188:191], v[44:47], v[40:43]
	s_waitcnt lgkmcnt(0)
	v_max_f32_e32 v7, v7, v7
	v_max_f32_e32 v6, v6, v7
	v_mov_b32_e32 v7, v6
	s_nop 1
	v_permlane32_swap_b32_e32 v7, v6
	s_waitcnt lgkmcnt(0)
	v_max3_f32 v6, v180, v6, v7
	v_sub_f32_e32 v32, v32, v6
	v_mul_f32_e32 v32, 0x3fb8aa3b, v32
	v_exp_f32_e32 v216, v32
	v_sub_f32_e32 v32, v33, v6
	v_mul_f32_e32 v32, 0x3fb8aa3b, v32
	v_exp_f32_e32 v217, v32
	v_sub_f32_e32 v32, v34, v6
	v_mul_f32_e32 v32, 0x3fb8aa3b, v32
	v_exp_f32_e32 v176, v32
	v_sub_f32_e32 v32, v35, v6
	v_mul_f32_e32 v32, 0x3fb8aa3b, v32
	v_exp_f32_e32 v174, v32
	v_sub_f32_e32 v32, v238, v6
	v_mul_f32_e32 v32, 0x3fb8aa3b, v32
	v_sub_f32_e32 v7, v180, v6
	v_exp_f32_e32 v172, v32
	v_sub_f32_e32 v32, v239, v6
	v_mul_f32_e32 v7, 0x3fb8aa3b, v7
	v_mul_f32_e32 v32, 0x3fb8aa3b, v32
	v_exp_f32_e32 v170, v32
	v_sub_f32_e32 v32, v240, v6
	v_exp_f32_e32 v180, v7
	v_mul_f32_e32 v32, 0x3fb8aa3b, v32
	v_exp_f32_e32 v168, v32
	v_sub_f32_e32 v32, v241, v6
	v_mul_f32_e32 v32, 0x3fb8aa3b, v32
	v_exp_f32_e32 v178, v32
	v_pk_mul_f32 v[34:35], v[58:59], v[180:181] op_sel_hi:[1,0]
	v_pk_mul_f32 v[32:33], v[56:57], v[180:181] op_sel_hi:[1,0]
	global_load_dwordx4 v[56:59], v[184:185], off
	global_load_dwordx4 v[238:241], v[184:185], off offset:256
	v_cvt_pk_bf16_f32 v44, v216, v217
	v_cvt_pk_bf16_f32 v45, v176, v174
	v_cvt_pk_bf16_f32 v46, v172, v170
	v_pk_mul_f32 v[18:19], v[18:19], v[180:181] op_sel_hi:[1,0]
	v_pk_mul_f32 v[16:17], v[16:17], v[180:181] op_sel_hi:[1,0]
	v_cvt_pk_bf16_f32 v47, v168, v178
	v_pk_mul_f32 v[26:27], v[26:27], v[180:181] op_sel_hi:[1,0]
	v_pk_mul_f32 v[24:25], v[24:25], v[180:181] op_sel_hi:[1,0]
	s_waitcnt vmcnt(0)
	v_mfma_f32_16x16x32_bf16 v[36:39], v[238:241], v[44:47], v[16:19]
	s_nop 2
	global_load_dwordx4 v[16:19], v[184:185], off offset:512
	v_pk_mul_f32 v[22:23], v[22:23], v[180:181] op_sel_hi:[1,0]
	global_load_dwordx4 v[184:187], v[184:185], off offset:768
	v_pk_mul_f32 v[20:21], v[20:21], v[180:181] op_sel_hi:[1,0]
	v_mfma_f32_16x16x32_bf16 v[32:35], v[56:59], v[44:47], v[32:35]
	s_waitcnt vmcnt(1)
	v_mfma_f32_16x16x32_bf16 v[40:43], v[16:19], v[44:47], v[24:27]
	s_waitcnt vmcnt(0)
	v_mfma_f32_16x16x32_bf16 v[44:47], v[184:187], v[44:47], v[20:23]
	v_mfma_f32_16x16x32_bf16 v[20:23], v[60:63], v[12:15], 0
	global_load_dwordx4 v[60:63], v[204:205], off
	v_mfma_f32_16x16x32_bf16 v[24:27], v[28:31], v[12:15], 0
	v_mfma_f32_16x16x32_bf16 v[20:23], v[194:197], v[8:11], v[20:23]
	v_mfma_f32_16x16x32_bf16 v[24:27], v[198:201], v[8:11], v[24:27]
	s_nop 6
	v_max_f32_e32 v7, v21, v21
	v_max_f32_e32 v28, v20, v20
	v_max_f32_e32 v7, v28, v7
	v_max_f32_e32 v28, v23, v23
	v_max_f32_e32 v29, v22, v22
	v_max_f32_e32 v28, v29, v28
	v_max_f32_e32 v29, v27, v27
	v_max_f32_e32 v30, v26, v26
	v_max_f32_e32 v29, v30, v29
	v_max3_f32 v29, v24, v25, v29
	v_max3_f32 v7, v7, v28, v29
	v_mov_b32_e32 v28, v7
	s_nop 1
	v_permlane16_swap_b32_e32 v28, v7
	s_waitcnt lgkmcnt(0)
	v_max_f32_e32 v28, v28, v28
	v_max_f32_e32 v7, v7, v28
	v_mov_b32_e32 v28, v7
	s_nop 1
	v_permlane32_swap_b32_e32 v28, v7
	s_waitcnt lgkmcnt(0)
	v_max3_f32 v189, v173, v7, v28
	v_sub_f32_e32 v7, v173, v189
	v_mul_f32_e32 v7, 0x3fb8aa3b, v7
	v_exp_f32_e32 v182, v7
	v_sub_f32_e32 v7, v20, v189
	v_sub_f32_e32 v20, v21, v189
	v_mul_f32_e32 v7, 0x3fb8aa3b, v7
	v_exp_f32_e32 v218, v7
	v_mul_f32_e32 v7, 0x3fb8aa3b, v20
	v_exp_f32_e32 v219, v7
	v_sub_f32_e32 v21, v22, v189
	v_sub_f32_e32 v22, v23, v189
	v_mul_f32_e32 v7, 0x3fb8aa3b, v21
	v_mul_f32_e32 v20, 0x3fb8aa3b, v22
	v_sub_f32_e32 v23, v24, v189
	v_sub_f32_e32 v24, v25, v189
	v_exp_f32_e32 v188, v20
	v_exp_f32_e32 v190, v7
	v_pk_mul_f32 v[28:29], v[52:53], v[182:183] op_sel_hi:[1,0]
	v_cvt_pk_bf16_f32 v52, v218, v219
	v_mul_f32_e32 v7, 0x3fb8aa3b, v23
	v_mul_f32_e32 v20, 0x3fb8aa3b, v24
	v_exp_f32_e32 v194, v20
	v_exp_f32_e32 v196, v7
	v_sub_f32_e32 v25, v26, v189
	v_sub_f32_e32 v26, v27, v189
	v_pk_mul_f32 v[30:31], v[54:55], v[182:183] op_sel_hi:[1,0]
	v_cvt_pk_bf16_f32 v54, v196, v194
	v_mul_f32_e32 v7, 0x3fb8aa3b, v25
	v_mul_f32_e32 v20, 0x3fb8aa3b, v26
	v_exp_f32_e32 v198, v20
	v_exp_f32_e32 v200, v7
	v_cvt_pk_bf16_f32 v53, v190, v188
	v_cvt_pk_bf16_f32 v55, v200, v198
	v_pk_mul_f32 v[22:23], v[222:223], v[182:183] op_sel_hi:[1,0]
	v_pk_mul_f32 v[20:21], v[220:221], v[182:183] op_sel_hi:[1,0]
	v_mfma_f32_16x16x32_bf16 v[28:31], v[56:59], v[52:55], v[28:31]
	global_load_dwordx4 v[56:59], v[204:205], off offset:3072
	v_mfma_f32_16x16x32_bf16 v[24:27], v[238:241], v[52:55], v[20:23]
	s_nop 2
	v_mul_f32_e64 v22, v248, v182
	v_mul_f32_e64 v23, v249, v182
	v_pk_mul_f32 v[20:21], v[246:247], v[182:183] op_sel_hi:[1,0]
	s_waitcnt vmcnt(0)
	v_mfma_f32_16x16x32_bf16 v[220:223], v[56:59], v[48:51], 0
	v_mfma_f32_16x16x32_bf16 v[20:23], v[16:19], v[52:55], v[20:23]
	v_mul_f32_e64 v18, v252, v182
	v_mul_f32_e64 v19, v253, v182
	v_pk_mul_f32 v[16:17], v[250:251], v[182:183] op_sel_hi:[1,0]
	s_nop 1
	v_mfma_f32_16x16x32_bf16 v[16:19], v[184:187], v[52:55], v[16:19]
	global_load_dwordx4 v[52:55], v[204:205], off offset:16
	v_mfma_f32_16x16x32_bf16 v[184:187], v[60:63], v[48:51], 0
	global_load_dwordx4 v[48:51], v[204:205], off offset:3088
	s_waitcnt vmcnt(1)
	v_mfma_f32_16x16x32_bf16 v[184:187], v[52:55], v[64:67], v[184:187]
	s_nop 7
	v_max_f32_e32 v7, v185, v185
	s_waitcnt vmcnt(0)
	v_mfma_f32_16x16x32_bf16 v[220:223], v[48:51], v[64:67], v[220:223]
	v_max_f32_e32 v64, v184, v184
	v_max_f32_e32 v7, v64, v7
	v_max_f32_e32 v64, v187, v187
	v_max_f32_e32 v65, v186, v186
	v_max_f32_e32 v64, v65, v64
	s_nop 2
	v_max_f32_e32 v65, v223, v223
	v_max_f32_e32 v66, v222, v222
	v_max_f32_e32 v65, v66, v65
	v_max3_f32 v65, v220, v221, v65
	v_max3_f32 v7, v7, v64, v65
	v_mov_b32_e32 v64, v7
	s_nop 1
	v_permlane16_swap_b32_e32 v64, v7
	v_mfma_f32_16x16x32_bf16 v[60:63], v[60:63], v[12:15], 0
	s_waitcnt lgkmcnt(0)
	v_max_f32_e32 v64, v64, v64
	v_max_f32_e32 v7, v7, v64
	v_mov_b32_e32 v64, v7
	s_nop 1
	v_permlane32_swap_b32_e32 v64, v7
	v_mfma_f32_16x16x32_bf16 v[12:15], v[56:59], v[12:15], 0
	s_waitcnt lgkmcnt(0)
	v_max3_f32 v173, v6, v7, v64
	v_sub_f32_e32 v66, v220, v173
	v_add_co_u32_e32 v220, vcc, s0, v202
	v_sub_f32_e32 v65, v221, v173
	s_nop 0
	v_addc_co_u32_e32 v221, vcc, 0, v203, vcc
	global_load_dwordx4 v[56:59], v[220:221], off
	v_sub_f32_e32 v175, v184, v173
	v_sub_f32_e32 v171, v185, v173
	v_sub_f32_e32 v169, v186, v173
	v_sub_f32_e32 v67, v187, v173
	v_sub_f32_e32 v64, v222, v173
	v_sub_f32_e32 v7, v223, v173
	v_sub_f32_e32 v6, v6, v173
	v_mul_f32_e32 v173, 0x3fb8aa3b, v175
	v_mul_f32_e32 v171, 0x3fb8aa3b, v171
	v_exp_f32_e32 v177, v173
	v_exp_f32_e32 v175, v171
	v_mul_f32_e32 v169, 0x3fb8aa3b, v169
	v_mul_f32_e32 v67, 0x3fb8aa3b, v67
	v_exp_f32_e32 v173, v169
	v_exp_f32_e32 v171, v67
	v_mul_f32_e32 v66, 0x3fb8aa3b, v66
	v_mul_f32_e32 v65, 0x3fb8aa3b, v65
	v_exp_f32_e32 v169, v66
	v_exp_f32_e32 v179, v65
	v_mul_f32_e32 v64, 0x3fb8aa3b, v64
	v_mul_f32_e32 v7, 0x3fb8aa3b, v7
	v_mul_f32_e32 v6, 0x3fb8aa3b, v6
	v_exp_f32_e32 v67, v64
	v_exp_f32_e32 v65, v7
	v_exp_f32_e32 v64, v6
	v_cvt_pk_bf16_f32 v184, v177, v175
	v_cvt_pk_bf16_f32 v185, v173, v171
	v_cvt_pk_bf16_f32 v186, v169, v179
	v_mfma_f32_16x16x32_bf16 v[52:55], v[52:55], v[8:11], v[60:63]
	v_cvt_pk_bf16_f32 v187, v67, v65
	v_pk_mul_f32 v[6:7], v[32:33], v[64:65] op_sel_hi:[1,0]
	v_pk_mul_f32 v[204:205], v[46:47], v[64:65] op_sel_hi:[1,0]
	v_mfma_f32_16x16x32_bf16 v[48:51], v[48:51], v[8:11], v[12:15]
	v_mul_f32_e64 v8, v34, v64
	v_mul_f32_e64 v9, v35, v64
	v_pk_mul_f32 v[202:203], v[44:45], v[64:65] op_sel_hi:[1,0]
	global_load_dwordx4 v[44:47], v[220:221], off offset:256
	s_waitcnt vmcnt(1)
	v_mfma_f32_16x16x32_bf16 v[32:35], v[56:59], v[184:187], v[6:9]
	s_nop 2
	v_mul_f32_e64 v8, v38, v64
	v_mul_f32_e64 v9, v39, v64
	v_pk_mul_f32 v[6:7], v[36:37], v[64:65] op_sel_hi:[1,0]
	v_pk_mul_f32 v[38:39], v[42:43], v[64:65] op_sel_hi:[1,0]
	v_pk_mul_f32 v[36:37], v[40:41], v[64:65] op_sel_hi:[1,0]
	global_load_dwordx4 v[40:43], v[220:221], off offset:512
	global_load_dwordx4 v[60:63], v[220:221], off offset:768
	v_max_f32_e32 v14, v53, v53
	v_max_f32_e32 v15, v52, v52
	v_max_f32_e32 v14, v15, v14
	v_max_f32_e32 v15, v55, v55
	v_max_f32_e32 v66, v54, v54
	s_waitcnt vmcnt(2)
	v_mfma_f32_16x16x32_bf16 v[10:13], v[44:47], v[184:187], v[6:9]
	v_max_f32_e32 v15, v66, v15
	v_max_f32_e32 v66, v51, v51
	s_waitcnt vmcnt(1)
	v_mfma_f32_16x16x32_bf16 v[6:9], v[40:43], v[184:187], v[36:39]
	s_waitcnt vmcnt(0)
	v_mfma_f32_16x16x32_bf16 v[36:39], v[60:63], v[184:187], v[202:205]
	v_max_f32_e32 v184, v50, v50
	v_max_f32_e32 v66, v184, v66
	v_max3_f32 v66, v48, v49, v66
	v_max3_f32 v14, v14, v15, v66
	v_mov_b32_e32 v15, v14
	s_nop 1
	v_permlane16_swap_b32_e32 v15, v14
	s_waitcnt lgkmcnt(0)
	v_max_f32_e32 v15, v15, v15
	v_max_f32_e32 v14, v14, v15
	v_mov_b32_e32 v15, v14
	s_nop 1
	v_permlane32_swap_b32_e32 v15, v14
	s_waitcnt lgkmcnt(0)
	v_max3_f32 v14, v189, v14, v15
	v_sub_f32_e32 v52, v52, v14
	v_mul_f32_e32 v52, 0x3fb8aa3b, v52
	v_exp_f32_e32 v191, v52
	v_sub_f32_e32 v52, v53, v14
	v_mul_f32_e32 v52, 0x3fb8aa3b, v52
	v_sub_f32_e32 v15, v189, v14
	v_exp_f32_e32 v189, v52
	v_sub_f32_e32 v52, v54, v14
	v_sub_f32_e32 v48, v48, v14
	v_mul_f32_e32 v52, 0x3fb8aa3b, v52
	v_mul_f32_e32 v48, 0x3fb8aa3b, v48
	v_exp_f32_e32 v197, v52
	v_sub_f32_e32 v52, v55, v14
	v_exp_f32_e32 v201, v48
	v_sub_f32_e32 v48, v49, v14
	v_mul_f32_e32 v52, 0x3fb8aa3b, v52
	v_mul_f32_e32 v48, 0x3fb8aa3b, v48
	v_exp_f32_e32 v195, v52
	v_exp_f32_e32 v199, v48
	v_sub_f32_e32 v48, v50, v14
	v_sub_f32_e32 v14, v51, v14
	v_mul_f32_e32 v48, 0x3fb8aa3b, v48
	v_mul_f32_e32 v14, 0x3fb8aa3b, v14
	v_mul_f32_e32 v15, 0x3fb8aa3b, v15
	v_exp_f32_e32 v53, v48
	v_exp_f32_e32 v51, v14
	v_exp_f32_e32 v50, v15
	v_cvt_pk_bf16_f32 v184, v191, v189
	v_cvt_pk_bf16_f32 v185, v197, v195
	v_cvt_pk_bf16_f32 v186, v201, v199
	v_cvt_pk_bf16_f32 v187, v53, v51
	v_lshl_add_u64 v[14:15], s[6:7], 0, v[0:1]
	v_lshlrev_b32_e32 v0, 11, v89
	v_lshl_add_u64 v[48:49], v[14:15], 0, s[44:45]
	v_lshl_add_u64 v[14:15], s[6:7], 0, v[0:1]
	v_pk_mul_f32 v[22:23], v[22:23], v[50:51] op_sel_hi:[1,0]
	v_pk_mul_f32 v[20:21], v[20:21], v[50:51] op_sel_hi:[1,0]
	v_pk_mul_f32 v[18:19], v[18:19], v[50:51] op_sel_hi:[1,0]
	v_pk_mul_f32 v[16:17], v[16:17], v[50:51] op_sel_hi:[1,0]
	v_add_f32_e32 v0, 0, v218
	v_mfma_f32_16x16x32_bf16 v[20:23], v[40:43], v[184:187], v[20:23]
	v_lshl_add_u64 v[40:41], v[14:15], 0, s[44:45]
	v_pk_mul_f32 v[26:27], v[26:27], v[50:51] op_sel_hi:[1,0]
	v_pk_mul_f32 v[24:25], v[24:25], v[50:51] op_sel_hi:[1,0]
	v_mfma_f32_16x16x32_bf16 v[14:17], v[60:63], v[184:187], v[16:19]
	v_mov_b32_e32 v43, v1
	v_mov_b32_e32 v89, v1
	v_pk_mul_f32 v[30:31], v[30:31], v[50:51] op_sel_hi:[1,0]
	v_add_f32_e32 v18, v219, v0
	v_add_f32_e32 v0, 0, v213
	v_add_f32_e32 v42, v214, v0
	v_add_f32_e32 v0, 0, v207
	v_mfma_f32_16x16x32_bf16 v[24:27], v[44:47], v[184:187], v[24:27]
	v_add_f32_e32 v44, v208, v0
	v_add_f32_e32 v0, 0, v151
	v_add_f32_e32 v0, v153, v0
	v_pk_add_f32 v[46:47], v[112:113], v[0:1]
	v_mov_b32_e32 v45, v1
	v_pk_add_f32 v[46:47], v[110:111], v[46:47]
	v_pk_mul_f32 v[28:29], v[28:29], v[50:51] op_sel_hi:[1,0]
	v_pk_add_f32 v[46:47], v[108:109], v[46:47]
	s_nop 0
	v_pk_add_f32 v[46:47], v[106:107], v[46:47]
	v_mfma_f32_16x16x32_bf16 v[28:31], v[56:59], v[184:187], v[28:31]
	v_add_f32_e64 v46, v104, v46
	v_add_f32_e64 v47, v105, v47
	v_pk_add_f32 v[46:47], v[102:103], v[46:47]
	s_nop 0
	v_pk_add_f32 v[4:5], v[4:5], v[46:47]
	s_nop 0
	v_add_f32_e32 v0, v5, v206
	v_fmac_f32_e32 v0, v4, v118
	v_pk_add_f32 v[4:5], v[132:133], v[44:45]
	v_mul_f32_e32 v118, v0, v134
	v_pk_add_f32 v[4:5], v[130:131], v[4:5]
	s_nop 0
	v_pk_add_f32 v[4:5], v[128:129], v[4:5]
	s_nop 0
	v_pk_add_f32 v[4:5], v[126:127], v[4:5]
	s_nop 0
	v_pk_add_f32 v[4:5], v[124:125], v[4:5]
	s_nop 0
	v_pk_add_f32 v[4:5], v[122:123], v[4:5]
	s_nop 0
	v_pk_add_f32 v[4:5], v[118:119], v[4:5]
	s_nop 0
	v_add_f32_e32 v0, v5, v211
	v_fmac_f32_e32 v0, v4, v150
	v_pk_add_f32 v[4:5], v[164:165], v[42:43]
	v_mul_f32_e32 v134, v0, v166
	v_pk_add_f32 v[4:5], v[162:163], v[4:5]
	v_add_f32_e32 v0, 0, v216
	v_pk_add_f32 v[4:5], v[160:161], v[4:5]
	s_nop 0
	v_pk_add_f32 v[4:5], v[158:159], v[4:5]
	s_nop 0
	v_pk_add_f32 v[4:5], v[156:157], v[4:5]
	s_nop 0
	v_pk_add_f32 v[4:5], v[154:155], v[4:5]
	s_nop 0
	v_pk_add_f32 v[4:5], v[134:135], v[4:5]
	s_nop 0
	v_add_f32_e32 v19, v5, v215
	v_fmac_f32_e32 v19, v4, v192
	v_add_f32_e32 v4, v217, v0
	v_add_f32_e32 v0, 0, v209
	v_add_f32_e32 v42, v210, v0
	v_add_f32_e32 v0, 0, v181
	v_add_f32_e32 v44, v193, v0
	v_add_f32_e32 v0, 0, v85
	v_add_f32_e32 v0, v87, v0
	v_pk_add_f32 v[46:47], v[100:101], v[0:1]
	v_mov_b32_e32 v5, v1
	v_pk_add_f32 v[46:47], v[98:99], v[46:47]
	v_mul_f32_e32 v52, v19, v182
	v_pk_add_f32 v[46:47], v[96:97], v[46:47]
	v_mov_b32_e32 v19, v1
	v_pk_add_f32 v[46:47], v[94:95], v[46:47]
	s_nop 0
	v_pk_add_f32 v[46:47], v[92:93], v[46:47]
	s_nop 0
	v_pk_add_f32 v[46:47], v[90:91], v[46:47]
	s_nop 0
	v_pk_add_f32 v[2:3], v[2:3], v[46:47]
	s_nop 0
	v_add_f32_e32 v0, v3, v167
	v_fmac_f32_e32 v0, v2, v114
	v_pk_add_f32 v[2:3], v[78:79], v[44:45]
	v_mul_f32_e32 v114, v0, v116
	v_pk_add_f32 v[2:3], v[76:77], v[2:3]
	s_nop 0
	v_pk_add_f32 v[2:3], v[74:75], v[2:3]
	s_nop 0
	v_pk_add_f32 v[2:3], v[72:73], v[2:3]
	s_nop 0
	v_pk_add_f32 v[2:3], v[70:71], v[2:3]
	s_nop 0
	v_pk_add_f32 v[2:3], v[68:69], v[2:3]
	s_nop 0
	v_pk_add_f32 v[2:3], v[114:115], v[2:3]
	s_nop 0
	v_add_f32_e32 v0, v3, v121
	v_fmac_f32_e32 v0, v2, v120
	v_pk_add_f32 v[2:3], v[146:147], v[42:43]
	v_mul_f32_e32 v116, v0, v148
	v_pk_add_f32 v[2:3], v[144:145], v[2:3]
	s_nop 0
	v_pk_add_f32 v[2:3], v[142:143], v[2:3]
	s_nop 0
	v_pk_add_f32 v[2:3], v[140:141], v[2:3]
	s_nop 0
	v_pk_add_f32 v[2:3], v[138:139], v[2:3]
	s_nop 0
	v_pk_add_f32 v[2:3], v[136:137], v[2:3]
	s_nop 0
	v_pk_add_f32 v[2:3], v[116:117], v[2:3]
	s_nop 0
	v_add_f32_e32 v0, v3, v212
	v_fmac_f32_e32 v0, v2, v152
	v_pk_add_f32 v[2:3], v[176:177], v[4:5]
	v_mul_f32_e32 v66, v0, v180
	v_pk_add_f32 v[2:3], v[174:175], v[2:3]
	s_nop 0
	v_pk_add_f32 v[2:3], v[172:173], v[2:3]
	s_nop 0
	v_pk_add_f32 v[2:3], v[170:171], v[2:3]
	s_nop 0
	v_pk_add_f32 v[2:3], v[168:169], v[2:3]
	s_nop 0
	v_pk_add_f32 v[2:3], v[178:179], v[2:3]
	s_nop 0
	v_pk_add_f32 v[2:3], v[66:67], v[2:3]
	s_nop 0
	v_add_f32_e32 v0, v3, v65
	v_fmac_f32_e32 v0, v2, v64
	v_mov_b32_e32 v4, v0
	s_nop 1
	v_permlane16_swap_b32_e32 v4, v0
	v_pk_add_f32 v[2:3], v[190:191], v[18:19]
	s_waitcnt lgkmcnt(0)
	v_add_f32_e32 v0, v0, v4
	v_mov_b32_e32 v4, v0
	s_nop 1
	v_permlane32_swap_b32_e32 v4, v0
	v_pk_add_f32 v[2:3], v[188:189], v[2:3]
	s_waitcnt lgkmcnt(0)
	v_add_f32_e32 v0, v0, v4
	v_pk_add_f32 v[2:3], v[196:197], v[2:3]
	v_div_scale_f32 v4, s[0:1], v0, v0, 1.0
	v_pk_add_f32 v[2:3], v[194:195], v[2:3]
	v_rcp_f32_e32 v5, v4
	v_pk_add_f32 v[2:3], v[200:201], v[2:3]
	s_nop 0
	v_pk_add_f32 v[2:3], v[198:199], v[2:3]
	s_nop 0
	v_pk_add_f32 v[2:3], v[52:53], v[2:3]
	s_nop 0
	v_add_f32_e32 v42, v3, v51
	v_fmac_f32_e32 v42, v2, v50
	v_fma_f32 v2, -v4, v5, 1.0
	v_fmac_f32_e32 v5, v2, v5
	v_div_scale_f32 v2, vcc, 1.0, v0, 1.0
	v_mul_f32_e32 v3, v2, v5
	v_fma_f32 v18, -v4, v3, v2
	v_fmac_f32_e32 v3, v18, v5
	v_fma_f32 v2, -v4, v3, v2
	v_div_fmas_f32 v2, v2, v5, v3
	v_div_fixup_f32 v0, v2, v0, 1.0
	v_mov_b32_e32 v2, v32
	v_mov_b32_e32 v3, v34
	v_pk_mul_f32 v[2:3], v[2:3], v[0:1] op_sel_hi:[1,0]
	v_mov_b32_e32 v34, v33
	v_pk_mul_f32 v[4:5], v[34:35], v[0:1] op_sel_hi:[1,0]
	v_and_b32_sdwa v18, v3, v236 dst_sel:DWORD dst_unused:UNUSED_PAD src0_sel:WORD_1 src1_sel:DWORD
	v_and_b32_sdwa v19, v2, v236 dst_sel:DWORD dst_unused:UNUSED_PAD src0_sel:WORD_1 src1_sel:DWORD
	v_add3_u32 v2, v2, v19, s60
	v_add3_u32 v3, v3, v18, s60
	v_and_b32_sdwa v18, v5, v236 dst_sel:DWORD dst_unused:UNUSED_PAD src0_sel:WORD_1 src1_sel:DWORD
	v_and_b32_sdwa v19, v4, v236 dst_sel:DWORD dst_unused:UNUSED_PAD src0_sel:WORD_1 src1_sel:DWORD
	v_add3_u32 v5, v5, v18, s60
	v_add3_u32 v4, v4, v19, s60
	v_and_b32_e32 v5, 0xffff0000, v5
	v_and_b32_e32 v4, 0xffff0000, v4
	v_or_b32_sdwa v3, v5, v3 dst_sel:DWORD dst_unused:UNUSED_PAD src0_sel:DWORD src1_sel:WORD_1
	v_or_b32_sdwa v2, v4, v2 dst_sel:DWORD dst_unused:UNUSED_PAD src0_sel:DWORD src1_sel:WORD_1
	v_lshl_add_u64 v[4:5], v[48:49], 0, v[88:89]
	v_lshl_add_u64 v[18:19], v[4:5], 0, s[18:19]
	v_add_co_u32_e32 v4, vcc, s2, v4
	s_nop 1
	v_addc_co_u32_e32 v5, vcc, 0, v5, vcc
	global_store_dwordx2 v[4:5], v[2:3], off offset:512
	v_mov_b32_e32 v2, v10
	v_mov_b32_e32 v3, v12
	v_pk_mul_f32 v[2:3], v[2:3], v[0:1] op_sel_hi:[1,0]
	v_mov_b32_e32 v12, v11
	v_pk_mul_f32 v[4:5], v[12:13], v[0:1] op_sel_hi:[1,0]
	v_and_b32_sdwa v10, v3, v236 dst_sel:DWORD dst_unused:UNUSED_PAD src0_sel:WORD_1 src1_sel:DWORD
	v_and_b32_sdwa v11, v2, v236 dst_sel:DWORD dst_unused:UNUSED_PAD src0_sel:WORD_1 src1_sel:DWORD
	v_add3_u32 v2, v2, v11, s60
	v_add3_u32 v3, v3, v10, s60
	v_and_b32_sdwa v10, v5, v236 dst_sel:DWORD dst_unused:UNUSED_PAD src0_sel:WORD_1 src1_sel:DWORD
	v_and_b32_sdwa v11, v4, v236 dst_sel:DWORD dst_unused:UNUSED_PAD src0_sel:WORD_1 src1_sel:DWORD
	v_add3_u32 v5, v5, v10, s60
	v_add3_u32 v4, v4, v11, s60
	v_and_b32_e32 v5, 0xffff0000, v5
	v_and_b32_e32 v4, 0xffff0000, v4
	v_or_b32_sdwa v3, v5, v3 dst_sel:DWORD dst_unused:UNUSED_PAD src0_sel:DWORD src1_sel:WORD_1
	v_or_b32_sdwa v2, v4, v2 dst_sel:DWORD dst_unused:UNUSED_PAD src0_sel:DWORD src1_sel:WORD_1
	global_store_dwordx2 v[18:19], v[2:3], off offset:32
	v_mov_b32_e32 v2, v6
	v_mov_b32_e32 v3, v8
	v_pk_mul_f32 v[2:3], v[2:3], v[0:1] op_sel_hi:[1,0]
	v_mov_b32_e32 v8, v7
	v_pk_mul_f32 v[4:5], v[8:9], v[0:1] op_sel_hi:[1,0]
	v_and_b32_sdwa v7, v2, v236 dst_sel:DWORD dst_unused:UNUSED_PAD src0_sel:WORD_1 src1_sel:DWORD
	v_add3_u32 v2, v2, v7, s60
	v_and_b32_sdwa v7, v4, v236 dst_sel:DWORD dst_unused:UNUSED_PAD src0_sel:WORD_1 src1_sel:DWORD
	v_add3_u32 v4, v4, v7, s60
	v_mov_b32_e32 v7, v42
	s_nop 1
	v_permlane16_swap_b32_e32 v7, v42
	v_and_b32_sdwa v6, v3, v236 dst_sel:DWORD dst_unused:UNUSED_PAD src0_sel:WORD_1 src1_sel:DWORD
	v_add3_u32 v3, v3, v6, s60
	v_and_b32_sdwa v6, v5, v236 dst_sel:DWORD dst_unused:UNUSED_PAD src0_sel:WORD_1 src1_sel:DWORD
	v_add3_u32 v5, v5, v6, s60
	v_and_b32_e32 v5, 0xffff0000, v5
	v_and_b32_e32 v4, 0xffff0000, v4
	s_waitcnt lgkmcnt(0)
	v_add_f32_e32 v7, v42, v7
	v_or_b32_sdwa v3, v5, v3 dst_sel:DWORD dst_unused:UNUSED_PAD src0_sel:DWORD src1_sel:WORD_1
	v_or_b32_sdwa v2, v4, v2 dst_sel:DWORD dst_unused:UNUSED_PAD src0_sel:DWORD src1_sel:WORD_1
	v_mov_b32_e32 v8, v7
	s_nop 1
	v_permlane32_swap_b32_e32 v8, v7
	global_store_dwordx2 v[18:19], v[2:3], off offset:64
	v_mov_b32_e32 v2, v36
	v_mov_b32_e32 v3, v38
	v_pk_mul_f32 v[2:3], v[2:3], v[0:1] op_sel_hi:[1,0]
	v_mov_b32_e32 v38, v37
	v_pk_mul_f32 v[4:5], v[38:39], v[0:1] op_sel_hi:[1,0]
	v_and_b32_sdwa v0, v3, v236 dst_sel:DWORD dst_unused:UNUSED_PAD src0_sel:WORD_1 src1_sel:DWORD
	v_and_b32_sdwa v6, v2, v236 dst_sel:DWORD dst_unused:UNUSED_PAD src0_sel:WORD_1 src1_sel:DWORD
	v_add3_u32 v0, v3, v0, s60
	v_and_b32_sdwa v3, v5, v236 dst_sel:DWORD dst_unused:UNUSED_PAD src0_sel:WORD_1 src1_sel:DWORD
	v_add3_u32 v2, v2, v6, s60
	v_and_b32_sdwa v6, v4, v236 dst_sel:DWORD dst_unused:UNUSED_PAD src0_sel:WORD_1 src1_sel:DWORD
	v_add3_u32 v3, v5, v3, s60
	s_waitcnt lgkmcnt(0)
	v_add_f32_e32 v5, v7, v8
	v_add3_u32 v4, v4, v6, s60
	v_div_scale_f32 v6, s[0:1], v5, v5, 1.0
	v_rcp_f32_e32 v7, v6
	v_and_b32_e32 v3, 0xffff0000, v3
	v_and_b32_e32 v4, 0xffff0000, v4
	v_or_b32_sdwa v3, v3, v0 dst_sel:DWORD dst_unused:UNUSED_PAD src0_sel:DWORD src1_sel:WORD_1
	v_fma_f32 v0, -v6, v7, 1.0
	v_or_b32_sdwa v2, v4, v2 dst_sel:DWORD dst_unused:UNUSED_PAD src0_sel:DWORD src1_sel:WORD_1
	v_fmac_f32_e32 v7, v0, v7
	v_div_scale_f32 v0, vcc, 1.0, v5, 1.0
	global_store_dwordx2 v[18:19], v[2:3], off offset:96
	v_mul_f32_e32 v2, v0, v7
	v_fma_f32 v3, -v6, v2, v0
	v_fmac_f32_e32 v2, v3, v7
	v_fma_f32 v0, -v6, v2, v0
	v_div_fmas_f32 v0, v0, v7, v2
	v_div_fixup_f32 v0, v0, v5, 1.0
	v_mov_b32_e32 v2, v28
	v_mov_b32_e32 v3, v30
	v_pk_mul_f32 v[2:3], v[2:3], v[0:1] op_sel_hi:[1,0]
	v_mov_b32_e32 v30, v29
	v_pk_mul_f32 v[4:5], v[30:31], v[0:1] op_sel_hi:[1,0]
	v_and_b32_sdwa v6, v3, v236 dst_sel:DWORD dst_unused:UNUSED_PAD src0_sel:WORD_1 src1_sel:DWORD
	v_and_b32_sdwa v7, v2, v236 dst_sel:DWORD dst_unused:UNUSED_PAD src0_sel:WORD_1 src1_sel:DWORD
	v_add3_u32 v2, v2, v7, s60
	v_add3_u32 v3, v3, v6, s60
	v_and_b32_sdwa v6, v5, v236 dst_sel:DWORD dst_unused:UNUSED_PAD src0_sel:WORD_1 src1_sel:DWORD
	v_and_b32_sdwa v7, v4, v236 dst_sel:DWORD dst_unused:UNUSED_PAD src0_sel:WORD_1 src1_sel:DWORD
	v_add3_u32 v5, v5, v6, s60
	v_add3_u32 v4, v4, v7, s60
	v_and_b32_e32 v5, 0xffff0000, v5
	v_and_b32_e32 v4, 0xffff0000, v4
	v_or_b32_sdwa v3, v5, v3 dst_sel:DWORD dst_unused:UNUSED_PAD src0_sel:DWORD src1_sel:WORD_1
	v_or_b32_sdwa v2, v4, v2 dst_sel:DWORD dst_unused:UNUSED_PAD src0_sel:DWORD src1_sel:WORD_1
	v_lshl_add_u64 v[4:5], v[40:41], 0, v[88:89]
	v_lshl_add_u64 v[6:7], v[4:5], 0, s[18:19]
	v_add_co_u32_e32 v4, vcc, s2, v4
	s_nop 1
	v_addc_co_u32_e32 v5, vcc, 0, v5, vcc
	global_store_dwordx2 v[4:5], v[2:3], off offset:512
	v_mov_b32_e32 v2, v24
	v_mov_b32_e32 v3, v26
	v_pk_mul_f32 v[2:3], v[2:3], v[0:1] op_sel_hi:[1,0]
	v_mov_b32_e32 v26, v25
	v_pk_mul_f32 v[4:5], v[26:27], v[0:1] op_sel_hi:[1,0]
	v_and_b32_sdwa v8, v3, v236 dst_sel:DWORD dst_unused:UNUSED_PAD src0_sel:WORD_1 src1_sel:DWORD
	v_and_b32_sdwa v9, v2, v236 dst_sel:DWORD dst_unused:UNUSED_PAD src0_sel:WORD_1 src1_sel:DWORD
	v_add3_u32 v2, v2, v9, s60
	v_add3_u32 v3, v3, v8, s60
	v_and_b32_sdwa v8, v5, v236 dst_sel:DWORD dst_unused:UNUSED_PAD src0_sel:WORD_1 src1_sel:DWORD
	v_and_b32_sdwa v9, v4, v236 dst_sel:DWORD dst_unused:UNUSED_PAD src0_sel:WORD_1 src1_sel:DWORD
	v_add3_u32 v5, v5, v8, s60
	v_add3_u32 v4, v4, v9, s60
	v_and_b32_e32 v5, 0xffff0000, v5
	v_and_b32_e32 v4, 0xffff0000, v4
	v_or_b32_sdwa v3, v5, v3 dst_sel:DWORD dst_unused:UNUSED_PAD src0_sel:DWORD src1_sel:WORD_1
	v_or_b32_sdwa v2, v4, v2 dst_sel:DWORD dst_unused:UNUSED_PAD src0_sel:DWORD src1_sel:WORD_1
	global_store_dwordx2 v[6:7], v[2:3], off offset:32
	v_mov_b32_e32 v2, v20
	v_mov_b32_e32 v3, v22
	v_pk_mul_f32 v[2:3], v[2:3], v[0:1] op_sel_hi:[1,0]
	v_mov_b32_e32 v22, v21
	v_pk_mul_f32 v[4:5], v[22:23], v[0:1] op_sel_hi:[1,0]
	v_and_b32_sdwa v8, v3, v236 dst_sel:DWORD dst_unused:UNUSED_PAD src0_sel:WORD_1 src1_sel:DWORD
	v_and_b32_sdwa v9, v2, v236 dst_sel:DWORD dst_unused:UNUSED_PAD src0_sel:WORD_1 src1_sel:DWORD
	v_add3_u32 v2, v2, v9, s60
	v_add3_u32 v3, v3, v8, s60
	v_and_b32_sdwa v8, v5, v236 dst_sel:DWORD dst_unused:UNUSED_PAD src0_sel:WORD_1 src1_sel:DWORD
	v_and_b32_sdwa v9, v4, v236 dst_sel:DWORD dst_unused:UNUSED_PAD src0_sel:WORD_1 src1_sel:DWORD
	v_add3_u32 v5, v5, v8, s60
	v_add3_u32 v4, v4, v9, s60
	v_and_b32_e32 v5, 0xffff0000, v5
	v_and_b32_e32 v4, 0xffff0000, v4
	v_or_b32_sdwa v3, v5, v3 dst_sel:DWORD dst_unused:UNUSED_PAD src0_sel:DWORD src1_sel:WORD_1
	v_or_b32_sdwa v2, v4, v2 dst_sel:DWORD dst_unused:UNUSED_PAD src0_sel:DWORD src1_sel:WORD_1
	global_store_dwordx2 v[6:7], v[2:3], off offset:64
	v_mov_b32_e32 v2, v14
	v_mov_b32_e32 v3, v16
	v_pk_mul_f32 v[2:3], v[2:3], v[0:1] op_sel_hi:[1,0]
	v_mov_b32_e32 v16, v15
	v_pk_mul_f32 v[4:5], v[16:17], v[0:1] op_sel_hi:[1,0]
	v_and_b32_sdwa v0, v3, v236 dst_sel:DWORD dst_unused:UNUSED_PAD src0_sel:WORD_1 src1_sel:DWORD
	v_and_b32_sdwa v8, v2, v236 dst_sel:DWORD dst_unused:UNUSED_PAD src0_sel:WORD_1 src1_sel:DWORD
	v_add3_u32 v2, v2, v8, s60
	v_add3_u32 v0, v3, v0, s60
	v_and_b32_sdwa v3, v5, v236 dst_sel:DWORD dst_unused:UNUSED_PAD src0_sel:WORD_1 src1_sel:DWORD
	v_and_b32_sdwa v8, v4, v236 dst_sel:DWORD dst_unused:UNUSED_PAD src0_sel:WORD_1 src1_sel:DWORD
	v_add3_u32 v3, v5, v3, s60
	v_add3_u32 v4, v4, v8, s60
	v_and_b32_e32 v3, 0xffff0000, v3
	v_and_b32_e32 v4, 0xffff0000, v4
	v_or_b32_sdwa v3, v3, v0 dst_sel:DWORD dst_unused:UNUSED_PAD src0_sel:DWORD src1_sel:WORD_1
	v_or_b32_sdwa v2, v4, v2 dst_sel:DWORD dst_unused:UNUSED_PAD src0_sel:DWORD src1_sel:WORD_1
	global_store_dwordx2 v[6:7], v[2:3], off offset:96
	s_branch .LBB0_1196
